# saddr DMA + unscaled fp8 MFMA + M-block handoff trims (setprio before barrier, redundant lgkmcnt dropped, barrier before setprio 0)
# speedup vs baseline: 1.0100x; 1.0029x over previous
.LBB0_422:
	ds_read_b128 v[146:149], v154
	ds_read_b128 v[158:161], v154 offset:1024
	ds_read_b128 v[162:165], v154 offset:2048
	ds_read_b128 v[166:169], v154 offset:3072
	ds_read_b128 v[170:173], v155
	ds_read_b128 v[178:181], v155 offset:1024
	ds_read_b128 v[182:185], v155 offset:2048
	ds_read_b128 v[186:189], v155 offset:3072
	s_add_u32 s30, s28, 0xfc000
	s_addc_u32 s31, s29, 0
	s_cmp_eq_u32 s53, 60
	s_cselect_b32 s36, s21, s30
	s_cselect_b32 s37, s9, s31
	s_cselect_b32 s34, s50, s51
	s_cselect_b32 s35, s19, s52
	s_add_u32 s30, s36, 0x100000
	s_addc_u32 s31, s37, 0
	s_add_i32 m0, s1, 0xc000
	ds_read_b128 v[190:193], v156
	ds_read_b128 v[194:197], v156 offset:1024
	ds_read_b128 v[198:201], v156 offset:2048
	ds_read_b128 v[202:205], v156 offset:3072
	ds_read_b128 v[206:209], v156 offset:4096
	ds_read_b128 v[210:213], v156 offset:5120
	ds_read_b128 v[214:217], v156 offset:6144
	ds_read_b128 v[218:221], v156 offset:7168
	global_load_lds_dwordx4 v138, s[28:29]
	s_add_i32 m0, s1, 0xe000
	s_nop 0
	global_load_lds_dwordx4 v140, s[28:29]
	s_waitcnt vmcnt(8)
	s_waitcnt lgkmcnt(0)
	s_setprio 1
	s_barrier
	v_mfma_f32_16x16x32_bf16 v[126:129], v[146:149], v[190:193], v[126:129]
	v_mfma_f32_16x16x32_bf16 v[122:125], v[162:165], v[190:193], v[122:125]
	v_mfma_f32_16x16x32_bf16 v[110:113], v[146:149], v[198:201], v[110:113]
	v_mfma_f32_16x16x32_bf16 v[106:109], v[162:165], v[198:201], v[106:109]
	v_mfma_f32_16x16x32_bf16 v[94:97], v[146:149], v[206:209], v[94:97]
	v_mfma_f32_16x16x32_bf16 v[90:93], v[162:165], v[206:209], v[90:93]
	v_mfma_f32_16x16x32_bf16 v[78:81], v[146:149], v[214:217], v[78:81]
	v_mfma_f32_16x16x32_bf16 v[74:77], v[162:165], v[214:217], v[74:77]
	v_mfma_f32_16x16x32_bf16 v[126:129], v[158:161], v[194:197], v[126:129]
	v_mfma_f32_16x16x32_bf16 v[122:125], v[166:169], v[194:197], v[122:125]
	v_mfma_f32_16x16x32_bf16 v[110:113], v[158:161], v[202:205], v[110:113]
	v_mfma_f32_16x16x32_bf16 v[106:109], v[166:169], v[202:205], v[106:109]
	v_mfma_f32_16x16x32_bf16 v[94:97], v[158:161], v[210:213], v[94:97]
	v_mfma_f32_16x16x32_bf16 v[90:93], v[166:169], v[210:213], v[90:93]
	v_mfma_f32_16x16x32_bf16 v[78:81], v[158:161], v[218:221], v[78:81]
	v_mfma_f32_16x16x32_bf16 v[74:77], v[166:169], v[218:221], v[74:77]
	s_setprio 0
	s_setprio 1
	v_mfma_f32_16x16x32_bf16 v[118:121], v[170:173], v[190:193], v[118:121]
	v_mfma_f32_16x16x32_bf16 v[114:117], v[182:185], v[190:193], v[114:117]
	v_mfma_f32_16x16x32_bf16 v[102:105], v[170:173], v[198:201], v[102:105]
	v_mfma_f32_16x16x32_bf16 v[98:101], v[182:185], v[198:201], v[98:101]
	v_mfma_f32_16x16x32_bf16 v[86:89], v[170:173], v[206:209], v[86:89]
	v_mfma_f32_16x16x32_bf16 v[82:85], v[182:185], v[206:209], v[82:85]
	v_mfma_f32_16x16x32_bf16 v[70:73], v[170:173], v[214:217], v[70:73]
	v_mfma_f32_16x16x32_bf16 v[66:69], v[182:185], v[214:217], v[66:69]
	v_mfma_f32_16x16x32_bf16 v[118:121], v[178:181], v[194:197], v[118:121]
	v_mfma_f32_16x16x32_bf16 v[114:117], v[186:189], v[194:197], v[114:117]
	v_mfma_f32_16x16x32_bf16 v[102:105], v[178:181], v[202:205], v[102:105]
	v_mfma_f32_16x16x32_bf16 v[98:101], v[186:189], v[202:205], v[98:101]
	v_mfma_f32_16x16x32_bf16 v[86:89], v[178:181], v[210:213], v[86:89]
	v_mfma_f32_16x16x32_bf16 v[82:85], v[186:189], v[210:213], v[82:85]
	v_mfma_f32_16x16x32_bf16 v[70:73], v[178:181], v[218:221], v[70:73]
	v_mfma_f32_16x16x32_bf16 v[66:69], v[186:189], v[218:221], v[66:69]
	s_barrier
	s_setprio 0
	s_add_i32 s54, s48, s0
	s_mov_b32 m0, s54
	ds_read_b128 v[190:193], v156 offset:16384
	ds_read_b128 v[194:197], v156 offset:17408
	ds_read_b128 v[198:201], v156 offset:18432
	ds_read_b128 v[202:205], v156 offset:19456
	ds_read_b128 v[206:209], v156 offset:20480
	ds_read_b128 v[210:213], v156 offset:21504
	ds_read_b128 v[214:217], v156 offset:22528
	ds_read_b128 v[218:221], v156 offset:23552
	global_load_lds_dwordx4 v132, s[34:35]
	s_add_i32 m0, s54, 0x2000
	s_add_u32 s54, s34, 0x4000
	s_addc_u32 s55, s35, 0
	s_add_i32 s56, s49, s0
	global_load_lds_dwordx4 v136, s[34:35]
	s_mov_b32 m0, s56
	s_nop 0
	global_load_lds_dwordx4 v132, s[54:55]
	s_add_i32 m0, s56, 0x2000
	s_nop 0
	global_load_lds_dwordx4 v136, s[54:55]
	s_mov_b32 m0, s1
	s_nop 0
	global_load_lds_dwordx4 v130, s[36:37]
	s_mov_b32 m0, s27
	s_nop 0
	global_load_lds_dwordx4 v134, s[36:37]
	s_waitcnt vmcnt(8)
	s_waitcnt lgkmcnt(0)
	s_setprio 1
	s_barrier
	v_mfma_f32_16x16x32_bf16 v[62:65], v[146:149], v[190:193], v[62:65]
	v_mfma_f32_16x16x32_bf16 v[58:61], v[162:165], v[190:193], v[58:61]
	v_mfma_f32_16x16x32_bf16 v[46:49], v[146:149], v[198:201], v[46:49]
	v_mfma_f32_16x16x32_bf16 v[42:45], v[162:165], v[198:201], v[42:45]
	v_mfma_f32_16x16x32_bf16 v[30:33], v[146:149], v[206:209], v[30:33]
	v_mfma_f32_16x16x32_bf16 v[26:29], v[162:165], v[206:209], v[26:29]
	v_mfma_f32_16x16x32_bf16 v[14:17], v[146:149], v[214:217], v[14:17]
	v_mfma_f32_16x16x32_bf16 v[10:13], v[162:165], v[214:217], v[10:13]
	v_mfma_f32_16x16x32_bf16 v[62:65], v[158:161], v[194:197], v[62:65]
	v_mfma_f32_16x16x32_bf16 v[58:61], v[166:169], v[194:197], v[58:61]
	v_mfma_f32_16x16x32_bf16 v[46:49], v[158:161], v[202:205], v[46:49]
	v_mfma_f32_16x16x32_bf16 v[42:45], v[166:169], v[202:205], v[42:45]
	v_mfma_f32_16x16x32_bf16 v[30:33], v[158:161], v[210:213], v[30:33]
	v_mfma_f32_16x16x32_bf16 v[26:29], v[166:169], v[210:213], v[26:29]
	v_mfma_f32_16x16x32_bf16 v[14:17], v[158:161], v[218:221], v[14:17]
	v_mfma_f32_16x16x32_bf16 v[10:13], v[166:169], v[218:221], v[10:13]
	s_setprio 0
	s_setprio 1
	v_mfma_f32_16x16x32_bf16 v[54:57], v[170:173], v[190:193], v[54:57]
	v_mfma_f32_16x16x32_bf16 v[50:53], v[182:185], v[190:193], v[50:53]
	v_mfma_f32_16x16x32_bf16 v[38:41], v[170:173], v[198:201], v[38:41]
	v_mfma_f32_16x16x32_bf16 v[34:37], v[182:185], v[198:201], v[34:37]
	v_mfma_f32_16x16x32_bf16 v[22:25], v[170:173], v[206:209], v[22:25]
	v_mfma_f32_16x16x32_bf16 v[18:21], v[182:185], v[206:209], v[18:21]
	v_mfma_f32_16x16x32_bf16 v[6:9], v[170:173], v[214:217], v[6:9]
	v_mfma_f32_16x16x32_bf16 v[2:5], v[182:185], v[214:217], v[2:5]
	v_mfma_f32_16x16x32_bf16 v[54:57], v[178:181], v[194:197], v[54:57]
	v_mfma_f32_16x16x32_bf16 v[50:53], v[186:189], v[194:197], v[50:53]
	v_mfma_f32_16x16x32_bf16 v[38:41], v[178:181], v[202:205], v[38:41]
	v_mfma_f32_16x16x32_bf16 v[34:37], v[186:189], v[202:205], v[34:37]
	v_mfma_f32_16x16x32_bf16 v[22:25], v[178:181], v[210:213], v[22:25]
	v_mfma_f32_16x16x32_bf16 v[18:21], v[186:189], v[210:213], v[18:21]
	v_mfma_f32_16x16x32_bf16 v[6:9], v[178:181], v[218:221], v[6:9]
	v_mfma_f32_16x16x32_bf16 v[2:5], v[186:189], v[218:221], v[2:5]
	s_barrier
	s_setprio 0
	s_add_i32 s54, 0, 0x18000
	v_add_u32_e32 v150, s54, v153
	s_add_i32 s55, 0, 0x1c000
	ds_read_b128 v[146:149], v150
	ds_read_b128 v[158:161], v150 offset:1024
	ds_read_b128 v[162:165], v150 offset:2048
	ds_read_b128 v[166:169], v150 offset:3072
	v_add_u32_e32 v150, s55, v153
	ds_read_b128 v[170:173], v150
	ds_read_b128 v[178:181], v150 offset:1024
	ds_read_b128 v[182:185], v150 offset:2048
	ds_read_b128 v[186:189], v150 offset:3072
	s_add_u32 s36, s36, 0x4000
	s_addc_u32 s37, s37, 0
	s_mov_b32 m0, s33
	ds_read_b128 v[190:193], v156 offset:32768
	ds_read_b128 v[194:197], v156 offset:33792
	ds_read_b128 v[198:201], v156 offset:34816
	ds_read_b128 v[202:205], v156 offset:35840
	ds_read_b128 v[206:209], v156 offset:36864
	ds_read_b128 v[210:213], v156 offset:37888
	ds_read_b128 v[214:217], v156 offset:38912
	ds_read_b128 v[218:221], v156 offset:39936
	global_load_lds_dwordx4 v130, s[36:37]
	s_mov_b32 m0, s38
	s_nop 0
	global_load_lds_dwordx4 v134, s[36:37]
	s_waitcnt vmcnt(8)
	s_waitcnt lgkmcnt(0)
	s_setprio 1
	s_barrier
	v_mfma_f32_16x16x32_bf16 v[126:129], v[146:149], v[190:193], v[126:129]
	v_mfma_f32_16x16x32_bf16 v[122:125], v[162:165], v[190:193], v[122:125]
	v_mfma_f32_16x16x32_bf16 v[110:113], v[146:149], v[198:201], v[110:113]
	v_mfma_f32_16x16x32_bf16 v[106:109], v[162:165], v[198:201], v[106:109]
	v_mfma_f32_16x16x32_bf16 v[94:97], v[146:149], v[206:209], v[94:97]
	v_mfma_f32_16x16x32_bf16 v[90:93], v[162:165], v[206:209], v[90:93]
	v_mfma_f32_16x16x32_bf16 v[78:81], v[146:149], v[214:217], v[78:81]
	v_mfma_f32_16x16x32_bf16 v[74:77], v[162:165], v[214:217], v[74:77]
	v_mfma_f32_16x16x32_bf16 v[126:129], v[158:161], v[194:197], v[126:129]
	v_mfma_f32_16x16x32_bf16 v[122:125], v[166:169], v[194:197], v[122:125]
	v_mfma_f32_16x16x32_bf16 v[110:113], v[158:161], v[202:205], v[110:113]
	v_mfma_f32_16x16x32_bf16 v[106:109], v[166:169], v[202:205], v[106:109]
	v_mfma_f32_16x16x32_bf16 v[94:97], v[158:161], v[210:213], v[94:97]
	v_mfma_f32_16x16x32_bf16 v[90:93], v[166:169], v[210:213], v[90:93]
	v_mfma_f32_16x16x32_bf16 v[78:81], v[158:161], v[218:221], v[78:81]
	v_mfma_f32_16x16x32_bf16 v[74:77], v[166:169], v[218:221], v[74:77]
	s_setprio 0
	s_setprio 1
	v_mfma_f32_16x16x32_bf16 v[118:121], v[170:173], v[190:193], v[118:121]
	v_mfma_f32_16x16x32_bf16 v[114:117], v[182:185], v[190:193], v[114:117]
	v_mfma_f32_16x16x32_bf16 v[102:105], v[170:173], v[198:201], v[102:105]
	v_mfma_f32_16x16x32_bf16 v[98:101], v[182:185], v[198:201], v[98:101]
	v_mfma_f32_16x16x32_bf16 v[86:89], v[170:173], v[206:209], v[86:89]
	v_mfma_f32_16x16x32_bf16 v[82:85], v[182:185], v[206:209], v[82:85]
	v_mfma_f32_16x16x32_bf16 v[70:73], v[170:173], v[214:217], v[70:73]
	v_mfma_f32_16x16x32_bf16 v[66:69], v[182:185], v[214:217], v[66:69]
	v_mfma_f32_16x16x32_bf16 v[118:121], v[178:181], v[194:197], v[118:121]
	v_mfma_f32_16x16x32_bf16 v[114:117], v[186:189], v[194:197], v[114:117]
	v_mfma_f32_16x16x32_bf16 v[102:105], v[178:181], v[202:205], v[102:105]
	v_mfma_f32_16x16x32_bf16 v[98:101], v[186:189], v[202:205], v[98:101]
	v_mfma_f32_16x16x32_bf16 v[86:89], v[178:181], v[210:213], v[86:89]
	v_mfma_f32_16x16x32_bf16 v[82:85], v[186:189], v[210:213], v[82:85]
	v_mfma_f32_16x16x32_bf16 v[70:73], v[178:181], v[218:221], v[70:73]
	v_mfma_f32_16x16x32_bf16 v[66:69], v[186:189], v[218:221], v[66:69]
	s_barrier
	s_setprio 0
	s_add_u32 s36, s34, 0x380000
	s_addc_u32 s37, s35, 0
	s_add_i32 s54, s54, s0
	s_mov_b32 m0, s54
	ds_read_b128 v[190:193], v156 offset:49152
	ds_read_b128 v[194:197], v156 offset:50176
	ds_read_b128 v[198:201], v156 offset:51200
	ds_read_b128 v[202:205], v156 offset:52224
	ds_read_b128 v[206:209], v156 offset:53248
	ds_read_b128 v[210:213], v156 offset:54272
	ds_read_b128 v[214:217], v156 offset:55296
	ds_read_b128 v[218:221], v156 offset:56320
	global_load_lds_dwordx4 v132, s[36:37]
	s_add_i32 m0, s54, 0x2000
	s_add_u32 s34, s34, 0x384000
	s_addc_u32 s35, s35, 0
	global_load_lds_dwordx4 v136, s[36:37]
	s_add_i32 s36, s55, s0
	s_mov_b32 m0, s36
	s_nop 0
	global_load_lds_dwordx4 v132, s[34:35]
	s_add_i32 m0, s36, 0x2000
	s_nop 0
	global_load_lds_dwordx4 v136, s[34:35]
	s_mov_b32 m0, s44
	s_nop 0
	global_load_lds_dwordx4 v130, s[30:31]
	s_mov_b32 m0, s45
	s_nop 0
	global_load_lds_dwordx4 v134, s[30:31]
	s_waitcnt vmcnt(8)
	s_waitcnt lgkmcnt(0)
	s_setprio 1
	s_barrier
	v_mfma_f32_16x16x32_bf16 v[62:65], v[146:149], v[190:193], v[62:65]
	v_mfma_f32_16x16x32_bf16 v[58:61], v[162:165], v[190:193], v[58:61]
	v_mfma_f32_16x16x32_bf16 v[46:49], v[146:149], v[198:201], v[46:49]
	v_mfma_f32_16x16x32_bf16 v[42:45], v[162:165], v[198:201], v[42:45]
	v_mfma_f32_16x16x32_bf16 v[30:33], v[146:149], v[206:209], v[30:33]
	v_mfma_f32_16x16x32_bf16 v[26:29], v[162:165], v[206:209], v[26:29]
	v_mfma_f32_16x16x32_bf16 v[14:17], v[146:149], v[214:217], v[14:17]
	v_mfma_f32_16x16x32_bf16 v[10:13], v[162:165], v[214:217], v[10:13]
	v_mfma_f32_16x16x32_bf16 v[62:65], v[158:161], v[194:197], v[62:65]
	v_mfma_f32_16x16x32_bf16 v[58:61], v[166:169], v[194:197], v[58:61]
	v_mfma_f32_16x16x32_bf16 v[46:49], v[158:161], v[202:205], v[46:49]
	v_mfma_f32_16x16x32_bf16 v[42:45], v[166:169], v[202:205], v[42:45]
	v_mfma_f32_16x16x32_bf16 v[30:33], v[158:161], v[210:213], v[30:33]
	v_mfma_f32_16x16x32_bf16 v[26:29], v[166:169], v[210:213], v[26:29]
	v_mfma_f32_16x16x32_bf16 v[14:17], v[158:161], v[218:221], v[14:17]
	v_mfma_f32_16x16x32_bf16 v[10:13], v[166:169], v[218:221], v[10:13]
	s_setprio 0
	s_setprio 1
	v_mfma_f32_16x16x32_bf16 v[54:57], v[170:173], v[190:193], v[54:57]
	v_mfma_f32_16x16x32_bf16 v[50:53], v[182:185], v[190:193], v[50:53]
	v_mfma_f32_16x16x32_bf16 v[38:41], v[170:173], v[198:201], v[38:41]
	v_mfma_f32_16x16x32_bf16 v[34:37], v[182:185], v[198:201], v[34:37]
	v_mfma_f32_16x16x32_bf16 v[22:25], v[170:173], v[206:209], v[22:25]
	v_mfma_f32_16x16x32_bf16 v[18:21], v[182:185], v[206:209], v[18:21]
	v_mfma_f32_16x16x32_bf16 v[6:9], v[170:173], v[214:217], v[6:9]
	v_mfma_f32_16x16x32_bf16 v[2:5], v[182:185], v[214:217], v[2:5]
	v_mfma_f32_16x16x32_bf16 v[54:57], v[178:181], v[194:197], v[54:57]
	v_mfma_f32_16x16x32_bf16 v[50:53], v[186:189], v[194:197], v[50:53]
	v_mfma_f32_16x16x32_bf16 v[38:41], v[178:181], v[202:205], v[38:41]
	v_mfma_f32_16x16x32_bf16 v[34:37], v[186:189], v[202:205], v[34:37]
	v_mfma_f32_16x16x32_bf16 v[22:25], v[178:181], v[210:213], v[22:25]
	v_mfma_f32_16x16x32_bf16 v[18:21], v[186:189], v[210:213], v[18:21]
	v_mfma_f32_16x16x32_bf16 v[6:9], v[178:181], v[218:221], v[6:9]
	v_mfma_f32_16x16x32_bf16 v[2:5], v[186:189], v[218:221], v[2:5]
	s_barrier
	s_setprio 0
	s_add_i32 s53, s53, 2
	s_add_u32 s51, s51, 0x700000
	s_addc_u32 s52, s52, 0
	s_add_u32 s28, s28, 0x200000
	s_addc_u32 s29, s29, 0
	s_cmp_gt_u32 s53, 61
	s_cbranch_scc0 .LBB0_422
	s_and_b64 vcc, exec, s[16:17]
	s_cbranch_vccz .LBB0_425
	s_barrier

.LBB0_501:
	ds_read_b128 v[146:149], v152
	ds_read_b128 v[156:159], v152 offset:1024
	ds_read_b128 v[160:163], v152 offset:2048
	ds_read_b128 v[164:167], v152 offset:3072
	ds_read_b128 v[168:171], v153
	ds_read_b128 v[172:175], v153 offset:1024
	ds_read_b128 v[178:181], v153 offset:2048
	ds_read_b128 v[182:185], v153 offset:3072
	s_add_u32 s26, s10, 0xfc000
	s_addc_u32 s27, s11, 0
	s_cmpk_eq_i32 s47, 0xdc
	s_cselect_b32 s30, s21, s26
	s_cselect_b32 s31, s5, s27
	s_cselect_b32 s28, s44, s45
	s_cselect_b32 s29, s19, s46
	s_add_u32 s26, s30, 0x100000
	s_addc_u32 s27, s31, 0
	s_add_i32 m0, s1, 0xc000
	ds_read_b128 v[186:189], v154
	ds_read_b128 v[190:193], v154 offset:1024
	ds_read_b128 v[194:197], v154 offset:2048
	ds_read_b128 v[198:201], v154 offset:3072
	ds_read_b128 v[202:205], v154 offset:4096
	ds_read_b128 v[206:209], v154 offset:5120
	ds_read_b128 v[210:213], v154 offset:6144
	ds_read_b128 v[214:217], v154 offset:7168
	global_load_lds_dwordx4 v138, s[10:11]
	s_add_i32 m0, s1, 0xe000
	s_nop 0
	global_load_lds_dwordx4 v140, s[10:11]
	s_waitcnt vmcnt(8)
	s_waitcnt lgkmcnt(0)
	s_setprio 1
	s_barrier
	v_mfma_f32_16x16x32_bf16 v[126:129], v[146:149], v[186:189], v[126:129]
	v_mfma_f32_16x16x32_bf16 v[122:125], v[160:163], v[186:189], v[122:125]
	v_mfma_f32_16x16x32_bf16 v[110:113], v[146:149], v[194:197], v[110:113]
	v_mfma_f32_16x16x32_bf16 v[106:109], v[160:163], v[194:197], v[106:109]
	v_mfma_f32_16x16x32_bf16 v[94:97], v[146:149], v[202:205], v[94:97]
	v_mfma_f32_16x16x32_bf16 v[90:93], v[160:163], v[202:205], v[90:93]
	v_mfma_f32_16x16x32_bf16 v[78:81], v[146:149], v[210:213], v[78:81]
	v_mfma_f32_16x16x32_bf16 v[74:77], v[160:163], v[210:213], v[74:77]
	v_mfma_f32_16x16x32_bf16 v[126:129], v[156:159], v[190:193], v[126:129]
	v_mfma_f32_16x16x32_bf16 v[122:125], v[164:167], v[190:193], v[122:125]
	v_mfma_f32_16x16x32_bf16 v[110:113], v[156:159], v[198:201], v[110:113]
	v_mfma_f32_16x16x32_bf16 v[106:109], v[164:167], v[198:201], v[106:109]
	v_mfma_f32_16x16x32_bf16 v[94:97], v[156:159], v[206:209], v[94:97]
	v_mfma_f32_16x16x32_bf16 v[90:93], v[164:167], v[206:209], v[90:93]
	v_mfma_f32_16x16x32_bf16 v[78:81], v[156:159], v[214:217], v[78:81]
	v_mfma_f32_16x16x32_bf16 v[74:77], v[164:167], v[214:217], v[74:77]
	s_setprio 0
	s_setprio 1
	v_mfma_f32_16x16x32_bf16 v[118:121], v[168:171], v[186:189], v[118:121]
	v_mfma_f32_16x16x32_bf16 v[114:117], v[178:181], v[186:189], v[114:117]
	v_mfma_f32_16x16x32_bf16 v[102:105], v[168:171], v[194:197], v[102:105]
	v_mfma_f32_16x16x32_bf16 v[98:101], v[178:181], v[194:197], v[98:101]
	v_mfma_f32_16x16x32_bf16 v[86:89], v[168:171], v[202:205], v[86:89]
	v_mfma_f32_16x16x32_bf16 v[82:85], v[178:181], v[202:205], v[82:85]
	v_mfma_f32_16x16x32_bf16 v[70:73], v[168:171], v[210:213], v[70:73]
	v_mfma_f32_16x16x32_bf16 v[66:69], v[178:181], v[210:213], v[66:69]
	v_mfma_f32_16x16x32_bf16 v[118:121], v[172:175], v[190:193], v[118:121]
	v_mfma_f32_16x16x32_bf16 v[114:117], v[182:185], v[190:193], v[114:117]
	v_mfma_f32_16x16x32_bf16 v[102:105], v[172:175], v[198:201], v[102:105]
	v_mfma_f32_16x16x32_bf16 v[98:101], v[182:185], v[198:201], v[98:101]
	v_mfma_f32_16x16x32_bf16 v[86:89], v[172:175], v[206:209], v[86:89]
	v_mfma_f32_16x16x32_bf16 v[82:85], v[182:185], v[206:209], v[82:85]
	v_mfma_f32_16x16x32_bf16 v[70:73], v[172:175], v[214:217], v[70:73]
	v_mfma_f32_16x16x32_bf16 v[66:69], v[182:185], v[214:217], v[66:69]
	s_barrier
	s_setprio 0
	s_add_i32 s48, s41, s0
	s_mov_b32 m0, s48
	ds_read_b128 v[186:189], v154 offset:16384
	ds_read_b128 v[190:193], v154 offset:17408
	ds_read_b128 v[194:197], v154 offset:18432
	ds_read_b128 v[198:201], v154 offset:19456
	ds_read_b128 v[202:205], v154 offset:20480
	ds_read_b128 v[206:209], v154 offset:21504
	ds_read_b128 v[210:213], v154 offset:22528
	ds_read_b128 v[214:217], v154 offset:23552
	global_load_lds_dwordx4 v132, s[28:29]
	s_add_i32 m0, s48, 0x2000
	s_add_u32 s48, s28, 0x4000
	s_addc_u32 s49, s29, 0
	s_add_i32 s50, s42, s0
	global_load_lds_dwordx4 v136, s[28:29]
	s_mov_b32 m0, s50
	s_nop 0
	global_load_lds_dwordx4 v132, s[48:49]
	s_add_i32 m0, s50, 0x2000
	s_nop 0
	global_load_lds_dwordx4 v136, s[48:49]
	s_mov_b32 m0, s1
	s_nop 0
	global_load_lds_dwordx4 v130, s[30:31]
	s_mov_b32 m0, s33
	s_nop 0
	global_load_lds_dwordx4 v134, s[30:31]
	s_waitcnt vmcnt(8)
	s_waitcnt lgkmcnt(0)
	s_setprio 1
	s_barrier
	v_mfma_f32_16x16x32_bf16 v[62:65], v[146:149], v[186:189], v[62:65]
	v_mfma_f32_16x16x32_bf16 v[58:61], v[160:163], v[186:189], v[58:61]
	v_mfma_f32_16x16x32_bf16 v[46:49], v[146:149], v[194:197], v[46:49]
	v_mfma_f32_16x16x32_bf16 v[42:45], v[160:163], v[194:197], v[42:45]
	v_mfma_f32_16x16x32_bf16 v[30:33], v[146:149], v[202:205], v[30:33]
	v_mfma_f32_16x16x32_bf16 v[26:29], v[160:163], v[202:205], v[26:29]
	v_mfma_f32_16x16x32_bf16 v[14:17], v[146:149], v[210:213], v[14:17]
	v_mfma_f32_16x16x32_bf16 v[10:13], v[160:163], v[210:213], v[10:13]
	v_mfma_f32_16x16x32_bf16 v[62:65], v[156:159], v[190:193], v[62:65]
	v_mfma_f32_16x16x32_bf16 v[58:61], v[164:167], v[190:193], v[58:61]
	v_mfma_f32_16x16x32_bf16 v[46:49], v[156:159], v[198:201], v[46:49]
	v_mfma_f32_16x16x32_bf16 v[42:45], v[164:167], v[198:201], v[42:45]
	v_mfma_f32_16x16x32_bf16 v[30:33], v[156:159], v[206:209], v[30:33]
	v_mfma_f32_16x16x32_bf16 v[26:29], v[164:167], v[206:209], v[26:29]
	v_mfma_f32_16x16x32_bf16 v[14:17], v[156:159], v[214:217], v[14:17]
	v_mfma_f32_16x16x32_bf16 v[10:13], v[164:167], v[214:217], v[10:13]
	s_setprio 0
	s_setprio 1
	v_mfma_f32_16x16x32_bf16 v[54:57], v[168:171], v[186:189], v[54:57]
	v_mfma_f32_16x16x32_bf16 v[50:53], v[178:181], v[186:189], v[50:53]
	v_mfma_f32_16x16x32_bf16 v[38:41], v[168:171], v[194:197], v[38:41]
	v_mfma_f32_16x16x32_bf16 v[34:37], v[178:181], v[194:197], v[34:37]
	v_mfma_f32_16x16x32_bf16 v[22:25], v[168:171], v[202:205], v[22:25]
	v_mfma_f32_16x16x32_bf16 v[18:21], v[178:181], v[202:205], v[18:21]
	v_mfma_f32_16x16x32_bf16 v[6:9], v[168:171], v[210:213], v[6:9]
	v_mfma_f32_16x16x32_bf16 v[2:5], v[178:181], v[210:213], v[2:5]
	v_mfma_f32_16x16x32_bf16 v[54:57], v[172:175], v[190:193], v[54:57]
	v_mfma_f32_16x16x32_bf16 v[50:53], v[182:185], v[190:193], v[50:53]
	v_mfma_f32_16x16x32_bf16 v[38:41], v[172:175], v[198:201], v[38:41]
	v_mfma_f32_16x16x32_bf16 v[34:37], v[182:185], v[198:201], v[34:37]
	v_mfma_f32_16x16x32_bf16 v[22:25], v[172:175], v[206:209], v[22:25]
	v_mfma_f32_16x16x32_bf16 v[18:21], v[182:185], v[206:209], v[18:21]
	v_mfma_f32_16x16x32_bf16 v[6:9], v[172:175], v[214:217], v[6:9]
	v_mfma_f32_16x16x32_bf16 v[2:5], v[182:185], v[214:217], v[2:5]
	s_barrier
	s_setprio 0
	s_add_i32 s48, 0, 0x18000
	s_add_i32 s49, 0, 0x1c000
	v_add_u32_e32 v164, s48, v151
	v_add_u32_e32 v176, s49, v151
	ds_read_b128 v[146:149], v164
	ds_read_b128 v[156:159], v164 offset:1024
	ds_read_b128 v[160:163], v164 offset:2048
	ds_read_b128 v[164:167], v164 offset:3072
	ds_read_b128 v[168:171], v176
	ds_read_b128 v[172:175], v176 offset:1024
	ds_read_b128 v[178:181], v176 offset:2048
	ds_read_b128 v[182:185], v176 offset:3072
	s_add_u32 s30, s30, 0x4000
	s_addc_u32 s31, s31, 0
	s_mov_b32 m0, s34
	ds_read_b128 v[186:189], v154 offset:32768
	ds_read_b128 v[190:193], v154 offset:33792
	ds_read_b128 v[194:197], v154 offset:34816
	ds_read_b128 v[198:201], v154 offset:35840
	ds_read_b128 v[202:205], v154 offset:36864
	ds_read_b128 v[206:209], v154 offset:37888
	ds_read_b128 v[210:213], v154 offset:38912
	ds_read_b128 v[214:217], v154 offset:39936
	global_load_lds_dwordx4 v130, s[30:31]
	s_mov_b32 m0, s35
	s_nop 0
	global_load_lds_dwordx4 v134, s[30:31]
	s_waitcnt vmcnt(8)
	s_waitcnt lgkmcnt(0)
	s_setprio 1
	s_barrier
	v_mfma_f32_16x16x32_bf16 v[126:129], v[146:149], v[186:189], v[126:129]
	v_mfma_f32_16x16x32_bf16 v[122:125], v[160:163], v[186:189], v[122:125]
	v_mfma_f32_16x16x32_bf16 v[110:113], v[146:149], v[194:197], v[110:113]
	v_mfma_f32_16x16x32_bf16 v[106:109], v[160:163], v[194:197], v[106:109]
	v_mfma_f32_16x16x32_bf16 v[94:97], v[146:149], v[202:205], v[94:97]
	v_mfma_f32_16x16x32_bf16 v[90:93], v[160:163], v[202:205], v[90:93]
	v_mfma_f32_16x16x32_bf16 v[78:81], v[146:149], v[210:213], v[78:81]
	v_mfma_f32_16x16x32_bf16 v[74:77], v[160:163], v[210:213], v[74:77]
	v_mfma_f32_16x16x32_bf16 v[126:129], v[156:159], v[190:193], v[126:129]
	v_mfma_f32_16x16x32_bf16 v[122:125], v[164:167], v[190:193], v[122:125]
	v_mfma_f32_16x16x32_bf16 v[110:113], v[156:159], v[198:201], v[110:113]
	v_mfma_f32_16x16x32_bf16 v[106:109], v[164:167], v[198:201], v[106:109]
	v_mfma_f32_16x16x32_bf16 v[94:97], v[156:159], v[206:209], v[94:97]
	v_mfma_f32_16x16x32_bf16 v[90:93], v[164:167], v[206:209], v[90:93]
	v_mfma_f32_16x16x32_bf16 v[78:81], v[156:159], v[214:217], v[78:81]
	v_mfma_f32_16x16x32_bf16 v[74:77], v[164:167], v[214:217], v[74:77]
	s_setprio 0
	s_setprio 1
	v_mfma_f32_16x16x32_bf16 v[118:121], v[168:171], v[186:189], v[118:121]
	v_mfma_f32_16x16x32_bf16 v[114:117], v[178:181], v[186:189], v[114:117]
	v_mfma_f32_16x16x32_bf16 v[102:105], v[168:171], v[194:197], v[102:105]
	v_mfma_f32_16x16x32_bf16 v[98:101], v[178:181], v[194:197], v[98:101]
	v_mfma_f32_16x16x32_bf16 v[86:89], v[168:171], v[202:205], v[86:89]
	v_mfma_f32_16x16x32_bf16 v[82:85], v[178:181], v[202:205], v[82:85]
	v_mfma_f32_16x16x32_bf16 v[70:73], v[168:171], v[210:213], v[70:73]
	v_mfma_f32_16x16x32_bf16 v[66:69], v[178:181], v[210:213], v[66:69]
	v_mfma_f32_16x16x32_bf16 v[118:121], v[172:175], v[190:193], v[118:121]
	v_mfma_f32_16x16x32_bf16 v[114:117], v[182:185], v[190:193], v[114:117]
	v_mfma_f32_16x16x32_bf16 v[102:105], v[172:175], v[198:201], v[102:105]
	v_mfma_f32_16x16x32_bf16 v[98:101], v[182:185], v[198:201], v[98:101]
	v_mfma_f32_16x16x32_bf16 v[86:89], v[172:175], v[206:209], v[86:89]
	v_mfma_f32_16x16x32_bf16 v[82:85], v[182:185], v[206:209], v[82:85]
	v_mfma_f32_16x16x32_bf16 v[70:73], v[172:175], v[214:217], v[70:73]
	v_mfma_f32_16x16x32_bf16 v[66:69], v[182:185], v[214:217], v[66:69]
	s_barrier
	s_setprio 0
	s_add_u32 s30, s28, 0x80000
	s_addc_u32 s31, s29, 0
	s_add_i32 s48, s48, s0
	s_mov_b32 m0, s48
	ds_read_b128 v[186:189], v154 offset:49152
	ds_read_b128 v[190:193], v154 offset:50176
	ds_read_b128 v[194:197], v154 offset:51200
	ds_read_b128 v[198:201], v154 offset:52224
	ds_read_b128 v[202:205], v154 offset:53248
	ds_read_b128 v[206:209], v154 offset:54272
	ds_read_b128 v[210:213], v154 offset:55296
	ds_read_b128 v[214:217], v154 offset:56320
	global_load_lds_dwordx4 v132, s[30:31]
	s_add_i32 m0, s48, 0x2000
	s_add_u32 s28, s28, 0x84000
	s_addc_u32 s29, s29, 0
	global_load_lds_dwordx4 v136, s[30:31]
	s_add_i32 s30, s49, s0
	s_mov_b32 m0, s30
	s_nop 0
	global_load_lds_dwordx4 v132, s[28:29]
	s_add_i32 m0, s30, 0x2000
	s_nop 0
	global_load_lds_dwordx4 v136, s[28:29]
	s_mov_b32 m0, s39
	s_nop 0
	global_load_lds_dwordx4 v130, s[26:27]
	s_mov_b32 m0, s40
	s_nop 0
	global_load_lds_dwordx4 v134, s[26:27]
	s_waitcnt vmcnt(8)
	s_waitcnt lgkmcnt(0)
	s_setprio 1
	s_barrier
	v_mfma_f32_16x16x32_bf16 v[62:65], v[146:149], v[186:189], v[62:65]
	v_mfma_f32_16x16x32_bf16 v[58:61], v[160:163], v[186:189], v[58:61]
	v_mfma_f32_16x16x32_bf16 v[46:49], v[146:149], v[194:197], v[46:49]
	v_mfma_f32_16x16x32_bf16 v[42:45], v[160:163], v[194:197], v[42:45]
	v_mfma_f32_16x16x32_bf16 v[30:33], v[146:149], v[202:205], v[30:33]
	v_mfma_f32_16x16x32_bf16 v[26:29], v[160:163], v[202:205], v[26:29]
	v_mfma_f32_16x16x32_bf16 v[14:17], v[146:149], v[210:213], v[14:17]
	v_mfma_f32_16x16x32_bf16 v[10:13], v[160:163], v[210:213], v[10:13]
	v_mfma_f32_16x16x32_bf16 v[62:65], v[156:159], v[190:193], v[62:65]
	v_mfma_f32_16x16x32_bf16 v[58:61], v[164:167], v[190:193], v[58:61]
	v_mfma_f32_16x16x32_bf16 v[46:49], v[156:159], v[198:201], v[46:49]
	v_mfma_f32_16x16x32_bf16 v[42:45], v[164:167], v[198:201], v[42:45]
	v_mfma_f32_16x16x32_bf16 v[30:33], v[156:159], v[206:209], v[30:33]
	v_mfma_f32_16x16x32_bf16 v[26:29], v[164:167], v[206:209], v[26:29]
	v_mfma_f32_16x16x32_bf16 v[14:17], v[156:159], v[214:217], v[14:17]
	v_mfma_f32_16x16x32_bf16 v[10:13], v[164:167], v[214:217], v[10:13]
	s_setprio 0
	s_setprio 1
	v_mfma_f32_16x16x32_bf16 v[54:57], v[168:171], v[186:189], v[54:57]
	v_mfma_f32_16x16x32_bf16 v[50:53], v[178:181], v[186:189], v[50:53]
	v_mfma_f32_16x16x32_bf16 v[38:41], v[168:171], v[194:197], v[38:41]
	v_mfma_f32_16x16x32_bf16 v[34:37], v[178:181], v[194:197], v[34:37]
	v_mfma_f32_16x16x32_bf16 v[22:25], v[168:171], v[202:205], v[22:25]
	v_mfma_f32_16x16x32_bf16 v[18:21], v[178:181], v[202:205], v[18:21]
	v_mfma_f32_16x16x32_bf16 v[6:9], v[168:171], v[210:213], v[6:9]
	v_mfma_f32_16x16x32_bf16 v[2:5], v[178:181], v[210:213], v[2:5]
	v_mfma_f32_16x16x32_bf16 v[54:57], v[172:175], v[190:193], v[54:57]
	v_mfma_f32_16x16x32_bf16 v[50:53], v[182:185], v[190:193], v[50:53]
	v_mfma_f32_16x16x32_bf16 v[38:41], v[172:175], v[198:201], v[38:41]
	v_mfma_f32_16x16x32_bf16 v[34:37], v[182:185], v[198:201], v[34:37]
	v_mfma_f32_16x16x32_bf16 v[22:25], v[172:175], v[206:209], v[22:25]
	v_mfma_f32_16x16x32_bf16 v[18:21], v[182:185], v[206:209], v[18:21]
	v_mfma_f32_16x16x32_bf16 v[6:9], v[172:175], v[214:217], v[6:9]
	v_mfma_f32_16x16x32_bf16 v[2:5], v[182:185], v[214:217], v[2:5]
	s_barrier
	s_setprio 0
	s_add_i32 s47, s47, 2
	s_add_u32 s45, s45, 0x100000
	s_addc_u32 s46, s46, 0
	s_add_u32 s10, s10, 0x200000
	s_addc_u32 s11, s11, 0
	s_cmpk_gt_u32 s47, 0xdd
	s_cbranch_scc0 .LBB0_501
	s_and_b64 vcc, exec, s[16:17]
	s_cbranch_vccz .LBB0_504
	s_barrier

.LBB0_801:
	ds_read_b128 v[130:133], v179
	ds_read_b128 v[134:137], v179 offset:1024
	ds_read_b128 v[156:159], v179 offset:2048
	ds_read_b128 v[160:163], v179 offset:3072
	ds_read_b128 v[164:167], v180
	ds_read_b128 v[168:171], v180 offset:1024
	ds_read_b128 v[172:175], v180 offset:2048
	ds_read_b128 v[186:189], v180 offset:3072
	s_add_u32 s26, s12, 0xfc000
	s_addc_u32 s27, s13, 0
	s_cmp_eq_u32 s47, 60
	s_cselect_b32 s30, s5, s26
	s_cselect_b32 s31, s3, s27
	s_cselect_b32 s28, s21, s45
	s_cselect_b32 s29, s19, s46
	s_add_u32 s26, s30, 0x100000
	s_addc_u32 s27, s31, 0
	s_add_i32 m0, s1, 0xc000
	ds_read_b128 v[190:193], v181
	ds_read_b128 v[194:197], v181 offset:1024
	ds_read_b128 v[198:201], v181 offset:2048
	ds_read_b128 v[202:205], v181 offset:3072
	ds_read_b128 v[206:209], v181 offset:4096
	ds_read_b128 v[210:213], v181 offset:5120
	ds_read_b128 v[214:217], v181 offset:6144
	ds_read_b128 v[218:221], v181 offset:7168
	global_load_lds_dwordx4 v148, s[12:13]
	s_add_i32 m0, s1, 0xe000
	s_nop 0
	global_load_lds_dwordx4 v150, s[12:13]
	s_waitcnt vmcnt(8)
	s_waitcnt lgkmcnt(0)
	s_setprio 1
	s_barrier
	v_mfma_f32_16x16x32_bf16 v[126:129], v[130:133], v[190:193], v[126:129]
	v_mfma_f32_16x16x32_bf16 v[122:125], v[156:159], v[190:193], v[122:125]
	v_mfma_f32_16x16x32_bf16 v[110:113], v[130:133], v[198:201], v[110:113]
	v_mfma_f32_16x16x32_bf16 v[106:109], v[156:159], v[198:201], v[106:109]
	v_mfma_f32_16x16x32_bf16 v[94:97], v[130:133], v[206:209], v[94:97]
	v_mfma_f32_16x16x32_bf16 v[90:93], v[156:159], v[206:209], v[90:93]
	v_mfma_f32_16x16x32_bf16 v[78:81], v[130:133], v[214:217], v[78:81]
	v_mfma_f32_16x16x32_bf16 v[74:77], v[156:159], v[214:217], v[74:77]
	v_mfma_f32_16x16x32_bf16 v[126:129], v[134:137], v[194:197], v[126:129]
	v_mfma_f32_16x16x32_bf16 v[122:125], v[160:163], v[194:197], v[122:125]
	v_mfma_f32_16x16x32_bf16 v[110:113], v[134:137], v[202:205], v[110:113]
	v_mfma_f32_16x16x32_bf16 v[106:109], v[160:163], v[202:205], v[106:109]
	v_mfma_f32_16x16x32_bf16 v[94:97], v[134:137], v[210:213], v[94:97]
	v_mfma_f32_16x16x32_bf16 v[90:93], v[160:163], v[210:213], v[90:93]
	v_mfma_f32_16x16x32_bf16 v[78:81], v[134:137], v[218:221], v[78:81]
	v_mfma_f32_16x16x32_bf16 v[74:77], v[160:163], v[218:221], v[74:77]
	s_setprio 0
	s_setprio 1
	v_mfma_f32_16x16x32_bf16 v[118:121], v[164:167], v[190:193], v[118:121]
	v_mfma_f32_16x16x32_bf16 v[114:117], v[172:175], v[190:193], v[114:117]
	v_mfma_f32_16x16x32_bf16 v[102:105], v[164:167], v[198:201], v[102:105]
	v_mfma_f32_16x16x32_bf16 v[98:101], v[172:175], v[198:201], v[98:101]
	v_mfma_f32_16x16x32_bf16 v[86:89], v[164:167], v[206:209], v[86:89]
	v_mfma_f32_16x16x32_bf16 v[82:85], v[172:175], v[206:209], v[82:85]
	v_mfma_f32_16x16x32_bf16 v[70:73], v[164:167], v[214:217], v[70:73]
	v_mfma_f32_16x16x32_bf16 v[66:69], v[172:175], v[214:217], v[66:69]
	v_mfma_f32_16x16x32_bf16 v[118:121], v[168:171], v[194:197], v[118:121]
	v_mfma_f32_16x16x32_bf16 v[114:117], v[186:189], v[194:197], v[114:117]
	v_mfma_f32_16x16x32_bf16 v[102:105], v[168:171], v[202:205], v[102:105]
	v_mfma_f32_16x16x32_bf16 v[98:101], v[186:189], v[202:205], v[98:101]
	v_mfma_f32_16x16x32_bf16 v[86:89], v[168:171], v[210:213], v[86:89]
	v_mfma_f32_16x16x32_bf16 v[82:85], v[186:189], v[210:213], v[82:85]
	v_mfma_f32_16x16x32_bf16 v[70:73], v[168:171], v[218:221], v[70:73]
	v_mfma_f32_16x16x32_bf16 v[66:69], v[186:189], v[218:221], v[66:69]
	s_barrier
	s_setprio 0
	s_add_i32 s48, s42, s0
	s_mov_b32 m0, s48
	ds_read_b128 v[190:193], v181 offset:16384
	ds_read_b128 v[194:197], v181 offset:17408
	ds_read_b128 v[198:201], v181 offset:18432
	ds_read_b128 v[202:205], v181 offset:19456
	ds_read_b128 v[206:209], v181 offset:20480
	ds_read_b128 v[210:213], v181 offset:21504
	ds_read_b128 v[214:217], v181 offset:22528
	ds_read_b128 v[218:221], v181 offset:23552
	global_load_lds_dwordx4 v140, s[28:29]
	s_add_i32 m0, s48, 0x2000
	s_add_u32 s48, s28, 0x4000
	s_addc_u32 s49, s29, 0
	s_add_i32 s50, s43, s0
	global_load_lds_dwordx4 v144, s[28:29]
	s_mov_b32 m0, s50
	s_nop 0
	global_load_lds_dwordx4 v140, s[48:49]
	s_add_i32 m0, s50, 0x2000
	s_nop 0
	global_load_lds_dwordx4 v144, s[48:49]
	s_mov_b32 m0, s1
	s_nop 0
	global_load_lds_dwordx4 v138, s[30:31]
	s_mov_b32 m0, s33
	s_nop 0
	global_load_lds_dwordx4 v142, s[30:31]
	s_waitcnt vmcnt(8)
	s_waitcnt lgkmcnt(0)
	s_setprio 1
	s_barrier
	v_mfma_f32_16x16x32_bf16 v[62:65], v[130:133], v[190:193], v[62:65]
	v_mfma_f32_16x16x32_bf16 v[58:61], v[156:159], v[190:193], v[58:61]
	v_mfma_f32_16x16x32_bf16 v[46:49], v[130:133], v[198:201], v[46:49]
	v_mfma_f32_16x16x32_bf16 v[42:45], v[156:159], v[198:201], v[42:45]
	v_mfma_f32_16x16x32_bf16 v[30:33], v[130:133], v[206:209], v[30:33]
	v_mfma_f32_16x16x32_bf16 v[26:29], v[156:159], v[206:209], v[26:29]
	v_mfma_f32_16x16x32_bf16 v[14:17], v[130:133], v[214:217], v[14:17]
	v_mfma_f32_16x16x32_bf16 v[10:13], v[156:159], v[214:217], v[10:13]
	v_mfma_f32_16x16x32_bf16 v[62:65], v[134:137], v[194:197], v[62:65]
	v_mfma_f32_16x16x32_bf16 v[58:61], v[160:163], v[194:197], v[58:61]
	v_mfma_f32_16x16x32_bf16 v[46:49], v[134:137], v[202:205], v[46:49]
	v_mfma_f32_16x16x32_bf16 v[42:45], v[160:163], v[202:205], v[42:45]
	v_mfma_f32_16x16x32_bf16 v[30:33], v[134:137], v[210:213], v[30:33]
	v_mfma_f32_16x16x32_bf16 v[26:29], v[160:163], v[210:213], v[26:29]
	v_mfma_f32_16x16x32_bf16 v[14:17], v[134:137], v[218:221], v[14:17]
	v_mfma_f32_16x16x32_bf16 v[10:13], v[160:163], v[218:221], v[10:13]
	s_setprio 0
	s_setprio 1
	v_mfma_f32_16x16x32_bf16 v[54:57], v[164:167], v[190:193], v[54:57]
	v_mfma_f32_16x16x32_bf16 v[50:53], v[172:175], v[190:193], v[50:53]
	v_mfma_f32_16x16x32_bf16 v[38:41], v[164:167], v[198:201], v[38:41]
	v_mfma_f32_16x16x32_bf16 v[34:37], v[172:175], v[198:201], v[34:37]
	v_mfma_f32_16x16x32_bf16 v[22:25], v[164:167], v[206:209], v[22:25]
	v_mfma_f32_16x16x32_bf16 v[18:21], v[172:175], v[206:209], v[18:21]
	v_mfma_f32_16x16x32_bf16 v[6:9], v[164:167], v[214:217], v[6:9]
	v_mfma_f32_16x16x32_bf16 v[2:5], v[172:175], v[214:217], v[2:5]
	v_mfma_f32_16x16x32_bf16 v[54:57], v[168:171], v[194:197], v[54:57]
	v_mfma_f32_16x16x32_bf16 v[50:53], v[186:189], v[194:197], v[50:53]
	v_mfma_f32_16x16x32_bf16 v[38:41], v[168:171], v[202:205], v[38:41]
	v_mfma_f32_16x16x32_bf16 v[34:37], v[186:189], v[202:205], v[34:37]
	v_mfma_f32_16x16x32_bf16 v[22:25], v[168:171], v[210:213], v[22:25]
	v_mfma_f32_16x16x32_bf16 v[18:21], v[186:189], v[210:213], v[18:21]
	v_mfma_f32_16x16x32_bf16 v[6:9], v[168:171], v[218:221], v[6:9]
	v_mfma_f32_16x16x32_bf16 v[2:5], v[186:189], v[218:221], v[2:5]
	s_barrier
	s_setprio 0
	s_add_i32 s48, 0, 0x18000
	v_add_u32_e32 v146, s48, v178
	s_add_i32 s49, 0, 0x1c000
	ds_read_b128 v[130:133], v146
	ds_read_b128 v[134:137], v146 offset:1024
	ds_read_b128 v[156:159], v146 offset:2048
	ds_read_b128 v[160:163], v146 offset:3072
	v_add_u32_e32 v146, s49, v178
	ds_read_b128 v[164:167], v146
	ds_read_b128 v[168:171], v146 offset:1024
	ds_read_b128 v[172:175], v146 offset:2048
	ds_read_b128 v[186:189], v146 offset:3072
	s_add_u32 s30, s30, 0x4000
	s_addc_u32 s31, s31, 0
	s_mov_b32 m0, s34
	ds_read_b128 v[190:193], v181 offset:32768
	ds_read_b128 v[194:197], v181 offset:33792
	ds_read_b128 v[198:201], v181 offset:34816
	ds_read_b128 v[202:205], v181 offset:35840
	ds_read_b128 v[206:209], v181 offset:36864
	ds_read_b128 v[210:213], v181 offset:37888
	ds_read_b128 v[214:217], v181 offset:38912
	ds_read_b128 v[218:221], v181 offset:39936
	global_load_lds_dwordx4 v138, s[30:31]
	s_mov_b32 m0, s35
	s_nop 0
	global_load_lds_dwordx4 v142, s[30:31]
	s_waitcnt vmcnt(8)
	s_waitcnt lgkmcnt(0)
	s_setprio 1
	s_barrier
	v_mfma_f32_16x16x32_bf16 v[126:129], v[130:133], v[190:193], v[126:129]
	v_mfma_f32_16x16x32_bf16 v[122:125], v[156:159], v[190:193], v[122:125]
	v_mfma_f32_16x16x32_bf16 v[110:113], v[130:133], v[198:201], v[110:113]
	v_mfma_f32_16x16x32_bf16 v[106:109], v[156:159], v[198:201], v[106:109]
	v_mfma_f32_16x16x32_bf16 v[94:97], v[130:133], v[206:209], v[94:97]
	v_mfma_f32_16x16x32_bf16 v[90:93], v[156:159], v[206:209], v[90:93]
	v_mfma_f32_16x16x32_bf16 v[78:81], v[130:133], v[214:217], v[78:81]
	v_mfma_f32_16x16x32_bf16 v[74:77], v[156:159], v[214:217], v[74:77]
	v_mfma_f32_16x16x32_bf16 v[126:129], v[134:137], v[194:197], v[126:129]
	v_mfma_f32_16x16x32_bf16 v[122:125], v[160:163], v[194:197], v[122:125]
	v_mfma_f32_16x16x32_bf16 v[110:113], v[134:137], v[202:205], v[110:113]
	v_mfma_f32_16x16x32_bf16 v[106:109], v[160:163], v[202:205], v[106:109]
	v_mfma_f32_16x16x32_bf16 v[94:97], v[134:137], v[210:213], v[94:97]
	v_mfma_f32_16x16x32_bf16 v[90:93], v[160:163], v[210:213], v[90:93]
	v_mfma_f32_16x16x32_bf16 v[78:81], v[134:137], v[218:221], v[78:81]
	v_mfma_f32_16x16x32_bf16 v[74:77], v[160:163], v[218:221], v[74:77]
	s_setprio 0
	s_setprio 1
	v_mfma_f32_16x16x32_bf16 v[118:121], v[164:167], v[190:193], v[118:121]
	v_mfma_f32_16x16x32_bf16 v[114:117], v[172:175], v[190:193], v[114:117]
	v_mfma_f32_16x16x32_bf16 v[102:105], v[164:167], v[198:201], v[102:105]
	v_mfma_f32_16x16x32_bf16 v[98:101], v[172:175], v[198:201], v[98:101]
	v_mfma_f32_16x16x32_bf16 v[86:89], v[164:167], v[206:209], v[86:89]
	v_mfma_f32_16x16x32_bf16 v[82:85], v[172:175], v[206:209], v[82:85]
	v_mfma_f32_16x16x32_bf16 v[70:73], v[164:167], v[214:217], v[70:73]
	v_mfma_f32_16x16x32_bf16 v[66:69], v[172:175], v[214:217], v[66:69]
	v_mfma_f32_16x16x32_bf16 v[118:121], v[168:171], v[194:197], v[118:121]
	v_mfma_f32_16x16x32_bf16 v[114:117], v[186:189], v[194:197], v[114:117]
	v_mfma_f32_16x16x32_bf16 v[102:105], v[168:171], v[202:205], v[102:105]
	v_mfma_f32_16x16x32_bf16 v[98:101], v[186:189], v[202:205], v[98:101]
	v_mfma_f32_16x16x32_bf16 v[86:89], v[168:171], v[210:213], v[86:89]
	v_mfma_f32_16x16x32_bf16 v[82:85], v[186:189], v[210:213], v[82:85]
	v_mfma_f32_16x16x32_bf16 v[70:73], v[168:171], v[218:221], v[70:73]
	v_mfma_f32_16x16x32_bf16 v[66:69], v[186:189], v[218:221], v[66:69]
	s_barrier
	s_setprio 0
	s_add_u32 s30, s28, 0x180000
	s_addc_u32 s31, s29, 0
	s_add_i32 s48, s48, s0
	s_mov_b32 m0, s48
	ds_read_b128 v[190:193], v181 offset:49152
	ds_read_b128 v[194:197], v181 offset:50176
	ds_read_b128 v[198:201], v181 offset:51200
	ds_read_b128 v[202:205], v181 offset:52224
	ds_read_b128 v[206:209], v181 offset:53248
	ds_read_b128 v[210:213], v181 offset:54272
	ds_read_b128 v[214:217], v181 offset:55296
	ds_read_b128 v[218:221], v181 offset:56320
	global_load_lds_dwordx4 v140, s[30:31]
	s_add_i32 m0, s48, 0x2000
	s_add_u32 s28, s28, 0x184000
	s_addc_u32 s29, s29, 0
	global_load_lds_dwordx4 v144, s[30:31]
	s_add_i32 s30, s49, s0
	s_mov_b32 m0, s30
	s_nop 0
	global_load_lds_dwordx4 v140, s[28:29]
	s_add_i32 m0, s30, 0x2000
	s_nop 0
	global_load_lds_dwordx4 v144, s[28:29]
	s_mov_b32 m0, s38
	s_nop 0
	global_load_lds_dwordx4 v138, s[26:27]
	s_mov_b32 m0, s39
	s_nop 0
	global_load_lds_dwordx4 v142, s[26:27]
	s_waitcnt vmcnt(8)
	s_waitcnt lgkmcnt(0)
	s_setprio 1
	s_barrier
	v_mfma_f32_16x16x32_bf16 v[62:65], v[130:133], v[190:193], v[62:65]
	v_mfma_f32_16x16x32_bf16 v[58:61], v[156:159], v[190:193], v[58:61]
	v_mfma_f32_16x16x32_bf16 v[46:49], v[130:133], v[198:201], v[46:49]
	v_mfma_f32_16x16x32_bf16 v[42:45], v[156:159], v[198:201], v[42:45]
	v_mfma_f32_16x16x32_bf16 v[30:33], v[130:133], v[206:209], v[30:33]
	v_mfma_f32_16x16x32_bf16 v[26:29], v[156:159], v[206:209], v[26:29]
	v_mfma_f32_16x16x32_bf16 v[14:17], v[130:133], v[214:217], v[14:17]
	v_mfma_f32_16x16x32_bf16 v[10:13], v[156:159], v[214:217], v[10:13]
	v_mfma_f32_16x16x32_bf16 v[62:65], v[134:137], v[194:197], v[62:65]
	v_mfma_f32_16x16x32_bf16 v[58:61], v[160:163], v[194:197], v[58:61]
	v_mfma_f32_16x16x32_bf16 v[46:49], v[134:137], v[202:205], v[46:49]
	v_mfma_f32_16x16x32_bf16 v[42:45], v[160:163], v[202:205], v[42:45]
	v_mfma_f32_16x16x32_bf16 v[30:33], v[134:137], v[210:213], v[30:33]
	v_mfma_f32_16x16x32_bf16 v[26:29], v[160:163], v[210:213], v[26:29]
	v_mfma_f32_16x16x32_bf16 v[14:17], v[134:137], v[218:221], v[14:17]
	v_mfma_f32_16x16x32_bf16 v[10:13], v[160:163], v[218:221], v[10:13]
	s_setprio 0
	s_setprio 1
	v_mfma_f32_16x16x32_bf16 v[54:57], v[164:167], v[190:193], v[54:57]
	v_mfma_f32_16x16x32_bf16 v[50:53], v[172:175], v[190:193], v[50:53]
	v_mfma_f32_16x16x32_bf16 v[38:41], v[164:167], v[198:201], v[38:41]
	v_mfma_f32_16x16x32_bf16 v[34:37], v[172:175], v[198:201], v[34:37]
	v_mfma_f32_16x16x32_bf16 v[22:25], v[164:167], v[206:209], v[22:25]
	v_mfma_f32_16x16x32_bf16 v[18:21], v[172:175], v[206:209], v[18:21]
	v_mfma_f32_16x16x32_bf16 v[6:9], v[164:167], v[214:217], v[6:9]
	v_mfma_f32_16x16x32_bf16 v[2:5], v[172:175], v[214:217], v[2:5]
	v_mfma_f32_16x16x32_bf16 v[54:57], v[168:171], v[194:197], v[54:57]
	v_mfma_f32_16x16x32_bf16 v[50:53], v[186:189], v[194:197], v[50:53]
	v_mfma_f32_16x16x32_bf16 v[38:41], v[168:171], v[202:205], v[38:41]
	v_mfma_f32_16x16x32_bf16 v[34:37], v[186:189], v[202:205], v[34:37]
	v_mfma_f32_16x16x32_bf16 v[22:25], v[168:171], v[210:213], v[22:25]
	v_mfma_f32_16x16x32_bf16 v[18:21], v[186:189], v[210:213], v[18:21]
	v_mfma_f32_16x16x32_bf16 v[6:9], v[168:171], v[218:221], v[6:9]
	v_mfma_f32_16x16x32_bf16 v[2:5], v[186:189], v[218:221], v[2:5]
	s_barrier
	s_setprio 0
	s_add_i32 s47, s47, 2
	s_add_u32 s45, s45, 0x300000
	s_addc_u32 s46, s46, 0
	s_add_u32 s12, s12, 0x200000
	s_addc_u32 s13, s13, 0
	s_cmp_gt_u32 s47, 61
	s_cbranch_scc0 .LBB0_801
	s_and_b64 vcc, exec, s[8:9]
	s_cbranch_vccz .LBB0_804
	s_barrier

.LBB0_1217:
	ds_read_b128 v[146:149], v152
	ds_read_b128 v[156:159], v152 offset:1024
	ds_read_b128 v[160:163], v152 offset:2048
	ds_read_b128 v[164:167], v152 offset:3072
	ds_read_b128 v[168:171], v153
	ds_read_b128 v[172:175], v153 offset:1024
	ds_read_b128 v[176:179], v153 offset:2048
	ds_read_b128 v[180:183], v153 offset:3072
	s_add_u32 s22, s20, 0xfc000
	s_addc_u32 s23, s21, 0
	s_cmp_eq_u32 s43, 60
	s_cselect_b32 s26, s15, s22
	s_cselect_b32 s27, s5, s23
	s_cselect_b32 s24, s40, s41
	s_cselect_b32 s25, s13, s42
	s_add_u32 s22, s26, 0x100000
	s_addc_u32 s23, s27, 0
	s_add_i32 m0, s1, 0xc000
	ds_read_b128 v[184:187], v154
	ds_read_b128 v[188:191], v154 offset:1024
	ds_read_b128 v[192:195], v154 offset:2048
	ds_read_b128 v[196:199], v154 offset:3072
	ds_read_b128 v[206:209], v154 offset:4096
	ds_read_b128 v[212:215], v154 offset:5120
	ds_read_b128 v[220:223], v154 offset:6144
	ds_read_b128 v[224:227], v154 offset:7168
	global_load_lds_dwordx4 v138, s[20:21]
	s_add_i32 m0, s1, 0xe000
	s_nop 0
	global_load_lds_dwordx4 v140, s[20:21]
	s_waitcnt vmcnt(8)
	s_waitcnt lgkmcnt(0)
	s_setprio 1
	s_barrier
	v_mfma_f32_16x16x32_bf16 v[126:129], v[146:149], v[184:187], v[126:129]
	v_mfma_f32_16x16x32_bf16 v[122:125], v[160:163], v[184:187], v[122:125]
	v_mfma_f32_16x16x32_bf16 v[110:113], v[146:149], v[192:195], v[110:113]
	v_mfma_f32_16x16x32_bf16 v[106:109], v[160:163], v[192:195], v[106:109]
	v_mfma_f32_16x16x32_bf16 v[94:97], v[146:149], v[206:209], v[94:97]
	v_mfma_f32_16x16x32_bf16 v[90:93], v[160:163], v[206:209], v[90:93]
	v_mfma_f32_16x16x32_bf16 v[78:81], v[146:149], v[220:223], v[78:81]
	v_mfma_f32_16x16x32_bf16 v[74:77], v[160:163], v[220:223], v[74:77]
	v_mfma_f32_16x16x32_bf16 v[126:129], v[156:159], v[188:191], v[126:129]
	v_mfma_f32_16x16x32_bf16 v[122:125], v[164:167], v[188:191], v[122:125]
	v_mfma_f32_16x16x32_bf16 v[110:113], v[156:159], v[196:199], v[110:113]
	v_mfma_f32_16x16x32_bf16 v[106:109], v[164:167], v[196:199], v[106:109]
	v_mfma_f32_16x16x32_bf16 v[94:97], v[156:159], v[212:215], v[94:97]
	v_mfma_f32_16x16x32_bf16 v[90:93], v[164:167], v[212:215], v[90:93]
	v_mfma_f32_16x16x32_bf16 v[78:81], v[156:159], v[224:227], v[78:81]
	v_mfma_f32_16x16x32_bf16 v[74:77], v[164:167], v[224:227], v[74:77]
	s_setprio 0
	s_setprio 1
	v_mfma_f32_16x16x32_bf16 v[118:121], v[168:171], v[184:187], v[118:121]
	v_mfma_f32_16x16x32_bf16 v[114:117], v[176:179], v[184:187], v[114:117]
	v_mfma_f32_16x16x32_bf16 v[102:105], v[168:171], v[192:195], v[102:105]
	v_mfma_f32_16x16x32_bf16 v[98:101], v[176:179], v[192:195], v[98:101]
	v_mfma_f32_16x16x32_bf16 v[86:89], v[168:171], v[206:209], v[86:89]
	v_mfma_f32_16x16x32_bf16 v[82:85], v[176:179], v[206:209], v[82:85]
	v_mfma_f32_16x16x32_bf16 v[70:73], v[168:171], v[220:223], v[70:73]
	v_mfma_f32_16x16x32_bf16 v[66:69], v[176:179], v[220:223], v[66:69]
	v_mfma_f32_16x16x32_bf16 v[118:121], v[172:175], v[188:191], v[118:121]
	v_mfma_f32_16x16x32_bf16 v[114:117], v[180:183], v[188:191], v[114:117]
	v_mfma_f32_16x16x32_bf16 v[102:105], v[172:175], v[196:199], v[102:105]
	v_mfma_f32_16x16x32_bf16 v[98:101], v[180:183], v[196:199], v[98:101]
	v_mfma_f32_16x16x32_bf16 v[86:89], v[172:175], v[212:215], v[86:89]
	v_mfma_f32_16x16x32_bf16 v[82:85], v[180:183], v[212:215], v[82:85]
	v_mfma_f32_16x16x32_bf16 v[70:73], v[172:175], v[224:227], v[70:73]
	v_mfma_f32_16x16x32_bf16 v[66:69], v[180:183], v[224:227], v[66:69]
	s_barrier
	s_setprio 0
	s_add_i32 s44, s37, s0
	s_mov_b32 m0, s44
	ds_read_b128 v[184:187], v154 offset:16384
	ds_read_b128 v[188:191], v154 offset:17408
	ds_read_b128 v[192:195], v154 offset:18432
	ds_read_b128 v[196:199], v154 offset:19456
	ds_read_b128 v[206:209], v154 offset:20480
	ds_read_b128 v[212:215], v154 offset:21504
	ds_read_b128 v[220:223], v154 offset:22528
	ds_read_b128 v[224:227], v154 offset:23552
	global_load_lds_dwordx4 v132, s[24:25]
	s_add_i32 m0, s44, 0x2000
	s_add_u32 s44, s24, 0x4000
	s_addc_u32 s45, s25, 0
	s_add_i32 s46, s38, s0
	global_load_lds_dwordx4 v136, s[24:25]
	s_mov_b32 m0, s46
	s_nop 0
	global_load_lds_dwordx4 v132, s[44:45]
	s_add_i32 m0, s46, 0x2000
	s_nop 0
	global_load_lds_dwordx4 v136, s[44:45]
	s_mov_b32 m0, s1
	s_nop 0
	global_load_lds_dwordx4 v130, s[26:27]
	s_mov_b32 m0, s28
	s_nop 0
	global_load_lds_dwordx4 v134, s[26:27]
	s_waitcnt vmcnt(8)
	s_waitcnt lgkmcnt(0)
	s_setprio 1
	s_barrier
	v_mfma_f32_16x16x32_bf16 v[62:65], v[146:149], v[184:187], v[62:65]
	v_mfma_f32_16x16x32_bf16 v[58:61], v[160:163], v[184:187], v[58:61]
	v_mfma_f32_16x16x32_bf16 v[46:49], v[146:149], v[192:195], v[46:49]
	v_mfma_f32_16x16x32_bf16 v[42:45], v[160:163], v[192:195], v[42:45]
	v_mfma_f32_16x16x32_bf16 v[30:33], v[146:149], v[206:209], v[30:33]
	v_mfma_f32_16x16x32_bf16 v[26:29], v[160:163], v[206:209], v[26:29]
	v_mfma_f32_16x16x32_bf16 v[14:17], v[146:149], v[220:223], v[14:17]
	v_mfma_f32_16x16x32_bf16 v[10:13], v[160:163], v[220:223], v[10:13]
	v_mfma_f32_16x16x32_bf16 v[62:65], v[156:159], v[188:191], v[62:65]
	v_mfma_f32_16x16x32_bf16 v[58:61], v[164:167], v[188:191], v[58:61]
	v_mfma_f32_16x16x32_bf16 v[46:49], v[156:159], v[196:199], v[46:49]
	v_mfma_f32_16x16x32_bf16 v[42:45], v[164:167], v[196:199], v[42:45]
	v_mfma_f32_16x16x32_bf16 v[30:33], v[156:159], v[212:215], v[30:33]
	v_mfma_f32_16x16x32_bf16 v[26:29], v[164:167], v[212:215], v[26:29]
	v_mfma_f32_16x16x32_bf16 v[14:17], v[156:159], v[224:227], v[14:17]
	v_mfma_f32_16x16x32_bf16 v[10:13], v[164:167], v[224:227], v[10:13]
	s_setprio 0
	s_setprio 1
	v_mfma_f32_16x16x32_bf16 v[54:57], v[168:171], v[184:187], v[54:57]
	v_mfma_f32_16x16x32_bf16 v[50:53], v[176:179], v[184:187], v[50:53]
	v_mfma_f32_16x16x32_bf16 v[38:41], v[168:171], v[192:195], v[38:41]
	v_mfma_f32_16x16x32_bf16 v[34:37], v[176:179], v[192:195], v[34:37]
	v_mfma_f32_16x16x32_bf16 v[22:25], v[168:171], v[206:209], v[22:25]
	v_mfma_f32_16x16x32_bf16 v[18:21], v[176:179], v[206:209], v[18:21]
	v_mfma_f32_16x16x32_bf16 v[6:9], v[168:171], v[220:223], v[6:9]
	v_mfma_f32_16x16x32_bf16 v[2:5], v[176:179], v[220:223], v[2:5]
	v_mfma_f32_16x16x32_bf16 v[54:57], v[172:175], v[188:191], v[54:57]
	v_mfma_f32_16x16x32_bf16 v[50:53], v[180:183], v[188:191], v[50:53]
	v_mfma_f32_16x16x32_bf16 v[38:41], v[172:175], v[196:199], v[38:41]
	v_mfma_f32_16x16x32_bf16 v[34:37], v[180:183], v[196:199], v[34:37]
	v_mfma_f32_16x16x32_bf16 v[22:25], v[172:175], v[212:215], v[22:25]
	v_mfma_f32_16x16x32_bf16 v[18:21], v[180:183], v[212:215], v[18:21]
	v_mfma_f32_16x16x32_bf16 v[6:9], v[172:175], v[224:227], v[6:9]
	v_mfma_f32_16x16x32_bf16 v[2:5], v[180:183], v[224:227], v[2:5]
	s_barrier
	s_setprio 0
	s_add_i32 s44, 0, 0x18000
	v_add_u32_e32 v155, s44, v151
	s_add_i32 s45, 0, 0x1c000
	ds_read_b128 v[146:149], v155
	ds_read_b128 v[156:159], v155 offset:1024
	ds_read_b128 v[160:163], v155 offset:2048
	ds_read_b128 v[164:167], v155 offset:3072
	v_add_u32_e32 v155, s45, v151
	ds_read_b128 v[168:171], v155
	ds_read_b128 v[172:175], v155 offset:1024
	ds_read_b128 v[176:179], v155 offset:2048
	ds_read_b128 v[180:183], v155 offset:3072
	s_add_u32 s26, s26, 0x4000
	s_addc_u32 s27, s27, 0
	s_mov_b32 m0, s29
	ds_read_b128 v[184:187], v154 offset:32768
	ds_read_b128 v[188:191], v154 offset:33792
	ds_read_b128 v[192:195], v154 offset:34816
	ds_read_b128 v[196:199], v154 offset:35840
	ds_read_b128 v[206:209], v154 offset:36864
	ds_read_b128 v[212:215], v154 offset:37888
	ds_read_b128 v[220:223], v154 offset:38912
	ds_read_b128 v[224:227], v154 offset:39936
	global_load_lds_dwordx4 v130, s[26:27]
	s_mov_b32 m0, s30
	s_nop 0
	global_load_lds_dwordx4 v134, s[26:27]
	s_waitcnt vmcnt(8)
	s_waitcnt lgkmcnt(0)
	s_setprio 1
	s_barrier
	v_mfma_f32_16x16x32_bf16 v[126:129], v[146:149], v[184:187], v[126:129]
	v_mfma_f32_16x16x32_bf16 v[122:125], v[160:163], v[184:187], v[122:125]
	v_mfma_f32_16x16x32_bf16 v[110:113], v[146:149], v[192:195], v[110:113]
	v_mfma_f32_16x16x32_bf16 v[106:109], v[160:163], v[192:195], v[106:109]
	v_mfma_f32_16x16x32_bf16 v[94:97], v[146:149], v[206:209], v[94:97]
	v_mfma_f32_16x16x32_bf16 v[90:93], v[160:163], v[206:209], v[90:93]
	v_mfma_f32_16x16x32_bf16 v[78:81], v[146:149], v[220:223], v[78:81]
	v_mfma_f32_16x16x32_bf16 v[74:77], v[160:163], v[220:223], v[74:77]
	v_mfma_f32_16x16x32_bf16 v[126:129], v[156:159], v[188:191], v[126:129]
	v_mfma_f32_16x16x32_bf16 v[122:125], v[164:167], v[188:191], v[122:125]
	v_mfma_f32_16x16x32_bf16 v[110:113], v[156:159], v[196:199], v[110:113]
	v_mfma_f32_16x16x32_bf16 v[106:109], v[164:167], v[196:199], v[106:109]
	v_mfma_f32_16x16x32_bf16 v[94:97], v[156:159], v[212:215], v[94:97]
	v_mfma_f32_16x16x32_bf16 v[90:93], v[164:167], v[212:215], v[90:93]
	v_mfma_f32_16x16x32_bf16 v[78:81], v[156:159], v[224:227], v[78:81]
	v_mfma_f32_16x16x32_bf16 v[74:77], v[164:167], v[224:227], v[74:77]
	s_setprio 0
	s_setprio 1
	v_mfma_f32_16x16x32_bf16 v[118:121], v[168:171], v[184:187], v[118:121]
	v_mfma_f32_16x16x32_bf16 v[114:117], v[176:179], v[184:187], v[114:117]
	v_mfma_f32_16x16x32_bf16 v[102:105], v[168:171], v[192:195], v[102:105]
	v_mfma_f32_16x16x32_bf16 v[98:101], v[176:179], v[192:195], v[98:101]
	v_mfma_f32_16x16x32_bf16 v[86:89], v[168:171], v[206:209], v[86:89]
	v_mfma_f32_16x16x32_bf16 v[82:85], v[176:179], v[206:209], v[82:85]
	v_mfma_f32_16x16x32_bf16 v[70:73], v[168:171], v[220:223], v[70:73]
	v_mfma_f32_16x16x32_bf16 v[66:69], v[176:179], v[220:223], v[66:69]
	v_mfma_f32_16x16x32_bf16 v[118:121], v[172:175], v[188:191], v[118:121]
	v_mfma_f32_16x16x32_bf16 v[114:117], v[180:183], v[188:191], v[114:117]
	v_mfma_f32_16x16x32_bf16 v[102:105], v[172:175], v[196:199], v[102:105]
	v_mfma_f32_16x16x32_bf16 v[98:101], v[180:183], v[196:199], v[98:101]
	v_mfma_f32_16x16x32_bf16 v[86:89], v[172:175], v[212:215], v[86:89]
	v_mfma_f32_16x16x32_bf16 v[82:85], v[180:183], v[212:215], v[82:85]
	v_mfma_f32_16x16x32_bf16 v[70:73], v[172:175], v[224:227], v[70:73]
	v_mfma_f32_16x16x32_bf16 v[66:69], v[180:183], v[224:227], v[66:69]
	s_barrier
	s_setprio 0
	s_add_u32 s26, s24, 0x80000
	s_addc_u32 s27, s25, 0
	s_add_i32 s44, s44, s0
	s_mov_b32 m0, s44
	ds_read_b128 v[184:187], v154 offset:49152
	ds_read_b128 v[188:191], v154 offset:50176
	ds_read_b128 v[192:195], v154 offset:51200
	ds_read_b128 v[196:199], v154 offset:52224
	ds_read_b128 v[206:209], v154 offset:53248
	ds_read_b128 v[212:215], v154 offset:54272
	ds_read_b128 v[220:223], v154 offset:55296
	ds_read_b128 v[224:227], v154 offset:56320
	global_load_lds_dwordx4 v132, s[26:27]
	s_add_i32 m0, s44, 0x2000
	s_add_u32 s24, s24, 0x84000
	s_addc_u32 s25, s25, 0
	global_load_lds_dwordx4 v136, s[26:27]
	s_add_i32 s26, s45, s0
	s_mov_b32 m0, s26
	s_nop 0
	global_load_lds_dwordx4 v132, s[24:25]
	s_add_i32 m0, s26, 0x2000
	s_nop 0
	global_load_lds_dwordx4 v136, s[24:25]
	s_mov_b32 m0, s35
	s_nop 0
	global_load_lds_dwordx4 v130, s[22:23]
	s_mov_b32 m0, s36
	s_nop 0
	global_load_lds_dwordx4 v134, s[22:23]
	s_waitcnt vmcnt(8)
	s_waitcnt lgkmcnt(0)
	s_setprio 1
	s_barrier
	v_mfma_f32_16x16x32_bf16 v[62:65], v[146:149], v[184:187], v[62:65]
	v_mfma_f32_16x16x32_bf16 v[58:61], v[160:163], v[184:187], v[58:61]
	v_mfma_f32_16x16x32_bf16 v[46:49], v[146:149], v[192:195], v[46:49]
	v_mfma_f32_16x16x32_bf16 v[42:45], v[160:163], v[192:195], v[42:45]
	v_mfma_f32_16x16x32_bf16 v[30:33], v[146:149], v[206:209], v[30:33]
	v_mfma_f32_16x16x32_bf16 v[26:29], v[160:163], v[206:209], v[26:29]
	v_mfma_f32_16x16x32_bf16 v[14:17], v[146:149], v[220:223], v[14:17]
	v_mfma_f32_16x16x32_bf16 v[10:13], v[160:163], v[220:223], v[10:13]
	v_mfma_f32_16x16x32_bf16 v[62:65], v[156:159], v[188:191], v[62:65]
	v_mfma_f32_16x16x32_bf16 v[58:61], v[164:167], v[188:191], v[58:61]
	v_mfma_f32_16x16x32_bf16 v[46:49], v[156:159], v[196:199], v[46:49]
	v_mfma_f32_16x16x32_bf16 v[42:45], v[164:167], v[196:199], v[42:45]
	v_mfma_f32_16x16x32_bf16 v[30:33], v[156:159], v[212:215], v[30:33]
	v_mfma_f32_16x16x32_bf16 v[26:29], v[164:167], v[212:215], v[26:29]
	v_mfma_f32_16x16x32_bf16 v[14:17], v[156:159], v[224:227], v[14:17]
	v_mfma_f32_16x16x32_bf16 v[10:13], v[164:167], v[224:227], v[10:13]
	s_setprio 0
	s_setprio 1
	v_mfma_f32_16x16x32_bf16 v[54:57], v[168:171], v[184:187], v[54:57]
	v_mfma_f32_16x16x32_bf16 v[50:53], v[176:179], v[184:187], v[50:53]
	v_mfma_f32_16x16x32_bf16 v[38:41], v[168:171], v[192:195], v[38:41]
	v_mfma_f32_16x16x32_bf16 v[34:37], v[176:179], v[192:195], v[34:37]
	v_mfma_f32_16x16x32_bf16 v[22:25], v[168:171], v[206:209], v[22:25]
	v_mfma_f32_16x16x32_bf16 v[18:21], v[176:179], v[206:209], v[18:21]
	v_mfma_f32_16x16x32_bf16 v[6:9], v[168:171], v[220:223], v[6:9]
	v_mfma_f32_16x16x32_bf16 v[2:5], v[176:179], v[220:223], v[2:5]
	v_mfma_f32_16x16x32_bf16 v[54:57], v[172:175], v[188:191], v[54:57]
	v_mfma_f32_16x16x32_bf16 v[50:53], v[180:183], v[188:191], v[50:53]
	v_mfma_f32_16x16x32_bf16 v[38:41], v[172:175], v[196:199], v[38:41]
	v_mfma_f32_16x16x32_bf16 v[34:37], v[180:183], v[196:199], v[34:37]
	v_mfma_f32_16x16x32_bf16 v[22:25], v[172:175], v[212:215], v[22:25]
	v_mfma_f32_16x16x32_bf16 v[18:21], v[180:183], v[212:215], v[18:21]
	v_mfma_f32_16x16x32_bf16 v[6:9], v[172:175], v[224:227], v[6:9]
	v_mfma_f32_16x16x32_bf16 v[2:5], v[180:183], v[224:227], v[2:5]
	s_barrier
	s_setprio 0
	s_add_i32 s43, s43, 2
	s_add_u32 s41, s41, 0x100000
	s_addc_u32 s42, s42, 0
	s_add_u32 s20, s20, 0x200000
	s_addc_u32 s21, s21, 0
	s_cmp_gt_u32 s43, 61
	s_cbranch_scc0 .LBB0_1217
	s_and_b64 vcc, exec, s[8:9]
	s_cbranch_vccz .LBB0_1220
	s_barrier

.LBB0_1670:
	ds_read_b128 v[148:151], v143
	ds_read_b128 v[152:155], v143 offset:1024
	ds_read_b128 v[156:159], v143 offset:2048
	ds_read_b128 v[160:163], v143 offset:3072
	ds_read_b128 v[164:167], v144
	ds_read_b128 v[168:171], v144 offset:1024
	ds_read_b128 v[172:175], v144 offset:2048
	ds_read_b128 v[176:179], v144 offset:3072
	s_add_u32 s10, s6, 0x4000
	s_addc_u32 s11, s7, 0
	s_cmp_eq_u32 s28, 60
	s_cselect_b32 s18, s14, s10
	s_cselect_b32 s19, s15, s11
	s_cselect_b32 s16, s4, s26
	s_cselect_b32 s17, s5, s27
	s_add_u32 s10, s18, 0x8000
	s_addc_u32 s11, s19, 0
	s_mov_b32 m0, s29
	ds_read_b128 v[180:183], v145
	ds_read_b128 v[184:187], v145 offset:1024
	ds_read_b128 v[188:191], v145 offset:2048
	ds_read_b128 v[192:195], v145 offset:3072
	ds_read_b128 v[196:199], v145 offset:4096
	ds_read_b128 v[206:209], v145 offset:5120
	ds_read_b128 v[212:215], v145 offset:6144
	ds_read_b128 v[220:223], v145 offset:7168
	global_load_lds_dwordx4 v138, s[6:7]
	s_mov_b32 m0, s30
	s_nop 0
	global_load_lds_dwordx4 v140, s[6:7]
	s_waitcnt vmcnt(8)
	s_waitcnt lgkmcnt(0)
	s_setprio 1
	s_barrier
	v_mfma_f32_16x16x32_bf16 v[126:129], v[148:151], v[180:183], v[126:129]
	v_mfma_f32_16x16x32_bf16 v[122:125], v[156:159], v[180:183], v[122:125]
	v_mfma_f32_16x16x32_bf16 v[118:121], v[148:151], v[188:191], v[118:121]
	v_mfma_f32_16x16x32_bf16 v[110:113], v[156:159], v[188:191], v[110:113]
	v_mfma_f32_16x16x32_bf16 v[102:105], v[148:151], v[196:199], v[102:105]
	v_mfma_f32_16x16x32_bf16 v[94:97], v[156:159], v[196:199], v[94:97]
	v_mfma_f32_16x16x32_bf16 v[86:89], v[148:151], v[212:215], v[86:89]
	v_mfma_f32_16x16x32_bf16 v[78:81], v[156:159], v[212:215], v[78:81]
	v_mfma_f32_16x16x32_bf16 v[126:129], v[152:155], v[184:187], v[126:129]
	v_mfma_f32_16x16x32_bf16 v[122:125], v[160:163], v[184:187], v[122:125]
	v_mfma_f32_16x16x32_bf16 v[118:121], v[152:155], v[192:195], v[118:121]
	v_mfma_f32_16x16x32_bf16 v[110:113], v[160:163], v[192:195], v[110:113]
	v_mfma_f32_16x16x32_bf16 v[102:105], v[152:155], v[206:209], v[102:105]
	v_mfma_f32_16x16x32_bf16 v[94:97], v[160:163], v[206:209], v[94:97]
	v_mfma_f32_16x16x32_bf16 v[86:89], v[152:155], v[220:223], v[86:89]
	v_mfma_f32_16x16x32_bf16 v[78:81], v[160:163], v[220:223], v[78:81]
	s_setprio 0
	s_setprio 1
	v_mfma_f32_16x16x32_bf16 v[114:117], v[164:167], v[180:183], v[114:117]
	v_mfma_f32_16x16x32_bf16 v[106:109], v[172:175], v[180:183], v[106:109]
	v_mfma_f32_16x16x32_bf16 v[98:101], v[164:167], v[188:191], v[98:101]
	v_mfma_f32_16x16x32_bf16 v[90:93], v[172:175], v[188:191], v[90:93]
	v_mfma_f32_16x16x32_bf16 v[82:85], v[164:167], v[196:199], v[82:85]
	v_mfma_f32_16x16x32_bf16 v[74:77], v[172:175], v[196:199], v[74:77]
	v_mfma_f32_16x16x32_bf16 v[70:73], v[164:167], v[212:215], v[70:73]
	v_mfma_f32_16x16x32_bf16 v[66:69], v[172:175], v[212:215], v[66:69]
	v_mfma_f32_16x16x32_bf16 v[114:117], v[168:171], v[184:187], v[114:117]
	v_mfma_f32_16x16x32_bf16 v[106:109], v[176:179], v[184:187], v[106:109]
	v_mfma_f32_16x16x32_bf16 v[98:101], v[168:171], v[192:195], v[98:101]
	v_mfma_f32_16x16x32_bf16 v[90:93], v[176:179], v[192:195], v[90:93]
	v_mfma_f32_16x16x32_bf16 v[82:85], v[168:171], v[206:209], v[82:85]
	v_mfma_f32_16x16x32_bf16 v[74:77], v[176:179], v[206:209], v[74:77]
	v_mfma_f32_16x16x32_bf16 v[70:73], v[168:171], v[220:223], v[70:73]
	v_mfma_f32_16x16x32_bf16 v[66:69], v[176:179], v[220:223], v[66:69]
	s_barrier
	s_setprio 0
	s_mov_b32 m0, s31
	s_add_u32 s40, s16, 0x4000
	ds_read_b128 v[180:183], v145 offset:16384
	ds_read_b128 v[184:187], v145 offset:17408
	ds_read_b128 v[188:191], v145 offset:18432
	ds_read_b128 v[192:195], v145 offset:19456
	ds_read_b128 v[196:199], v145 offset:20480
	ds_read_b128 v[206:209], v145 offset:21504
	ds_read_b128 v[212:215], v145 offset:22528
	ds_read_b128 v[220:223], v145 offset:23552
	global_load_lds_dwordx4 v134, s[16:17]
	s_mov_b32 m0, s33
	s_addc_u32 s41, s17, 0
	global_load_lds_dwordx4 v130, s[16:17]
	s_mov_b32 m0, s34
	s_nop 0
	global_load_lds_dwordx4 v134, s[40:41]
	s_mov_b32 m0, s35
	s_nop 0
	global_load_lds_dwordx4 v130, s[40:41]
	s_mov_b32 m0, s1
	s_nop 0
	global_load_lds_dwordx4 v136, s[18:19]
	s_mov_b32 m0, s3
	s_nop 0
	global_load_lds_dwordx4 v132, s[18:19]
	s_waitcnt vmcnt(8)
	s_waitcnt lgkmcnt(0)
	s_setprio 1
	s_barrier
	v_mfma_f32_16x16x32_bf16 v[62:65], v[148:151], v[180:183], v[62:65]
	v_mfma_f32_16x16x32_bf16 v[58:61], v[156:159], v[180:183], v[58:61]
	v_mfma_f32_16x16x32_bf16 v[54:57], v[148:151], v[188:191], v[54:57]
	v_mfma_f32_16x16x32_bf16 v[46:49], v[156:159], v[188:191], v[46:49]
	v_mfma_f32_16x16x32_bf16 v[38:41], v[148:151], v[196:199], v[38:41]
	v_mfma_f32_16x16x32_bf16 v[30:33], v[156:159], v[196:199], v[30:33]
	v_mfma_f32_16x16x32_bf16 v[22:25], v[148:151], v[212:215], v[22:25]
	v_mfma_f32_16x16x32_bf16 v[14:17], v[156:159], v[212:215], v[14:17]
	v_mfma_f32_16x16x32_bf16 v[62:65], v[152:155], v[184:187], v[62:65]
	v_mfma_f32_16x16x32_bf16 v[58:61], v[160:163], v[184:187], v[58:61]
	v_mfma_f32_16x16x32_bf16 v[54:57], v[152:155], v[192:195], v[54:57]
	v_mfma_f32_16x16x32_bf16 v[46:49], v[160:163], v[192:195], v[46:49]
	v_mfma_f32_16x16x32_bf16 v[38:41], v[152:155], v[206:209], v[38:41]
	v_mfma_f32_16x16x32_bf16 v[30:33], v[160:163], v[206:209], v[30:33]
	v_mfma_f32_16x16x32_bf16 v[22:25], v[152:155], v[220:223], v[22:25]
	v_mfma_f32_16x16x32_bf16 v[14:17], v[160:163], v[220:223], v[14:17]
	s_setprio 0
	s_setprio 1
	v_mfma_f32_16x16x32_bf16 v[50:53], v[164:167], v[180:183], v[50:53]
	v_mfma_f32_16x16x32_bf16 v[42:45], v[172:175], v[180:183], v[42:45]
	v_mfma_f32_16x16x32_bf16 v[34:37], v[164:167], v[188:191], v[34:37]
	v_mfma_f32_16x16x32_bf16 v[26:29], v[172:175], v[188:191], v[26:29]
	v_mfma_f32_16x16x32_bf16 v[18:21], v[164:167], v[196:199], v[18:21]
	v_mfma_f32_16x16x32_bf16 v[10:13], v[172:175], v[196:199], v[10:13]
	v_mfma_f32_16x16x32_bf16 v[6:9], v[164:167], v[212:215], v[6:9]
	v_mfma_f32_16x16x32_bf16 v[2:5], v[172:175], v[212:215], v[2:5]
	v_mfma_f32_16x16x32_bf16 v[50:53], v[168:171], v[184:187], v[50:53]
	v_mfma_f32_16x16x32_bf16 v[42:45], v[176:179], v[184:187], v[42:45]
	v_mfma_f32_16x16x32_bf16 v[34:37], v[168:171], v[192:195], v[34:37]
	v_mfma_f32_16x16x32_bf16 v[26:29], v[176:179], v[192:195], v[26:29]
	v_mfma_f32_16x16x32_bf16 v[18:21], v[168:171], v[206:209], v[18:21]
	v_mfma_f32_16x16x32_bf16 v[10:13], v[176:179], v[206:209], v[10:13]
	v_mfma_f32_16x16x32_bf16 v[6:9], v[168:171], v[220:223], v[6:9]
	v_mfma_f32_16x16x32_bf16 v[2:5], v[176:179], v[220:223], v[2:5]
	s_barrier
	s_setprio 0
	ds_read_b128 v[148:151], v146
	ds_read_b128 v[152:155], v146 offset:1024
	ds_read_b128 v[156:159], v146 offset:2048
	ds_read_b128 v[160:163], v146 offset:3072
	ds_read_b128 v[164:167], v147
	ds_read_b128 v[168:171], v147 offset:1024
	ds_read_b128 v[172:175], v147 offset:2048
	ds_read_b128 v[176:179], v147 offset:3072
	s_add_u32 s18, s18, 0x4000
	s_addc_u32 s19, s19, 0
	s_mov_b32 m0, s20
	ds_read_b128 v[180:183], v145 offset:32768
	ds_read_b128 v[184:187], v145 offset:33792
	ds_read_b128 v[188:191], v145 offset:34816
	ds_read_b128 v[192:195], v145 offset:35840
	ds_read_b128 v[196:199], v145 offset:36864
	ds_read_b128 v[206:209], v145 offset:37888
	ds_read_b128 v[212:215], v145 offset:38912
	ds_read_b128 v[220:223], v145 offset:39936
	global_load_lds_dwordx4 v136, s[18:19]
	s_mov_b32 m0, s21
	s_nop 0
	global_load_lds_dwordx4 v132, s[18:19]
	s_waitcnt vmcnt(8)
	s_waitcnt lgkmcnt(0)
	s_setprio 1
	s_barrier
	v_mfma_f32_16x16x32_bf16 v[126:129], v[148:151], v[180:183], v[126:129]
	v_mfma_f32_16x16x32_bf16 v[122:125], v[156:159], v[180:183], v[122:125]
	v_mfma_f32_16x16x32_bf16 v[118:121], v[148:151], v[188:191], v[118:121]
	v_mfma_f32_16x16x32_bf16 v[110:113], v[156:159], v[188:191], v[110:113]
	v_mfma_f32_16x16x32_bf16 v[102:105], v[148:151], v[196:199], v[102:105]
	v_mfma_f32_16x16x32_bf16 v[94:97], v[156:159], v[196:199], v[94:97]
	v_mfma_f32_16x16x32_bf16 v[86:89], v[148:151], v[212:215], v[86:89]
	v_mfma_f32_16x16x32_bf16 v[78:81], v[156:159], v[212:215], v[78:81]
	v_mfma_f32_16x16x32_bf16 v[126:129], v[152:155], v[184:187], v[126:129]
	v_mfma_f32_16x16x32_bf16 v[122:125], v[160:163], v[184:187], v[122:125]
	v_mfma_f32_16x16x32_bf16 v[118:121], v[152:155], v[192:195], v[118:121]
	v_mfma_f32_16x16x32_bf16 v[110:113], v[160:163], v[192:195], v[110:113]
	v_mfma_f32_16x16x32_bf16 v[102:105], v[152:155], v[206:209], v[102:105]
	v_mfma_f32_16x16x32_bf16 v[94:97], v[160:163], v[206:209], v[94:97]
	v_mfma_f32_16x16x32_bf16 v[86:89], v[152:155], v[220:223], v[86:89]
	v_mfma_f32_16x16x32_bf16 v[78:81], v[160:163], v[220:223], v[78:81]
	s_setprio 0
	s_setprio 1
	v_mfma_f32_16x16x32_bf16 v[114:117], v[164:167], v[180:183], v[114:117]
	v_mfma_f32_16x16x32_bf16 v[106:109], v[172:175], v[180:183], v[106:109]
	v_mfma_f32_16x16x32_bf16 v[98:101], v[164:167], v[188:191], v[98:101]
	v_mfma_f32_16x16x32_bf16 v[90:93], v[172:175], v[188:191], v[90:93]
	v_mfma_f32_16x16x32_bf16 v[82:85], v[164:167], v[196:199], v[82:85]
	v_mfma_f32_16x16x32_bf16 v[74:77], v[172:175], v[196:199], v[74:77]
	v_mfma_f32_16x16x32_bf16 v[70:73], v[164:167], v[212:215], v[70:73]
	v_mfma_f32_16x16x32_bf16 v[66:69], v[172:175], v[212:215], v[66:69]
	v_mfma_f32_16x16x32_bf16 v[114:117], v[168:171], v[184:187], v[114:117]
	v_mfma_f32_16x16x32_bf16 v[106:109], v[176:179], v[184:187], v[106:109]
	v_mfma_f32_16x16x32_bf16 v[98:101], v[168:171], v[192:195], v[98:101]
	v_mfma_f32_16x16x32_bf16 v[90:93], v[176:179], v[192:195], v[90:93]
	v_mfma_f32_16x16x32_bf16 v[82:85], v[168:171], v[206:209], v[82:85]
	v_mfma_f32_16x16x32_bf16 v[74:77], v[176:179], v[206:209], v[74:77]
	v_mfma_f32_16x16x32_bf16 v[70:73], v[168:171], v[220:223], v[70:73]
	v_mfma_f32_16x16x32_bf16 v[66:69], v[176:179], v[220:223], v[66:69]
	s_barrier
	s_setprio 0
	s_add_u32 s18, s16, 0x20000
	s_addc_u32 s19, s17, 0
	s_mov_b32 m0, s36
	s_add_u32 s16, s16, 0x24000
	ds_read_b128 v[180:183], v145 offset:49152
	ds_read_b128 v[184:187], v145 offset:50176
	ds_read_b128 v[188:191], v145 offset:51200
	ds_read_b128 v[192:195], v145 offset:52224
	ds_read_b128 v[196:199], v145 offset:53248
	ds_read_b128 v[206:209], v145 offset:54272
	ds_read_b128 v[212:215], v145 offset:55296
	ds_read_b128 v[220:223], v145 offset:56320
	global_load_lds_dwordx4 v134, s[18:19]
	s_mov_b32 m0, s37
	s_addc_u32 s17, s17, 0
	global_load_lds_dwordx4 v130, s[18:19]
	s_mov_b32 m0, s38
	s_nop 0
	global_load_lds_dwordx4 v134, s[16:17]
	s_mov_b32 m0, s39
	s_nop 0
	global_load_lds_dwordx4 v130, s[16:17]
	s_mov_b32 m0, s24
	s_nop 0
	global_load_lds_dwordx4 v136, s[10:11]
	s_mov_b32 m0, s25
	s_nop 0
	global_load_lds_dwordx4 v132, s[10:11]
	s_waitcnt vmcnt(8)
	s_waitcnt lgkmcnt(0)
	s_setprio 1
	s_barrier
	v_mfma_f32_16x16x32_bf16 v[62:65], v[148:151], v[180:183], v[62:65]
	v_mfma_f32_16x16x32_bf16 v[58:61], v[156:159], v[180:183], v[58:61]
	v_mfma_f32_16x16x32_bf16 v[54:57], v[148:151], v[188:191], v[54:57]
	v_mfma_f32_16x16x32_bf16 v[46:49], v[156:159], v[188:191], v[46:49]
	v_mfma_f32_16x16x32_bf16 v[38:41], v[148:151], v[196:199], v[38:41]
	v_mfma_f32_16x16x32_bf16 v[30:33], v[156:159], v[196:199], v[30:33]
	v_mfma_f32_16x16x32_bf16 v[22:25], v[148:151], v[212:215], v[22:25]
	v_mfma_f32_16x16x32_bf16 v[14:17], v[156:159], v[212:215], v[14:17]
	v_mfma_f32_16x16x32_bf16 v[62:65], v[152:155], v[184:187], v[62:65]
	v_mfma_f32_16x16x32_bf16 v[58:61], v[160:163], v[184:187], v[58:61]
	v_mfma_f32_16x16x32_bf16 v[54:57], v[152:155], v[192:195], v[54:57]
	v_mfma_f32_16x16x32_bf16 v[46:49], v[160:163], v[192:195], v[46:49]
	v_mfma_f32_16x16x32_bf16 v[38:41], v[152:155], v[206:209], v[38:41]
	v_mfma_f32_16x16x32_bf16 v[30:33], v[160:163], v[206:209], v[30:33]
	v_mfma_f32_16x16x32_bf16 v[22:25], v[152:155], v[220:223], v[22:25]
	v_mfma_f32_16x16x32_bf16 v[14:17], v[160:163], v[220:223], v[14:17]
	s_setprio 0
	s_setprio 1
	v_mfma_f32_16x16x32_bf16 v[50:53], v[164:167], v[180:183], v[50:53]
	v_mfma_f32_16x16x32_bf16 v[42:45], v[172:175], v[180:183], v[42:45]
	v_mfma_f32_16x16x32_bf16 v[34:37], v[164:167], v[188:191], v[34:37]
	v_mfma_f32_16x16x32_bf16 v[26:29], v[172:175], v[188:191], v[26:29]
	v_mfma_f32_16x16x32_bf16 v[18:21], v[164:167], v[196:199], v[18:21]
	v_mfma_f32_16x16x32_bf16 v[10:13], v[172:175], v[196:199], v[10:13]
	v_mfma_f32_16x16x32_bf16 v[6:9], v[164:167], v[212:215], v[6:9]
	v_mfma_f32_16x16x32_bf16 v[2:5], v[172:175], v[212:215], v[2:5]
	v_mfma_f32_16x16x32_bf16 v[50:53], v[168:171], v[184:187], v[50:53]
	v_mfma_f32_16x16x32_bf16 v[42:45], v[176:179], v[184:187], v[42:45]
	v_mfma_f32_16x16x32_bf16 v[34:37], v[168:171], v[192:195], v[34:37]
	v_mfma_f32_16x16x32_bf16 v[26:29], v[176:179], v[192:195], v[26:29]
	v_mfma_f32_16x16x32_bf16 v[18:21], v[168:171], v[206:209], v[18:21]
	v_mfma_f32_16x16x32_bf16 v[10:13], v[176:179], v[206:209], v[10:13]
	v_mfma_f32_16x16x32_bf16 v[6:9], v[168:171], v[220:223], v[6:9]
	v_mfma_f32_16x16x32_bf16 v[2:5], v[176:179], v[220:223], v[2:5]
	s_barrier
	s_setprio 0
	s_add_i32 s28, s28, 2
	s_add_u32 s26, s26, 0x40000
	s_addc_u32 s27, s27, 0
	s_add_u32 s6, s6, 0x10000
	s_addc_u32 s7, s7, 0
	s_cmp_gt_u32 s28, 61
	s_cbranch_scc0 .LBB0_1670
	s_lshl_b32 s1, s2, 8
	v_and_or_b32 v132, v142, 15, s22
	v_lshrrev_b32_e32 v130, 1, v142
	v_and_or_b32 v130, v130, 24, s1
	v_ashrrev_i32_e32 v133, 31, v132
	v_or_b32_e32 v134, s23, v130
	v_lshlrev_b64 v[130:131], 11, v[132:133]
	v_lshl_add_u64 v[130:131], s[8:9], 0, v[130:131]
	v_lshlrev_b32_e32 v134, 1, v134
	v_mov_b32_e32 v135, 0
	v_lshl_add_u64 v[130:131], v[130:131], 0, v[134:135]
	v_cvt_pk_bf16_f32 v126, v126, v127
	v_cvt_pk_bf16_f32 v127, v128, v129
	v_cvt_pk_bf16_f32 v128, v122, v123
	v_cvt_pk_bf16_f32 v129, v124, v125
	global_store_dwordx4 v[130:131], v[126:129], off
	v_cvt_pk_bf16_f32 v114, v114, v115
	v_cvt_pk_bf16_f32 v115, v116, v117
	v_cvt_pk_bf16_f32 v116, v106, v107
	v_or_b32_e32 v106, 16, v132
	v_ashrrev_i32_e32 v107, 31, v106
	v_lshlrev_b64 v[106:107], 11, v[106:107]
	v_lshl_add_u64 v[106:107], s[8:9], 0, v[106:107]
	v_cvt_pk_bf16_f32 v117, v108, v109
	global_store_dwordx4 v[130:131], v[114:117], off offset:256
	s_mov_b32 s1, 0x40000
	s_mov_b64 s[2:3], 0x40000
	v_lshl_add_u64 v[114:115], v[106:107], 0, v[134:135]
	v_cvt_pk_bf16_f32 v106, v118, v119
	v_cvt_pk_bf16_f32 v107, v120, v121
	v_cvt_pk_bf16_f32 v108, v110, v111
	v_cvt_pk_bf16_f32 v109, v112, v113
	global_store_dwordx4 v[114:115], v[106:109], off
	v_cvt_pk_bf16_f32 v98, v98, v99
	v_cvt_pk_bf16_f32 v99, v100, v101
	v_cvt_pk_bf16_f32 v100, v90, v91
	v_or_b32_e32 v90, 32, v132
	v_ashrrev_i32_e32 v91, 31, v90
	v_lshlrev_b64 v[90:91], 11, v[90:91]
	v_lshl_add_u64 v[90:91], s[8:9], 0, v[90:91]
	v_cvt_pk_bf16_f32 v101, v92, v93
	global_store_dwordx4 v[114:115], v[98:101], off offset:256
	s_cmpk_lt_u32 s0, 0x100
	s_nop 0
	v_lshl_add_u64 v[98:99], v[90:91], 0, v[134:135]
	v_cvt_pk_bf16_f32 v90, v102, v103
	v_cvt_pk_bf16_f32 v91, v104, v105
	v_cvt_pk_bf16_f32 v92, v94, v95
	v_cvt_pk_bf16_f32 v93, v96, v97
	global_store_dwordx4 v[98:99], v[90:93], off
	v_cvt_pk_bf16_f32 v82, v82, v83
	v_cvt_pk_bf16_f32 v83, v84, v85
	v_cvt_pk_bf16_f32 v84, v74, v75
	v_or_b32_e32 v74, 48, v132
	v_ashrrev_i32_e32 v75, 31, v74
	v_lshlrev_b64 v[74:75], 11, v[74:75]
	v_lshl_add_u64 v[74:75], s[8:9], 0, v[74:75]
	v_cvt_pk_bf16_f32 v85, v76, v77
	global_store_dwordx4 v[98:99], v[82:85], off offset:256
	s_nop 1
	v_lshl_add_u64 v[82:83], v[74:75], 0, v[134:135]
	v_cvt_pk_bf16_f32 v74, v86, v87
	v_cvt_pk_bf16_f32 v75, v88, v89
	v_cvt_pk_bf16_f32 v76, v78, v79
	v_cvt_pk_bf16_f32 v77, v80, v81
	global_store_dwordx4 v[82:83], v[74:77], off
	v_cvt_pk_bf16_f32 v70, v70, v71
	v_cvt_pk_bf16_f32 v71, v72, v73
	v_cvt_pk_bf16_f32 v72, v66, v67
	v_cvt_pk_bf16_f32 v73, v68, v69
	global_store_dwordx4 v[82:83], v[70:73], off offset:256
	v_cvt_pk_bf16_f32 v62, v62, v63
	v_cvt_pk_bf16_f32 v63, v64, v65
	v_cvt_pk_bf16_f32 v64, v58, v59
	v_add_co_u32_e32 v58, vcc, s1, v130
	v_lshl_add_u64 v[66:67], v[130:131], 0, s[2:3]
	s_nop 0
	v_addc_co_u32_e32 v59, vcc, 0, v131, vcc
	s_mov_b32 s1, 0x48000
	v_cvt_pk_bf16_f32 v65, v60, v61
	global_store_dwordx4 v[58:59], v[62:65], off
	v_cvt_pk_bf16_f32 v50, v50, v51
	v_cvt_pk_bf16_f32 v51, v52, v53
	v_cvt_pk_bf16_f32 v52, v42, v43
	v_cvt_pk_bf16_f32 v53, v44, v45
	global_store_dwordx4 v[66:67], v[50:53], off offset:256
	s_mov_b64 s[2:3], 0x48000
	v_cvt_pk_bf16_f32 v42, v54, v55
	v_cvt_pk_bf16_f32 v43, v56, v57
	v_cvt_pk_bf16_f32 v44, v46, v47
	v_add_co_u32_e32 v46, vcc, s1, v130
	v_lshl_add_u64 v[50:51], v[130:131], 0, s[2:3]
	s_nop 0
	v_addc_co_u32_e32 v47, vcc, 0, v131, vcc
	s_mov_b32 s1, 0x50000
	v_cvt_pk_bf16_f32 v45, v48, v49
	global_store_dwordx4 v[46:47], v[42:45], off
	v_cvt_pk_bf16_f32 v34, v34, v35
	v_cvt_pk_bf16_f32 v35, v36, v37
	v_cvt_pk_bf16_f32 v36, v26, v27
	v_cvt_pk_bf16_f32 v37, v28, v29
	global_store_dwordx4 v[50:51], v[34:37], off offset:256
	s_mov_b64 s[2:3], 0x50000
	v_cvt_pk_bf16_f32 v26, v38, v39
	v_cvt_pk_bf16_f32 v27, v40, v41
	v_cvt_pk_bf16_f32 v28, v30, v31
	v_add_co_u32_e32 v30, vcc, s1, v130
	v_lshl_add_u64 v[34:35], v[130:131], 0, s[2:3]
	s_nop 0
	v_addc_co_u32_e32 v31, vcc, 0, v131, vcc
	s_mov_b32 s1, 0x58000
	v_cvt_pk_bf16_f32 v29, v32, v33
	global_store_dwordx4 v[30:31], v[26:29], off
	v_cvt_pk_bf16_f32 v18, v18, v19
	v_cvt_pk_bf16_f32 v19, v20, v21
	v_cvt_pk_bf16_f32 v20, v10, v11
	v_cvt_pk_bf16_f32 v21, v12, v13
	global_store_dwordx4 v[34:35], v[18:21], off offset:256
	s_mov_b64 s[2:3], 0x58000
	v_cvt_pk_bf16_f32 v10, v22, v23
	v_cvt_pk_bf16_f32 v11, v24, v25
	v_cvt_pk_bf16_f32 v12, v14, v15
	v_add_co_u32_e32 v14, vcc, s1, v130
	v_lshl_add_u64 v[18:19], v[130:131], 0, s[2:3]
	s_nop 0
	v_addc_co_u32_e32 v15, vcc, 0, v131, vcc
	v_cvt_pk_bf16_f32 v13, v16, v17
	global_store_dwordx4 v[14:15], v[10:13], off
	v_cvt_pk_bf16_f32 v6, v6, v7
	v_cvt_pk_bf16_f32 v7, v8, v9
	v_cvt_pk_bf16_f32 v8, v2, v3
	v_cvt_pk_bf16_f32 v9, v4, v5
	global_store_dwordx4 v[18:19], v[6:9], off offset:256
	s_waitcnt vmcnt(0)
	s_cbranch_scc0 .LBB0_1673
	s_barrier

.LBB0_1691:
	ds_read_b128 v[142:145], v150
	ds_read_b128 v[154:157], v150 offset:1024
	ds_read_b128 v[158:161], v150 offset:2048
	ds_read_b128 v[162:165], v150 offset:3072
	ds_read_b128 v[166:169], v151
	ds_read_b128 v[170:173], v151 offset:1024
	ds_read_b128 v[174:177], v151 offset:2048
	ds_read_b128 v[178:181], v151 offset:3072
	s_add_u32 s24, s22, 0xfc000
	s_addc_u32 s25, s23, 0
	s_cmp_eq_u32 s46, 60
	s_cselect_b32 s28, s17, s24
	s_cselect_b32 s29, s11, s25
	s_cselect_b32 s26, s43, s44
	s_cselect_b32 s27, s7, s45
	s_add_u32 s24, s28, 0x100000
	s_addc_u32 s25, s29, 0
	s_add_i32 m0, s30, 0xc000
	ds_read_b128 v[182:185], v152
	ds_read_b128 v[186:189], v152 offset:1024
	ds_read_b128 v[190:193], v152 offset:2048
	ds_read_b128 v[194:197], v152 offset:3072
	ds_read_b128 v[206:209], v152 offset:4096
	ds_read_b128 v[212:215], v152 offset:5120
	ds_read_b128 v[220:223], v152 offset:6144
	ds_read_b128 v[224:227], v152 offset:7168
	global_load_lds_dwordx4 v138, s[22:23]
	s_add_i32 m0, s30, 0xe000
	s_nop 0
	global_load_lds_dwordx4 v140, s[22:23]
	s_waitcnt vmcnt(8)
	s_waitcnt lgkmcnt(0)
	s_setprio 1
	s_barrier
	v_mfma_f32_16x16x32_bf16 v[126:129], v[142:145], v[182:185], v[126:129]
	v_mfma_f32_16x16x32_bf16 v[122:125], v[158:161], v[182:185], v[122:125]
	v_mfma_f32_16x16x32_bf16 v[110:113], v[142:145], v[190:193], v[110:113]
	v_mfma_f32_16x16x32_bf16 v[106:109], v[158:161], v[190:193], v[106:109]
	v_mfma_f32_16x16x32_bf16 v[94:97], v[142:145], v[206:209], v[94:97]
	v_mfma_f32_16x16x32_bf16 v[90:93], v[158:161], v[206:209], v[90:93]
	v_mfma_f32_16x16x32_bf16 v[78:81], v[142:145], v[220:223], v[78:81]
	v_mfma_f32_16x16x32_bf16 v[74:77], v[158:161], v[220:223], v[74:77]
	v_mfma_f32_16x16x32_bf16 v[126:129], v[154:157], v[186:189], v[126:129]
	v_mfma_f32_16x16x32_bf16 v[122:125], v[162:165], v[186:189], v[122:125]
	v_mfma_f32_16x16x32_bf16 v[110:113], v[154:157], v[194:197], v[110:113]
	v_mfma_f32_16x16x32_bf16 v[106:109], v[162:165], v[194:197], v[106:109]
	v_mfma_f32_16x16x32_bf16 v[94:97], v[154:157], v[212:215], v[94:97]
	v_mfma_f32_16x16x32_bf16 v[90:93], v[162:165], v[212:215], v[90:93]
	v_mfma_f32_16x16x32_bf16 v[78:81], v[154:157], v[224:227], v[78:81]
	v_mfma_f32_16x16x32_bf16 v[74:77], v[162:165], v[224:227], v[74:77]
	s_setprio 0
	s_setprio 1
	v_mfma_f32_16x16x32_bf16 v[118:121], v[166:169], v[182:185], v[118:121]
	v_mfma_f32_16x16x32_bf16 v[114:117], v[174:177], v[182:185], v[114:117]
	v_mfma_f32_16x16x32_bf16 v[102:105], v[166:169], v[190:193], v[102:105]
	v_mfma_f32_16x16x32_bf16 v[98:101], v[174:177], v[190:193], v[98:101]
	v_mfma_f32_16x16x32_bf16 v[86:89], v[166:169], v[206:209], v[86:89]
	v_mfma_f32_16x16x32_bf16 v[82:85], v[174:177], v[206:209], v[82:85]
	v_mfma_f32_16x16x32_bf16 v[70:73], v[166:169], v[220:223], v[70:73]
	v_mfma_f32_16x16x32_bf16 v[66:69], v[174:177], v[220:223], v[66:69]
	v_mfma_f32_16x16x32_bf16 v[118:121], v[170:173], v[186:189], v[118:121]
	v_mfma_f32_16x16x32_bf16 v[114:117], v[178:181], v[186:189], v[114:117]
	v_mfma_f32_16x16x32_bf16 v[102:105], v[170:173], v[194:197], v[102:105]
	v_mfma_f32_16x16x32_bf16 v[98:101], v[178:181], v[194:197], v[98:101]
	v_mfma_f32_16x16x32_bf16 v[86:89], v[170:173], v[212:215], v[86:89]
	v_mfma_f32_16x16x32_bf16 v[82:85], v[178:181], v[212:215], v[82:85]
	v_mfma_f32_16x16x32_bf16 v[70:73], v[170:173], v[224:227], v[70:73]
	v_mfma_f32_16x16x32_bf16 v[66:69], v[178:181], v[224:227], v[66:69]
	s_barrier
	s_setprio 0
	s_add_i32 s47, s40, s1
	s_mov_b32 m0, s47
	ds_read_b128 v[182:185], v152 offset:16384
	ds_read_b128 v[186:189], v152 offset:17408
	ds_read_b128 v[190:193], v152 offset:18432
	ds_read_b128 v[194:197], v152 offset:19456
	ds_read_b128 v[206:209], v152 offset:20480
	ds_read_b128 v[212:215], v152 offset:21504
	ds_read_b128 v[220:223], v152 offset:22528
	ds_read_b128 v[224:227], v152 offset:23552
	global_load_lds_dwordx4 v132, s[26:27]
	s_add_i32 m0, s47, 0x2000
	s_add_u32 s48, s26, 0x4000
	s_addc_u32 s49, s27, 0
	s_add_i32 s47, s41, s1
	global_load_lds_dwordx4 v136, s[26:27]
	s_mov_b32 m0, s47
	s_nop 0
	global_load_lds_dwordx4 v132, s[48:49]
	s_add_i32 m0, s47, 0x2000
	s_nop 0
	global_load_lds_dwordx4 v136, s[48:49]
	s_mov_b32 m0, s30
	s_nop 0
	global_load_lds_dwordx4 v130, s[28:29]
	s_mov_b32 m0, s31
	s_nop 0
	global_load_lds_dwordx4 v134, s[28:29]
	s_waitcnt vmcnt(8)
	s_waitcnt lgkmcnt(0)
	s_setprio 1
	s_barrier
	v_mfma_f32_16x16x32_bf16 v[62:65], v[142:145], v[182:185], v[62:65]
	v_mfma_f32_16x16x32_bf16 v[58:61], v[158:161], v[182:185], v[58:61]
	v_mfma_f32_16x16x32_bf16 v[46:49], v[142:145], v[190:193], v[46:49]
	v_mfma_f32_16x16x32_bf16 v[42:45], v[158:161], v[190:193], v[42:45]
	v_mfma_f32_16x16x32_bf16 v[30:33], v[142:145], v[206:209], v[30:33]
	v_mfma_f32_16x16x32_bf16 v[26:29], v[158:161], v[206:209], v[26:29]
	v_mfma_f32_16x16x32_bf16 v[14:17], v[142:145], v[220:223], v[14:17]
	v_mfma_f32_16x16x32_bf16 v[10:13], v[158:161], v[220:223], v[10:13]
	v_mfma_f32_16x16x32_bf16 v[62:65], v[154:157], v[186:189], v[62:65]
	v_mfma_f32_16x16x32_bf16 v[58:61], v[162:165], v[186:189], v[58:61]
	v_mfma_f32_16x16x32_bf16 v[46:49], v[154:157], v[194:197], v[46:49]
	v_mfma_f32_16x16x32_bf16 v[42:45], v[162:165], v[194:197], v[42:45]
	v_mfma_f32_16x16x32_bf16 v[30:33], v[154:157], v[212:215], v[30:33]
	v_mfma_f32_16x16x32_bf16 v[26:29], v[162:165], v[212:215], v[26:29]
	v_mfma_f32_16x16x32_bf16 v[14:17], v[154:157], v[224:227], v[14:17]
	v_mfma_f32_16x16x32_bf16 v[10:13], v[162:165], v[224:227], v[10:13]
	s_setprio 0
	s_setprio 1
	v_mfma_f32_16x16x32_bf16 v[54:57], v[166:169], v[182:185], v[54:57]
	v_mfma_f32_16x16x32_bf16 v[50:53], v[174:177], v[182:185], v[50:53]
	v_mfma_f32_16x16x32_bf16 v[38:41], v[166:169], v[190:193], v[38:41]
	v_mfma_f32_16x16x32_bf16 v[34:37], v[174:177], v[190:193], v[34:37]
	v_mfma_f32_16x16x32_bf16 v[22:25], v[166:169], v[206:209], v[22:25]
	v_mfma_f32_16x16x32_bf16 v[18:21], v[174:177], v[206:209], v[18:21]
	v_mfma_f32_16x16x32_bf16 v[6:9], v[166:169], v[220:223], v[6:9]
	v_mfma_f32_16x16x32_bf16 v[2:5], v[174:177], v[220:223], v[2:5]
	v_mfma_f32_16x16x32_bf16 v[54:57], v[170:173], v[186:189], v[54:57]
	v_mfma_f32_16x16x32_bf16 v[50:53], v[178:181], v[186:189], v[50:53]
	v_mfma_f32_16x16x32_bf16 v[38:41], v[170:173], v[194:197], v[38:41]
	v_mfma_f32_16x16x32_bf16 v[34:37], v[178:181], v[194:197], v[34:37]
	v_mfma_f32_16x16x32_bf16 v[22:25], v[170:173], v[212:215], v[22:25]
	v_mfma_f32_16x16x32_bf16 v[18:21], v[178:181], v[212:215], v[18:21]
	v_mfma_f32_16x16x32_bf16 v[6:9], v[170:173], v[224:227], v[6:9]
	v_mfma_f32_16x16x32_bf16 v[2:5], v[178:181], v[224:227], v[2:5]
	s_barrier
	s_setprio 0
	s_add_i32 s47, 0, 0x18000
	v_add_u32_e32 v146, s47, v149
	s_add_i32 s48, 0, 0x1c000
	ds_read_b128 v[142:145], v146
	ds_read_b128 v[154:157], v146 offset:1024
	ds_read_b128 v[158:161], v146 offset:2048
	ds_read_b128 v[162:165], v146 offset:3072
	v_add_u32_e32 v146, s48, v149
	ds_read_b128 v[166:169], v146
	ds_read_b128 v[170:173], v146 offset:1024
	ds_read_b128 v[174:177], v146 offset:2048
	ds_read_b128 v[178:181], v146 offset:3072
	s_add_u32 s28, s28, 0x4000
	s_addc_u32 s29, s29, 0
	s_mov_b32 m0, s33
	ds_read_b128 v[182:185], v152 offset:32768
	ds_read_b128 v[186:189], v152 offset:33792
	ds_read_b128 v[190:193], v152 offset:34816
	ds_read_b128 v[194:197], v152 offset:35840
	ds_read_b128 v[206:209], v152 offset:36864
	ds_read_b128 v[212:215], v152 offset:37888
	ds_read_b128 v[220:223], v152 offset:38912
	ds_read_b128 v[224:227], v152 offset:39936
	global_load_lds_dwordx4 v130, s[28:29]
	s_mov_b32 m0, s34
	s_nop 0
	global_load_lds_dwordx4 v134, s[28:29]
	s_waitcnt vmcnt(8)
	s_waitcnt lgkmcnt(0)
	s_setprio 1
	s_barrier
	v_mfma_f32_16x16x32_bf16 v[126:129], v[142:145], v[182:185], v[126:129]
	v_mfma_f32_16x16x32_bf16 v[122:125], v[158:161], v[182:185], v[122:125]
	v_mfma_f32_16x16x32_bf16 v[110:113], v[142:145], v[190:193], v[110:113]
	v_mfma_f32_16x16x32_bf16 v[106:109], v[158:161], v[190:193], v[106:109]
	v_mfma_f32_16x16x32_bf16 v[94:97], v[142:145], v[206:209], v[94:97]
	v_mfma_f32_16x16x32_bf16 v[90:93], v[158:161], v[206:209], v[90:93]
	v_mfma_f32_16x16x32_bf16 v[78:81], v[142:145], v[220:223], v[78:81]
	v_mfma_f32_16x16x32_bf16 v[74:77], v[158:161], v[220:223], v[74:77]
	v_mfma_f32_16x16x32_bf16 v[126:129], v[154:157], v[186:189], v[126:129]
	v_mfma_f32_16x16x32_bf16 v[122:125], v[162:165], v[186:189], v[122:125]
	v_mfma_f32_16x16x32_bf16 v[110:113], v[154:157], v[194:197], v[110:113]
	v_mfma_f32_16x16x32_bf16 v[106:109], v[162:165], v[194:197], v[106:109]
	v_mfma_f32_16x16x32_bf16 v[94:97], v[154:157], v[212:215], v[94:97]
	v_mfma_f32_16x16x32_bf16 v[90:93], v[162:165], v[212:215], v[90:93]
	v_mfma_f32_16x16x32_bf16 v[78:81], v[154:157], v[224:227], v[78:81]
	v_mfma_f32_16x16x32_bf16 v[74:77], v[162:165], v[224:227], v[74:77]
	s_setprio 0
	s_setprio 1
	v_mfma_f32_16x16x32_bf16 v[118:121], v[166:169], v[182:185], v[118:121]
	v_mfma_f32_16x16x32_bf16 v[114:117], v[174:177], v[182:185], v[114:117]
	v_mfma_f32_16x16x32_bf16 v[102:105], v[166:169], v[190:193], v[102:105]
	v_mfma_f32_16x16x32_bf16 v[98:101], v[174:177], v[190:193], v[98:101]
	v_mfma_f32_16x16x32_bf16 v[86:89], v[166:169], v[206:209], v[86:89]
	v_mfma_f32_16x16x32_bf16 v[82:85], v[174:177], v[206:209], v[82:85]
	v_mfma_f32_16x16x32_bf16 v[70:73], v[166:169], v[220:223], v[70:73]
	v_mfma_f32_16x16x32_bf16 v[66:69], v[174:177], v[220:223], v[66:69]
	v_mfma_f32_16x16x32_bf16 v[118:121], v[170:173], v[186:189], v[118:121]
	v_mfma_f32_16x16x32_bf16 v[114:117], v[178:181], v[186:189], v[114:117]
	v_mfma_f32_16x16x32_bf16 v[102:105], v[170:173], v[194:197], v[102:105]
	v_mfma_f32_16x16x32_bf16 v[98:101], v[178:181], v[194:197], v[98:101]
	v_mfma_f32_16x16x32_bf16 v[86:89], v[170:173], v[212:215], v[86:89]
	v_mfma_f32_16x16x32_bf16 v[82:85], v[178:181], v[212:215], v[82:85]
	v_mfma_f32_16x16x32_bf16 v[70:73], v[170:173], v[224:227], v[70:73]
	v_mfma_f32_16x16x32_bf16 v[66:69], v[178:181], v[224:227], v[66:69]
	s_barrier
	s_setprio 0
	s_add_u32 s28, s26, 0x10000
	s_addc_u32 s29, s27, 0
	s_add_i32 s47, s47, s1
	s_mov_b32 m0, s47
	ds_read_b128 v[182:185], v152 offset:49152
	ds_read_b128 v[186:189], v152 offset:50176
	ds_read_b128 v[190:193], v152 offset:51200
	ds_read_b128 v[194:197], v152 offset:52224
	ds_read_b128 v[206:209], v152 offset:53248
	ds_read_b128 v[212:215], v152 offset:54272
	ds_read_b128 v[220:223], v152 offset:55296
	ds_read_b128 v[224:227], v152 offset:56320
	global_load_lds_dwordx4 v132, s[28:29]
	s_add_i32 m0, s47, 0x2000
	s_add_u32 s26, s26, 0x14000
	s_addc_u32 s27, s27, 0
	global_load_lds_dwordx4 v136, s[28:29]
	s_add_i32 s28, s48, s1
	s_mov_b32 m0, s28
	s_nop 0
	global_load_lds_dwordx4 v132, s[26:27]
	s_add_i32 m0, s28, 0x2000
	s_nop 0
	global_load_lds_dwordx4 v136, s[26:27]
	s_mov_b32 m0, s38
	s_nop 0
	global_load_lds_dwordx4 v130, s[24:25]
	s_mov_b32 m0, s39
	s_nop 0
	global_load_lds_dwordx4 v134, s[24:25]
	s_waitcnt vmcnt(8)
	s_waitcnt lgkmcnt(0)
	s_setprio 1
	s_barrier
	v_mfma_f32_16x16x32_bf16 v[62:65], v[142:145], v[182:185], v[62:65]
	v_mfma_f32_16x16x32_bf16 v[58:61], v[158:161], v[182:185], v[58:61]
	v_mfma_f32_16x16x32_bf16 v[46:49], v[142:145], v[190:193], v[46:49]
	v_mfma_f32_16x16x32_bf16 v[42:45], v[158:161], v[190:193], v[42:45]
	v_mfma_f32_16x16x32_bf16 v[30:33], v[142:145], v[206:209], v[30:33]
	v_mfma_f32_16x16x32_bf16 v[26:29], v[158:161], v[206:209], v[26:29]
	v_mfma_f32_16x16x32_bf16 v[14:17], v[142:145], v[220:223], v[14:17]
	v_mfma_f32_16x16x32_bf16 v[10:13], v[158:161], v[220:223], v[10:13]
	v_mfma_f32_16x16x32_bf16 v[62:65], v[154:157], v[186:189], v[62:65]
	v_mfma_f32_16x16x32_bf16 v[58:61], v[162:165], v[186:189], v[58:61]
	v_mfma_f32_16x16x32_bf16 v[46:49], v[154:157], v[194:197], v[46:49]
	v_mfma_f32_16x16x32_bf16 v[42:45], v[162:165], v[194:197], v[42:45]
	v_mfma_f32_16x16x32_bf16 v[30:33], v[154:157], v[212:215], v[30:33]
	v_mfma_f32_16x16x32_bf16 v[26:29], v[162:165], v[212:215], v[26:29]
	v_mfma_f32_16x16x32_bf16 v[14:17], v[154:157], v[224:227], v[14:17]
	v_mfma_f32_16x16x32_bf16 v[10:13], v[162:165], v[224:227], v[10:13]
	s_setprio 0
	s_setprio 1
	v_mfma_f32_16x16x32_bf16 v[54:57], v[166:169], v[182:185], v[54:57]
	v_mfma_f32_16x16x32_bf16 v[50:53], v[174:177], v[182:185], v[50:53]
	v_mfma_f32_16x16x32_bf16 v[38:41], v[166:169], v[190:193], v[38:41]
	v_mfma_f32_16x16x32_bf16 v[34:37], v[174:177], v[190:193], v[34:37]
	v_mfma_f32_16x16x32_bf16 v[22:25], v[166:169], v[206:209], v[22:25]
	v_mfma_f32_16x16x32_bf16 v[18:21], v[174:177], v[206:209], v[18:21]
	v_mfma_f32_16x16x32_bf16 v[6:9], v[166:169], v[220:223], v[6:9]
	v_mfma_f32_16x16x32_bf16 v[2:5], v[174:177], v[220:223], v[2:5]
	v_mfma_f32_16x16x32_bf16 v[54:57], v[170:173], v[186:189], v[54:57]
	v_mfma_f32_16x16x32_bf16 v[50:53], v[178:181], v[186:189], v[50:53]
	v_mfma_f32_16x16x32_bf16 v[38:41], v[170:173], v[194:197], v[38:41]
	v_mfma_f32_16x16x32_bf16 v[34:37], v[178:181], v[194:197], v[34:37]
	v_mfma_f32_16x16x32_bf16 v[22:25], v[170:173], v[212:215], v[22:25]
	v_mfma_f32_16x16x32_bf16 v[18:21], v[178:181], v[212:215], v[18:21]
	v_mfma_f32_16x16x32_bf16 v[6:9], v[170:173], v[224:227], v[6:9]
	v_mfma_f32_16x16x32_bf16 v[2:5], v[178:181], v[224:227], v[2:5]
	s_barrier
	s_setprio 0
	s_add_i32 s46, s46, 2
	s_add_u32 s44, s44, 0x20000
	s_addc_u32 s45, s45, 0
	s_add_u32 s22, s22, 0x200000
	s_addc_u32 s23, s23, 0
	s_cmp_gt_u32 s46, 61
	s_cbranch_scc0 .LBB0_1691
	s_lshl_b32 s7, s10, 8
	v_mov_b32_e32 v144, v147
	s_add_i32 s7, s7, s36
	v_cndmask_b32_e64 v145, 0, 1, s[2:3]
	v_and_or_b32 v142, v144, 15, s7
	v_ashrrev_i32_e32 v143, 31, v142
	v_mov_b32_e32 v146, 0x3e0293ee
	v_cmp_ne_u32_e64 s[10:11], 1, v145
	s_andn2_b64 vcc, exec, s[2:3]
	v_mov_b32_e32 v148, 0x3e0293ee
	s_cbranch_vccnz .LBB0_1694
	v_readlane_b32 s22, v245, 16
	v_readlane_b32 s23, v245, 17
	s_nop 1
	v_lshl_add_u64 v[154:155], v[142:143], 2, s[22:23]
	global_load_dword v145, v[154:155], off
	s_waitcnt vmcnt(0)
	v_mul_f32_e32 v148, 0x3e0293ee, v145

.LBB0_1718:
	ds_read_b128 v[152:155], v147
	ds_read_b128 v[156:159], v147 offset:1024
	ds_read_b128 v[160:163], v147 offset:2048
	ds_read_b128 v[164:167], v147 offset:3072
	ds_read_b128 v[168:171], v148
	ds_read_b128 v[172:175], v148 offset:1024
	ds_read_b128 v[176:179], v148 offset:2048
	ds_read_b128 v[180:183], v148 offset:3072
	s_add_u32 s18, s16, 0x4000
	s_addc_u32 s19, s17, 0
	s_cmp_eq_u32 s50, 60
	s_cselect_b32 s22, s14, s18
	s_cselect_b32 s23, s15, s19
	s_cselect_b32 s20, s47, s48
	s_cselect_b32 s21, s46, s49
	s_add_u32 s18, s22, 0x8000
	s_addc_u32 s19, s23, 0
	s_mov_b32 m0, s31
	ds_read_b128 v[184:187], v149
	ds_read_b128 v[188:191], v149 offset:1024
	ds_read_b128 v[192:195], v149 offset:2048
	ds_read_b128 v[196:199], v149 offset:3072
	ds_read_b128 v[206:209], v149 offset:4096
	ds_read_b128 v[212:215], v149 offset:5120
	ds_read_b128 v[220:223], v149 offset:6144
	ds_read_b128 v[224:227], v149 offset:7168
	global_load_lds_dwordx4 v140, s[16:17]
	s_mov_b32 m0, s33
	s_nop 0
	global_load_lds_dwordx4 v142, s[16:17]
	s_waitcnt vmcnt(8)
	s_waitcnt lgkmcnt(0)
	s_setprio 1
	s_barrier
	v_mfma_f32_16x16x32_bf16 v[126:129], v[152:155], v[184:187], v[126:129]
	v_mfma_f32_16x16x32_bf16 v[122:125], v[160:163], v[184:187], v[122:125]
	v_mfma_f32_16x16x32_bf16 v[118:121], v[152:155], v[192:195], v[118:121]
	v_mfma_f32_16x16x32_bf16 v[110:113], v[160:163], v[192:195], v[110:113]
	v_mfma_f32_16x16x32_bf16 v[102:105], v[152:155], v[206:209], v[102:105]
	v_mfma_f32_16x16x32_bf16 v[94:97], v[160:163], v[206:209], v[94:97]
	v_mfma_f32_16x16x32_bf16 v[86:89], v[152:155], v[220:223], v[86:89]
	v_mfma_f32_16x16x32_bf16 v[78:81], v[160:163], v[220:223], v[78:81]
	v_mfma_f32_16x16x32_bf16 v[126:129], v[156:159], v[188:191], v[126:129]
	v_mfma_f32_16x16x32_bf16 v[122:125], v[164:167], v[188:191], v[122:125]
	v_mfma_f32_16x16x32_bf16 v[118:121], v[156:159], v[196:199], v[118:121]
	v_mfma_f32_16x16x32_bf16 v[110:113], v[164:167], v[196:199], v[110:113]
	v_mfma_f32_16x16x32_bf16 v[102:105], v[156:159], v[212:215], v[102:105]
	v_mfma_f32_16x16x32_bf16 v[94:97], v[164:167], v[212:215], v[94:97]
	v_mfma_f32_16x16x32_bf16 v[86:89], v[156:159], v[224:227], v[86:89]
	v_mfma_f32_16x16x32_bf16 v[78:81], v[164:167], v[224:227], v[78:81]
	s_setprio 0
	s_setprio 1
	v_mfma_f32_16x16x32_bf16 v[114:117], v[168:171], v[184:187], v[114:117]
	v_mfma_f32_16x16x32_bf16 v[106:109], v[176:179], v[184:187], v[106:109]
	v_mfma_f32_16x16x32_bf16 v[98:101], v[168:171], v[192:195], v[98:101]
	v_mfma_f32_16x16x32_bf16 v[90:93], v[176:179], v[192:195], v[90:93]
	v_mfma_f32_16x16x32_bf16 v[82:85], v[168:171], v[206:209], v[82:85]
	v_mfma_f32_16x16x32_bf16 v[74:77], v[176:179], v[206:209], v[74:77]
	v_mfma_f32_16x16x32_bf16 v[70:73], v[168:171], v[220:223], v[70:73]
	v_mfma_f32_16x16x32_bf16 v[66:69], v[176:179], v[220:223], v[66:69]
	v_mfma_f32_16x16x32_bf16 v[114:117], v[172:175], v[188:191], v[114:117]
	v_mfma_f32_16x16x32_bf16 v[106:109], v[180:183], v[188:191], v[106:109]
	v_mfma_f32_16x16x32_bf16 v[98:101], v[172:175], v[196:199], v[98:101]
	v_mfma_f32_16x16x32_bf16 v[90:93], v[180:183], v[196:199], v[90:93]
	v_mfma_f32_16x16x32_bf16 v[82:85], v[172:175], v[212:215], v[82:85]
	v_mfma_f32_16x16x32_bf16 v[74:77], v[180:183], v[212:215], v[74:77]
	v_mfma_f32_16x16x32_bf16 v[70:73], v[172:175], v[224:227], v[70:73]
	v_mfma_f32_16x16x32_bf16 v[66:69], v[180:183], v[224:227], v[66:69]
	s_barrier
	s_setprio 0
	s_mov_b32 m0, s36
	s_add_u32 s52, s20, 0x4000
	ds_read_b128 v[184:187], v149 offset:16384
	ds_read_b128 v[188:191], v149 offset:17408
	ds_read_b128 v[192:195], v149 offset:18432
	ds_read_b128 v[196:199], v149 offset:19456
	ds_read_b128 v[206:209], v149 offset:20480
	ds_read_b128 v[212:215], v149 offset:21504
	ds_read_b128 v[220:223], v149 offset:22528
	ds_read_b128 v[224:227], v149 offset:23552
	global_load_lds_dwordx4 v134, s[20:21]
	s_mov_b32 m0, s37
	s_addc_u32 s53, s21, 0
	global_load_lds_dwordx4 v130, s[20:21]
	s_mov_b32 m0, s38
	s_nop 0
	global_load_lds_dwordx4 v134, s[52:53]
	s_mov_b32 m0, s39
	s_nop 0
	global_load_lds_dwordx4 v130, s[52:53]
	s_mov_b32 m0, s1
	s_nop 0
	global_load_lds_dwordx4 v136, s[22:23]
	s_mov_b32 m0, s24
	s_nop 0
	global_load_lds_dwordx4 v132, s[22:23]
	s_waitcnt vmcnt(8)
	s_waitcnt lgkmcnt(0)
	s_setprio 1
	s_barrier
	v_mfma_f32_16x16x32_bf16 v[62:65], v[152:155], v[184:187], v[62:65]
	v_mfma_f32_16x16x32_bf16 v[58:61], v[160:163], v[184:187], v[58:61]
	v_mfma_f32_16x16x32_bf16 v[54:57], v[152:155], v[192:195], v[54:57]
	v_mfma_f32_16x16x32_bf16 v[46:49], v[160:163], v[192:195], v[46:49]
	v_mfma_f32_16x16x32_bf16 v[38:41], v[152:155], v[206:209], v[38:41]
	v_mfma_f32_16x16x32_bf16 v[30:33], v[160:163], v[206:209], v[30:33]
	v_mfma_f32_16x16x32_bf16 v[22:25], v[152:155], v[220:223], v[22:25]
	v_mfma_f32_16x16x32_bf16 v[14:17], v[160:163], v[220:223], v[14:17]
	v_mfma_f32_16x16x32_bf16 v[62:65], v[156:159], v[188:191], v[62:65]
	v_mfma_f32_16x16x32_bf16 v[58:61], v[164:167], v[188:191], v[58:61]
	v_mfma_f32_16x16x32_bf16 v[54:57], v[156:159], v[196:199], v[54:57]
	v_mfma_f32_16x16x32_bf16 v[46:49], v[164:167], v[196:199], v[46:49]
	v_mfma_f32_16x16x32_bf16 v[38:41], v[156:159], v[212:215], v[38:41]
	v_mfma_f32_16x16x32_bf16 v[30:33], v[164:167], v[212:215], v[30:33]
	v_mfma_f32_16x16x32_bf16 v[22:25], v[156:159], v[224:227], v[22:25]
	v_mfma_f32_16x16x32_bf16 v[14:17], v[164:167], v[224:227], v[14:17]
	s_setprio 0
	s_setprio 1
	v_mfma_f32_16x16x32_bf16 v[50:53], v[168:171], v[184:187], v[50:53]
	v_mfma_f32_16x16x32_bf16 v[42:45], v[176:179], v[184:187], v[42:45]
	v_mfma_f32_16x16x32_bf16 v[34:37], v[168:171], v[192:195], v[34:37]
	v_mfma_f32_16x16x32_bf16 v[26:29], v[176:179], v[192:195], v[26:29]
	v_mfma_f32_16x16x32_bf16 v[18:21], v[168:171], v[206:209], v[18:21]
	v_mfma_f32_16x16x32_bf16 v[10:13], v[176:179], v[206:209], v[10:13]
	v_mfma_f32_16x16x32_bf16 v[6:9], v[168:171], v[220:223], v[6:9]
	v_mfma_f32_16x16x32_bf16 v[2:5], v[176:179], v[220:223], v[2:5]
	v_mfma_f32_16x16x32_bf16 v[50:53], v[172:175], v[188:191], v[50:53]
	v_mfma_f32_16x16x32_bf16 v[42:45], v[180:183], v[188:191], v[42:45]
	v_mfma_f32_16x16x32_bf16 v[34:37], v[172:175], v[196:199], v[34:37]
	v_mfma_f32_16x16x32_bf16 v[26:29], v[180:183], v[196:199], v[26:29]
	v_mfma_f32_16x16x32_bf16 v[18:21], v[172:175], v[212:215], v[18:21]
	v_mfma_f32_16x16x32_bf16 v[10:13], v[180:183], v[212:215], v[10:13]
	v_mfma_f32_16x16x32_bf16 v[6:9], v[172:175], v[224:227], v[6:9]
	v_mfma_f32_16x16x32_bf16 v[2:5], v[180:183], v[224:227], v[2:5]
	s_barrier
	s_setprio 0
	ds_read_b128 v[152:155], v150
	ds_read_b128 v[156:159], v150 offset:1024
	ds_read_b128 v[160:163], v150 offset:2048
	ds_read_b128 v[164:167], v150 offset:3072
	ds_read_b128 v[168:171], v151
	ds_read_b128 v[172:175], v151 offset:1024
	ds_read_b128 v[176:179], v151 offset:2048
	ds_read_b128 v[180:183], v151 offset:3072
	s_add_u32 s22, s22, 0x4000
	s_addc_u32 s23, s23, 0
	s_mov_b32 m0, s25
	ds_read_b128 v[184:187], v149 offset:32768
	ds_read_b128 v[188:191], v149 offset:33792
	ds_read_b128 v[192:195], v149 offset:34816
	ds_read_b128 v[196:199], v149 offset:35840
	ds_read_b128 v[206:209], v149 offset:36864
	ds_read_b128 v[212:215], v149 offset:37888
	ds_read_b128 v[220:223], v149 offset:38912
	ds_read_b128 v[224:227], v149 offset:39936
	global_load_lds_dwordx4 v136, s[22:23]
	s_mov_b32 m0, s26
	s_nop 0
	global_load_lds_dwordx4 v132, s[22:23]
	s_waitcnt vmcnt(8)
	s_waitcnt lgkmcnt(0)
	s_setprio 1
	s_barrier
	v_mfma_f32_16x16x32_bf16 v[126:129], v[152:155], v[184:187], v[126:129]
	v_mfma_f32_16x16x32_bf16 v[122:125], v[160:163], v[184:187], v[122:125]
	v_mfma_f32_16x16x32_bf16 v[118:121], v[152:155], v[192:195], v[118:121]
	v_mfma_f32_16x16x32_bf16 v[110:113], v[160:163], v[192:195], v[110:113]
	v_mfma_f32_16x16x32_bf16 v[102:105], v[152:155], v[206:209], v[102:105]
	v_mfma_f32_16x16x32_bf16 v[94:97], v[160:163], v[206:209], v[94:97]
	v_mfma_f32_16x16x32_bf16 v[86:89], v[152:155], v[220:223], v[86:89]
	v_mfma_f32_16x16x32_bf16 v[78:81], v[160:163], v[220:223], v[78:81]
	v_mfma_f32_16x16x32_bf16 v[126:129], v[156:159], v[188:191], v[126:129]
	v_mfma_f32_16x16x32_bf16 v[122:125], v[164:167], v[188:191], v[122:125]
	v_mfma_f32_16x16x32_bf16 v[118:121], v[156:159], v[196:199], v[118:121]
	v_mfma_f32_16x16x32_bf16 v[110:113], v[164:167], v[196:199], v[110:113]
	v_mfma_f32_16x16x32_bf16 v[102:105], v[156:159], v[212:215], v[102:105]
	v_mfma_f32_16x16x32_bf16 v[94:97], v[164:167], v[212:215], v[94:97]
	v_mfma_f32_16x16x32_bf16 v[86:89], v[156:159], v[224:227], v[86:89]
	v_mfma_f32_16x16x32_bf16 v[78:81], v[164:167], v[224:227], v[78:81]
	s_setprio 0
	s_setprio 1
	v_mfma_f32_16x16x32_bf16 v[114:117], v[168:171], v[184:187], v[114:117]
	v_mfma_f32_16x16x32_bf16 v[106:109], v[176:179], v[184:187], v[106:109]
	v_mfma_f32_16x16x32_bf16 v[98:101], v[168:171], v[192:195], v[98:101]
	v_mfma_f32_16x16x32_bf16 v[90:93], v[176:179], v[192:195], v[90:93]
	v_mfma_f32_16x16x32_bf16 v[82:85], v[168:171], v[206:209], v[82:85]
	v_mfma_f32_16x16x32_bf16 v[74:77], v[176:179], v[206:209], v[74:77]
	v_mfma_f32_16x16x32_bf16 v[70:73], v[168:171], v[220:223], v[70:73]
	v_mfma_f32_16x16x32_bf16 v[66:69], v[176:179], v[220:223], v[66:69]
	v_mfma_f32_16x16x32_bf16 v[114:117], v[172:175], v[188:191], v[114:117]
	v_mfma_f32_16x16x32_bf16 v[106:109], v[180:183], v[188:191], v[106:109]
	v_mfma_f32_16x16x32_bf16 v[98:101], v[172:175], v[196:199], v[98:101]
	v_mfma_f32_16x16x32_bf16 v[90:93], v[180:183], v[196:199], v[90:93]
	v_mfma_f32_16x16x32_bf16 v[82:85], v[172:175], v[212:215], v[82:85]
	v_mfma_f32_16x16x32_bf16 v[74:77], v[180:183], v[212:215], v[74:77]
	v_mfma_f32_16x16x32_bf16 v[70:73], v[172:175], v[224:227], v[70:73]
	v_mfma_f32_16x16x32_bf16 v[66:69], v[180:183], v[224:227], v[66:69]
	s_barrier
	s_setprio 0
	s_add_u32 s22, s20, 0x20000
	s_addc_u32 s23, s21, 0
	s_mov_b32 m0, s40
	s_add_u32 s20, s20, 0x24000
	ds_read_b128 v[184:187], v149 offset:49152
	ds_read_b128 v[188:191], v149 offset:50176
	ds_read_b128 v[192:195], v149 offset:51200
	ds_read_b128 v[196:199], v149 offset:52224
	ds_read_b128 v[206:209], v149 offset:53248
	ds_read_b128 v[212:215], v149 offset:54272
	ds_read_b128 v[220:223], v149 offset:55296
	ds_read_b128 v[224:227], v149 offset:56320
	global_load_lds_dwordx4 v134, s[22:23]
	s_mov_b32 m0, s41
	s_addc_u32 s21, s21, 0
	global_load_lds_dwordx4 v130, s[22:23]
	s_mov_b32 m0, s42
	s_nop 0
	global_load_lds_dwordx4 v134, s[20:21]
	s_mov_b32 m0, s43
	s_nop 0
	global_load_lds_dwordx4 v130, s[20:21]
	s_mov_b32 m0, s29
	s_nop 0
	global_load_lds_dwordx4 v136, s[18:19]
	s_mov_b32 m0, s30
	s_nop 0
	global_load_lds_dwordx4 v132, s[18:19]
	s_waitcnt vmcnt(8)
	s_waitcnt lgkmcnt(0)
	s_setprio 1
	s_barrier
	v_mfma_f32_16x16x32_bf16 v[62:65], v[152:155], v[184:187], v[62:65]
	v_mfma_f32_16x16x32_bf16 v[58:61], v[160:163], v[184:187], v[58:61]
	v_mfma_f32_16x16x32_bf16 v[54:57], v[152:155], v[192:195], v[54:57]
	v_mfma_f32_16x16x32_bf16 v[46:49], v[160:163], v[192:195], v[46:49]
	v_mfma_f32_16x16x32_bf16 v[38:41], v[152:155], v[206:209], v[38:41]
	v_mfma_f32_16x16x32_bf16 v[30:33], v[160:163], v[206:209], v[30:33]
	v_mfma_f32_16x16x32_bf16 v[22:25], v[152:155], v[220:223], v[22:25]
	v_mfma_f32_16x16x32_bf16 v[14:17], v[160:163], v[220:223], v[14:17]
	v_mfma_f32_16x16x32_bf16 v[62:65], v[156:159], v[188:191], v[62:65]
	v_mfma_f32_16x16x32_bf16 v[58:61], v[164:167], v[188:191], v[58:61]
	v_mfma_f32_16x16x32_bf16 v[54:57], v[156:159], v[196:199], v[54:57]
	v_mfma_f32_16x16x32_bf16 v[46:49], v[164:167], v[196:199], v[46:49]
	v_mfma_f32_16x16x32_bf16 v[38:41], v[156:159], v[212:215], v[38:41]
	v_mfma_f32_16x16x32_bf16 v[30:33], v[164:167], v[212:215], v[30:33]
	v_mfma_f32_16x16x32_bf16 v[22:25], v[156:159], v[224:227], v[22:25]
	v_mfma_f32_16x16x32_bf16 v[14:17], v[164:167], v[224:227], v[14:17]
	s_setprio 0
	s_setprio 1
	v_mfma_f32_16x16x32_bf16 v[50:53], v[168:171], v[184:187], v[50:53]
	v_mfma_f32_16x16x32_bf16 v[42:45], v[176:179], v[184:187], v[42:45]
	v_mfma_f32_16x16x32_bf16 v[34:37], v[168:171], v[192:195], v[34:37]
	v_mfma_f32_16x16x32_bf16 v[26:29], v[176:179], v[192:195], v[26:29]
	v_mfma_f32_16x16x32_bf16 v[18:21], v[168:171], v[206:209], v[18:21]
	v_mfma_f32_16x16x32_bf16 v[10:13], v[176:179], v[206:209], v[10:13]
	v_mfma_f32_16x16x32_bf16 v[6:9], v[168:171], v[220:223], v[6:9]
	v_mfma_f32_16x16x32_bf16 v[2:5], v[176:179], v[220:223], v[2:5]
	v_mfma_f32_16x16x32_bf16 v[50:53], v[172:175], v[188:191], v[50:53]
	v_mfma_f32_16x16x32_bf16 v[42:45], v[180:183], v[188:191], v[42:45]
	v_mfma_f32_16x16x32_bf16 v[34:37], v[172:175], v[196:199], v[34:37]
	v_mfma_f32_16x16x32_bf16 v[26:29], v[180:183], v[196:199], v[26:29]
	v_mfma_f32_16x16x32_bf16 v[18:21], v[172:175], v[212:215], v[18:21]
	v_mfma_f32_16x16x32_bf16 v[10:13], v[180:183], v[212:215], v[10:13]
	v_mfma_f32_16x16x32_bf16 v[6:9], v[172:175], v[224:227], v[6:9]
	v_mfma_f32_16x16x32_bf16 v[2:5], v[180:183], v[224:227], v[2:5]
	s_barrier
	s_setprio 0
	s_add_i32 s50, s50, 2
	s_add_u32 s48, s48, 0x40000
	s_addc_u32 s49, s49, 0
	s_add_u32 s16, s16, 0x10000
	s_addc_u32 s17, s17, 0
	s_cmp_gt_u32 s50, 61
	s_cbranch_scc0 .LBB0_1718
	v_mov_b32_e32 v138, v146
	s_lshl_b32 s16, s45, 8
	v_and_or_b32 v152, v138, 15, s27
	v_lshrrev_b32_e32 v138, 1, v138
	v_and_or_b32 v138, v138, 24, s16
	v_ashrrev_i32_e32 v153, 31, v152
	v_or_b32_e32 v138, s28, v138
	v_lshlrev_b64 v[144:145], 11, v[152:153]
	v_lshl_add_u64 v[144:145], s[8:9], 0, v[144:145]
	v_lshlrev_b64 v[154:155], 1, v[138:139]
	v_lshl_add_u64 v[144:145], v[144:145], 0, v[154:155]
	v_cvt_pk_bf16_f32 v126, v126, v127
	v_cvt_pk_bf16_f32 v127, v128, v129
	v_cvt_pk_bf16_f32 v128, v122, v123
	v_cvt_pk_bf16_f32 v129, v124, v125
	global_store_dwordx4 v[144:145], v[126:129], off
	v_cvt_pk_bf16_f32 v114, v114, v115
	v_cvt_pk_bf16_f32 v115, v116, v117
	v_cvt_pk_bf16_f32 v116, v106, v107
	v_or_b32_e32 v106, 16, v152
	v_ashrrev_i32_e32 v107, 31, v106
	v_lshlrev_b64 v[106:107], 11, v[106:107]
	v_lshl_add_u64 v[106:107], s[8:9], 0, v[106:107]
	v_cvt_pk_bf16_f32 v117, v108, v109
	global_store_dwordx4 v[144:145], v[114:117], off offset:256
	s_mov_b64 s[16:17], 0x40000
	s_cmp_eq_u32 s44, 4
	v_lshl_add_u64 v[114:115], v[106:107], 0, v[154:155]
	v_cvt_pk_bf16_f32 v106, v118, v119
	v_cvt_pk_bf16_f32 v107, v120, v121
	v_cvt_pk_bf16_f32 v108, v110, v111
	v_cvt_pk_bf16_f32 v109, v112, v113
	global_store_dwordx4 v[114:115], v[106:109], off
	v_cvt_pk_bf16_f32 v98, v98, v99
	v_cvt_pk_bf16_f32 v99, v100, v101
	v_cvt_pk_bf16_f32 v100, v90, v91
	v_or_b32_e32 v90, 32, v152
	v_ashrrev_i32_e32 v91, 31, v90
	v_lshlrev_b64 v[90:91], 11, v[90:91]
	v_lshl_add_u64 v[90:91], s[8:9], 0, v[90:91]
	v_cvt_pk_bf16_f32 v101, v92, v93
	global_store_dwordx4 v[114:115], v[98:101], off offset:256
	s_mov_b32 s45, s44
	s_nop 0
	v_lshl_add_u64 v[98:99], v[90:91], 0, v[154:155]
	v_cvt_pk_bf16_f32 v90, v102, v103
	v_cvt_pk_bf16_f32 v91, v104, v105
	v_cvt_pk_bf16_f32 v92, v94, v95
	v_cvt_pk_bf16_f32 v93, v96, v97
	global_store_dwordx4 v[98:99], v[90:93], off
	v_cvt_pk_bf16_f32 v82, v82, v83
	v_cvt_pk_bf16_f32 v83, v84, v85
	v_cvt_pk_bf16_f32 v84, v74, v75
	v_or_b32_e32 v74, 48, v152
	v_ashrrev_i32_e32 v75, 31, v74
	v_lshlrev_b64 v[74:75], 11, v[74:75]
	v_lshl_add_u64 v[74:75], s[8:9], 0, v[74:75]
	v_cvt_pk_bf16_f32 v85, v76, v77
	global_store_dwordx4 v[98:99], v[82:85], off offset:256
	s_nop 1
	v_lshl_add_u64 v[82:83], v[74:75], 0, v[154:155]
	v_cvt_pk_bf16_f32 v74, v86, v87
	v_cvt_pk_bf16_f32 v75, v88, v89
	v_cvt_pk_bf16_f32 v76, v78, v79
	v_cvt_pk_bf16_f32 v77, v80, v81
	global_store_dwordx4 v[82:83], v[74:77], off
	v_cvt_pk_bf16_f32 v70, v70, v71
	v_cvt_pk_bf16_f32 v71, v72, v73
	v_cvt_pk_bf16_f32 v72, v66, v67
	v_lshl_add_u64 v[66:67], v[144:145], 0, s[16:17]
	s_mov_b32 s16, 0x40000
	v_cvt_pk_bf16_f32 v73, v68, v69
	global_store_dwordx4 v[82:83], v[70:73], off offset:256
	v_cvt_pk_bf16_f32 v62, v62, v63
	v_cvt_pk_bf16_f32 v63, v64, v65
	v_cvt_pk_bf16_f32 v64, v58, v59
	v_add_co_u32_e32 v58, vcc, s16, v144
	v_cvt_pk_bf16_f32 v65, v60, v61
	s_mov_b64 s[16:17], 0x48000
	s_nop 0
	v_addc_co_u32_e32 v59, vcc, 0, v145, vcc
	global_store_dwordx4 v[58:59], v[62:65], off
	v_cvt_pk_bf16_f32 v50, v50, v51
	v_cvt_pk_bf16_f32 v51, v52, v53
	v_cvt_pk_bf16_f32 v52, v42, v43
	v_cvt_pk_bf16_f32 v53, v44, v45
	global_store_dwordx4 v[66:67], v[50:53], off offset:256
	v_cvt_pk_bf16_f32 v42, v54, v55
	v_cvt_pk_bf16_f32 v43, v56, v57
	v_cvt_pk_bf16_f32 v44, v46, v47
	v_cvt_pk_bf16_f32 v45, v48, v49
	s_nop 1
	v_lshl_add_u64 v[50:51], v[144:145], 0, s[16:17]
	s_mov_b32 s16, 0x48000
	v_add_co_u32_e32 v46, vcc, s16, v144
	s_mov_b64 s[16:17], s[10:11]
	s_nop 0
	v_addc_co_u32_e32 v47, vcc, 0, v145, vcc
	global_store_dwordx4 v[46:47], v[42:45], off
	v_cvt_pk_bf16_f32 v34, v34, v35
	v_cvt_pk_bf16_f32 v35, v36, v37
	v_cvt_pk_bf16_f32 v36, v26, v27
	v_cvt_pk_bf16_f32 v37, v28, v29
	global_store_dwordx4 v[50:51], v[34:37], off offset:256
	v_cvt_pk_bf16_f32 v26, v38, v39
	v_cvt_pk_bf16_f32 v27, v40, v41
	v_cvt_pk_bf16_f32 v28, v30, v31
	v_add_co_u32_e32 v30, vcc, s34, v144
	s_nop 0
	v_lshl_add_u64 v[34:35], v[144:145], 0, s[4:5]
	v_addc_co_u32_e32 v31, vcc, 0, v145, vcc
	v_cvt_pk_bf16_f32 v29, v32, v33
	global_store_dwordx4 v[30:31], v[26:29], off
	v_cvt_pk_bf16_f32 v18, v18, v19
	v_cvt_pk_bf16_f32 v19, v20, v21
	v_cvt_pk_bf16_f32 v20, v10, v11
	v_cvt_pk_bf16_f32 v21, v12, v13
	global_store_dwordx4 v[34:35], v[18:21], off offset:256
	v_cvt_pk_bf16_f32 v10, v22, v23
	v_cvt_pk_bf16_f32 v11, v24, v25
	v_cvt_pk_bf16_f32 v12, v14, v15
	v_add_co_u32_e32 v14, vcc, s35, v144
	s_nop 0
	v_lshl_add_u64 v[18:19], v[144:145], 0, s[6:7]
	v_addc_co_u32_e32 v15, vcc, 0, v145, vcc
	v_cvt_pk_bf16_f32 v13, v16, v17
	global_store_dwordx4 v[14:15], v[10:13], off
	v_cvt_pk_bf16_f32 v6, v6, v7
	v_cvt_pk_bf16_f32 v7, v8, v9
	v_cvt_pk_bf16_f32 v8, v2, v3
	v_cvt_pk_bf16_f32 v9, v4, v5
	global_store_dwordx4 v[18:19], v[6:9], off offset:256
	s_cbranch_scc0 .LBB0_1717
	s_waitcnt vmcnt(0)
	s_cmpk_gt_u32 s0, 0xff
	s_cbranch_scc1 .LBB0_1722
	s_barrier

.LBB0_2185:
	ds_read_b128 v[146:149], v152
	ds_read_b128 v[156:159], v152 offset:1024
	ds_read_b128 v[160:163], v152 offset:2048
	ds_read_b128 v[164:167], v152 offset:3072
	ds_read_b128 v[168:171], v153
	ds_read_b128 v[172:175], v153 offset:1024
	ds_read_b128 v[176:179], v153 offset:2048
	ds_read_b128 v[180:183], v153 offset:3072
	s_add_u32 s22, s20, 0xfc000
	s_addc_u32 s23, s21, 0
	s_cmp_eq_u32 s44, 4
	s_cselect_b32 s26, s15, s22
	s_cselect_b32 s27, s5, s23
	s_cselect_b32 s24, s41, s42
	s_cselect_b32 s25, s13, s43
	s_add_u32 s22, s26, 0x100000
	s_addc_u32 s23, s27, 0
	s_add_i32 m0, s1, 0xc000
	ds_read_b128 v[184:187], v154
	ds_read_b128 v[188:191], v154 offset:1024
	ds_read_b128 v[192:195], v154 offset:2048
	ds_read_b128 v[196:199], v154 offset:3072
	ds_read_b128 v[206:209], v154 offset:4096
	ds_read_b128 v[212:215], v154 offset:5120
	ds_read_b128 v[220:223], v154 offset:6144
	ds_read_b128 v[224:227], v154 offset:7168
	global_load_lds_dwordx4 v138, s[20:21]
	s_add_i32 m0, s1, 0xe000
	s_nop 0
	global_load_lds_dwordx4 v140, s[20:21]
	s_waitcnt vmcnt(8)
	s_waitcnt lgkmcnt(0)
	s_setprio 1
	s_barrier
	v_mfma_f32_16x16x32_bf16 v[126:129], v[146:149], v[184:187], v[126:129]
	v_mfma_f32_16x16x32_bf16 v[122:125], v[160:163], v[184:187], v[122:125]
	v_mfma_f32_16x16x32_bf16 v[110:113], v[146:149], v[192:195], v[110:113]
	v_mfma_f32_16x16x32_bf16 v[106:109], v[160:163], v[192:195], v[106:109]
	v_mfma_f32_16x16x32_bf16 v[94:97], v[146:149], v[206:209], v[94:97]
	v_mfma_f32_16x16x32_bf16 v[90:93], v[160:163], v[206:209], v[90:93]
	v_mfma_f32_16x16x32_bf16 v[78:81], v[146:149], v[220:223], v[78:81]
	v_mfma_f32_16x16x32_bf16 v[74:77], v[160:163], v[220:223], v[74:77]
	v_mfma_f32_16x16x32_bf16 v[126:129], v[156:159], v[188:191], v[126:129]
	v_mfma_f32_16x16x32_bf16 v[122:125], v[164:167], v[188:191], v[122:125]
	v_mfma_f32_16x16x32_bf16 v[110:113], v[156:159], v[196:199], v[110:113]
	v_mfma_f32_16x16x32_bf16 v[106:109], v[164:167], v[196:199], v[106:109]
	v_mfma_f32_16x16x32_bf16 v[94:97], v[156:159], v[212:215], v[94:97]
	v_mfma_f32_16x16x32_bf16 v[90:93], v[164:167], v[212:215], v[90:93]
	v_mfma_f32_16x16x32_bf16 v[78:81], v[156:159], v[224:227], v[78:81]
	v_mfma_f32_16x16x32_bf16 v[74:77], v[164:167], v[224:227], v[74:77]
	s_setprio 0
	s_setprio 1
	v_mfma_f32_16x16x32_bf16 v[118:121], v[168:171], v[184:187], v[118:121]
	v_mfma_f32_16x16x32_bf16 v[114:117], v[176:179], v[184:187], v[114:117]
	v_mfma_f32_16x16x32_bf16 v[102:105], v[168:171], v[192:195], v[102:105]
	v_mfma_f32_16x16x32_bf16 v[98:101], v[176:179], v[192:195], v[98:101]
	v_mfma_f32_16x16x32_bf16 v[86:89], v[168:171], v[206:209], v[86:89]
	v_mfma_f32_16x16x32_bf16 v[82:85], v[176:179], v[206:209], v[82:85]
	v_mfma_f32_16x16x32_bf16 v[70:73], v[168:171], v[220:223], v[70:73]
	v_mfma_f32_16x16x32_bf16 v[66:69], v[176:179], v[220:223], v[66:69]
	v_mfma_f32_16x16x32_bf16 v[118:121], v[172:175], v[188:191], v[118:121]
	v_mfma_f32_16x16x32_bf16 v[114:117], v[180:183], v[188:191], v[114:117]
	v_mfma_f32_16x16x32_bf16 v[102:105], v[172:175], v[196:199], v[102:105]
	v_mfma_f32_16x16x32_bf16 v[98:101], v[180:183], v[196:199], v[98:101]
	v_mfma_f32_16x16x32_bf16 v[86:89], v[172:175], v[212:215], v[86:89]
	v_mfma_f32_16x16x32_bf16 v[82:85], v[180:183], v[212:215], v[82:85]
	v_mfma_f32_16x16x32_bf16 v[70:73], v[172:175], v[224:227], v[70:73]
	v_mfma_f32_16x16x32_bf16 v[66:69], v[180:183], v[224:227], v[66:69]
	s_barrier
	s_setprio 0
	s_add_i32 s45, s38, s0
	s_mov_b32 m0, s45
	ds_read_b128 v[184:187], v154 offset:16384
	ds_read_b128 v[188:191], v154 offset:17408
	ds_read_b128 v[192:195], v154 offset:18432
	ds_read_b128 v[196:199], v154 offset:19456
	ds_read_b128 v[206:209], v154 offset:20480
	ds_read_b128 v[212:215], v154 offset:21504
	ds_read_b128 v[220:223], v154 offset:22528
	ds_read_b128 v[224:227], v154 offset:23552
	global_load_lds_dwordx4 v132, s[24:25]
	s_add_i32 m0, s45, 0x2000
	s_add_u32 s46, s24, 0x4000
	s_addc_u32 s47, s25, 0
	s_add_i32 s45, s39, s0
	global_load_lds_dwordx4 v136, s[24:25]
	s_mov_b32 m0, s45
	s_nop 0
	global_load_lds_dwordx4 v132, s[46:47]
	s_add_i32 m0, s45, 0x2000
	s_nop 0
	global_load_lds_dwordx4 v136, s[46:47]
	s_mov_b32 m0, s1
	s_nop 0
	global_load_lds_dwordx4 v130, s[26:27]
	s_mov_b32 m0, s28
	s_nop 0
	global_load_lds_dwordx4 v134, s[26:27]
	s_waitcnt vmcnt(8)
	s_waitcnt lgkmcnt(0)
	s_setprio 1
	s_barrier
	v_mfma_f32_16x16x32_bf16 v[62:65], v[146:149], v[184:187], v[62:65]
	v_mfma_f32_16x16x32_bf16 v[58:61], v[160:163], v[184:187], v[58:61]
	v_mfma_f32_16x16x32_bf16 v[46:49], v[146:149], v[192:195], v[46:49]
	v_mfma_f32_16x16x32_bf16 v[42:45], v[160:163], v[192:195], v[42:45]
	v_mfma_f32_16x16x32_bf16 v[30:33], v[146:149], v[206:209], v[30:33]
	v_mfma_f32_16x16x32_bf16 v[26:29], v[160:163], v[206:209], v[26:29]
	v_mfma_f32_16x16x32_bf16 v[14:17], v[146:149], v[220:223], v[14:17]
	v_mfma_f32_16x16x32_bf16 v[10:13], v[160:163], v[220:223], v[10:13]
	v_mfma_f32_16x16x32_bf16 v[62:65], v[156:159], v[188:191], v[62:65]
	v_mfma_f32_16x16x32_bf16 v[58:61], v[164:167], v[188:191], v[58:61]
	v_mfma_f32_16x16x32_bf16 v[46:49], v[156:159], v[196:199], v[46:49]
	v_mfma_f32_16x16x32_bf16 v[42:45], v[164:167], v[196:199], v[42:45]
	v_mfma_f32_16x16x32_bf16 v[30:33], v[156:159], v[212:215], v[30:33]
	v_mfma_f32_16x16x32_bf16 v[26:29], v[164:167], v[212:215], v[26:29]
	v_mfma_f32_16x16x32_bf16 v[14:17], v[156:159], v[224:227], v[14:17]
	v_mfma_f32_16x16x32_bf16 v[10:13], v[164:167], v[224:227], v[10:13]
	s_setprio 0
	s_setprio 1
	v_mfma_f32_16x16x32_bf16 v[54:57], v[168:171], v[184:187], v[54:57]
	v_mfma_f32_16x16x32_bf16 v[50:53], v[176:179], v[184:187], v[50:53]
	v_mfma_f32_16x16x32_bf16 v[38:41], v[168:171], v[192:195], v[38:41]
	v_mfma_f32_16x16x32_bf16 v[34:37], v[176:179], v[192:195], v[34:37]
	v_mfma_f32_16x16x32_bf16 v[22:25], v[168:171], v[206:209], v[22:25]
	v_mfma_f32_16x16x32_bf16 v[18:21], v[176:179], v[206:209], v[18:21]
	v_mfma_f32_16x16x32_bf16 v[6:9], v[168:171], v[220:223], v[6:9]
	v_mfma_f32_16x16x32_bf16 v[2:5], v[176:179], v[220:223], v[2:5]
	v_mfma_f32_16x16x32_bf16 v[54:57], v[172:175], v[188:191], v[54:57]
	v_mfma_f32_16x16x32_bf16 v[50:53], v[180:183], v[188:191], v[50:53]
	v_mfma_f32_16x16x32_bf16 v[38:41], v[172:175], v[196:199], v[38:41]
	v_mfma_f32_16x16x32_bf16 v[34:37], v[180:183], v[196:199], v[34:37]
	v_mfma_f32_16x16x32_bf16 v[22:25], v[172:175], v[212:215], v[22:25]
	v_mfma_f32_16x16x32_bf16 v[18:21], v[180:183], v[212:215], v[18:21]
	v_mfma_f32_16x16x32_bf16 v[6:9], v[172:175], v[224:227], v[6:9]
	v_mfma_f32_16x16x32_bf16 v[2:5], v[180:183], v[224:227], v[2:5]
	s_barrier
	s_setprio 0
	s_add_i32 s45, 0, 0x18000
	v_add_u32_e32 v155, s45, v151
	s_add_i32 s46, 0, 0x1c000
	ds_read_b128 v[146:149], v155
	ds_read_b128 v[156:159], v155 offset:1024
	ds_read_b128 v[160:163], v155 offset:2048
	ds_read_b128 v[164:167], v155 offset:3072
	v_add_u32_e32 v155, s46, v151
	ds_read_b128 v[168:171], v155
	ds_read_b128 v[172:175], v155 offset:1024
	ds_read_b128 v[176:179], v155 offset:2048
	ds_read_b128 v[180:183], v155 offset:3072
	s_add_u32 s26, s26, 0x4000
	s_addc_u32 s27, s27, 0
	s_mov_b32 m0, s29
	ds_read_b128 v[184:187], v154 offset:32768
	ds_read_b128 v[188:191], v154 offset:33792
	ds_read_b128 v[192:195], v154 offset:34816
	ds_read_b128 v[196:199], v154 offset:35840
	ds_read_b128 v[206:209], v154 offset:36864
	ds_read_b128 v[212:215], v154 offset:37888
	ds_read_b128 v[220:223], v154 offset:38912
	ds_read_b128 v[224:227], v154 offset:39936
	global_load_lds_dwordx4 v130, s[26:27]
	s_mov_b32 m0, s30
	s_nop 0
	global_load_lds_dwordx4 v134, s[26:27]
	s_waitcnt vmcnt(8)
	s_waitcnt lgkmcnt(0)
	s_setprio 1
	s_barrier
	v_mfma_f32_16x16x32_bf16 v[126:129], v[146:149], v[184:187], v[126:129]
	v_mfma_f32_16x16x32_bf16 v[122:125], v[160:163], v[184:187], v[122:125]
	v_mfma_f32_16x16x32_bf16 v[110:113], v[146:149], v[192:195], v[110:113]
	v_mfma_f32_16x16x32_bf16 v[106:109], v[160:163], v[192:195], v[106:109]
	v_mfma_f32_16x16x32_bf16 v[94:97], v[146:149], v[206:209], v[94:97]
	v_mfma_f32_16x16x32_bf16 v[90:93], v[160:163], v[206:209], v[90:93]
	v_mfma_f32_16x16x32_bf16 v[78:81], v[146:149], v[220:223], v[78:81]
	v_mfma_f32_16x16x32_bf16 v[74:77], v[160:163], v[220:223], v[74:77]
	v_mfma_f32_16x16x32_bf16 v[126:129], v[156:159], v[188:191], v[126:129]
	v_mfma_f32_16x16x32_bf16 v[122:125], v[164:167], v[188:191], v[122:125]
	v_mfma_f32_16x16x32_bf16 v[110:113], v[156:159], v[196:199], v[110:113]
	v_mfma_f32_16x16x32_bf16 v[106:109], v[164:167], v[196:199], v[106:109]
	v_mfma_f32_16x16x32_bf16 v[94:97], v[156:159], v[212:215], v[94:97]
	v_mfma_f32_16x16x32_bf16 v[90:93], v[164:167], v[212:215], v[90:93]
	v_mfma_f32_16x16x32_bf16 v[78:81], v[156:159], v[224:227], v[78:81]
	v_mfma_f32_16x16x32_bf16 v[74:77], v[164:167], v[224:227], v[74:77]
	s_setprio 0
	s_setprio 1
	v_mfma_f32_16x16x32_bf16 v[118:121], v[168:171], v[184:187], v[118:121]
	v_mfma_f32_16x16x32_bf16 v[114:117], v[176:179], v[184:187], v[114:117]
	v_mfma_f32_16x16x32_bf16 v[102:105], v[168:171], v[192:195], v[102:105]
	v_mfma_f32_16x16x32_bf16 v[98:101], v[176:179], v[192:195], v[98:101]
	v_mfma_f32_16x16x32_bf16 v[86:89], v[168:171], v[206:209], v[86:89]
	v_mfma_f32_16x16x32_bf16 v[82:85], v[176:179], v[206:209], v[82:85]
	v_mfma_f32_16x16x32_bf16 v[70:73], v[168:171], v[220:223], v[70:73]
	v_mfma_f32_16x16x32_bf16 v[66:69], v[176:179], v[220:223], v[66:69]
	v_mfma_f32_16x16x32_bf16 v[118:121], v[172:175], v[188:191], v[118:121]
	v_mfma_f32_16x16x32_bf16 v[114:117], v[180:183], v[188:191], v[114:117]
	v_mfma_f32_16x16x32_bf16 v[102:105], v[172:175], v[196:199], v[102:105]
	v_mfma_f32_16x16x32_bf16 v[98:101], v[180:183], v[196:199], v[98:101]
	v_mfma_f32_16x16x32_bf16 v[86:89], v[172:175], v[212:215], v[86:89]
	v_mfma_f32_16x16x32_bf16 v[82:85], v[180:183], v[212:215], v[82:85]
	v_mfma_f32_16x16x32_bf16 v[70:73], v[172:175], v[224:227], v[70:73]
	v_mfma_f32_16x16x32_bf16 v[66:69], v[180:183], v[224:227], v[66:69]
	s_barrier
	s_setprio 0
	s_add_u32 s26, s24, 0x80000
	s_addc_u32 s27, s25, 0
	s_add_i32 s45, s45, s0
	s_mov_b32 m0, s45
	ds_read_b128 v[184:187], v154 offset:49152
	ds_read_b128 v[188:191], v154 offset:50176
	ds_read_b128 v[192:195], v154 offset:51200
	ds_read_b128 v[196:199], v154 offset:52224
	ds_read_b128 v[206:209], v154 offset:53248
	ds_read_b128 v[212:215], v154 offset:54272
	ds_read_b128 v[220:223], v154 offset:55296
	ds_read_b128 v[224:227], v154 offset:56320
	global_load_lds_dwordx4 v132, s[26:27]
	s_add_i32 m0, s45, 0x2000
	s_add_u32 s24, s24, 0x84000
	s_addc_u32 s25, s25, 0
	global_load_lds_dwordx4 v136, s[26:27]
	s_add_i32 s26, s46, s0
	s_mov_b32 m0, s26
	s_nop 0
	global_load_lds_dwordx4 v132, s[24:25]
	s_add_i32 m0, s26, 0x2000
	s_nop 0
	global_load_lds_dwordx4 v136, s[24:25]
	s_mov_b32 m0, s36
	s_nop 0
	global_load_lds_dwordx4 v130, s[22:23]
	s_mov_b32 m0, s37
	s_nop 0
	global_load_lds_dwordx4 v134, s[22:23]
	s_waitcnt vmcnt(8)
	s_waitcnt lgkmcnt(0)
	s_setprio 1
	s_barrier
	v_mfma_f32_16x16x32_bf16 v[62:65], v[146:149], v[184:187], v[62:65]
	v_mfma_f32_16x16x32_bf16 v[58:61], v[160:163], v[184:187], v[58:61]
	v_mfma_f32_16x16x32_bf16 v[46:49], v[146:149], v[192:195], v[46:49]
	v_mfma_f32_16x16x32_bf16 v[42:45], v[160:163], v[192:195], v[42:45]
	v_mfma_f32_16x16x32_bf16 v[30:33], v[146:149], v[206:209], v[30:33]
	v_mfma_f32_16x16x32_bf16 v[26:29], v[160:163], v[206:209], v[26:29]
	v_mfma_f32_16x16x32_bf16 v[14:17], v[146:149], v[220:223], v[14:17]
	v_mfma_f32_16x16x32_bf16 v[10:13], v[160:163], v[220:223], v[10:13]
	v_mfma_f32_16x16x32_bf16 v[62:65], v[156:159], v[188:191], v[62:65]
	v_mfma_f32_16x16x32_bf16 v[58:61], v[164:167], v[188:191], v[58:61]
	v_mfma_f32_16x16x32_bf16 v[46:49], v[156:159], v[196:199], v[46:49]
	v_mfma_f32_16x16x32_bf16 v[42:45], v[164:167], v[196:199], v[42:45]
	v_mfma_f32_16x16x32_bf16 v[30:33], v[156:159], v[212:215], v[30:33]
	v_mfma_f32_16x16x32_bf16 v[26:29], v[164:167], v[212:215], v[26:29]
	v_mfma_f32_16x16x32_bf16 v[14:17], v[156:159], v[224:227], v[14:17]
	v_mfma_f32_16x16x32_bf16 v[10:13], v[164:167], v[224:227], v[10:13]
	s_setprio 0
	s_setprio 1
	v_mfma_f32_16x16x32_bf16 v[54:57], v[168:171], v[184:187], v[54:57]
	v_mfma_f32_16x16x32_bf16 v[50:53], v[176:179], v[184:187], v[50:53]
	v_mfma_f32_16x16x32_bf16 v[38:41], v[168:171], v[192:195], v[38:41]
	v_mfma_f32_16x16x32_bf16 v[34:37], v[176:179], v[192:195], v[34:37]
	v_mfma_f32_16x16x32_bf16 v[22:25], v[168:171], v[206:209], v[22:25]
	v_mfma_f32_16x16x32_bf16 v[18:21], v[176:179], v[206:209], v[18:21]
	v_mfma_f32_16x16x32_bf16 v[6:9], v[168:171], v[220:223], v[6:9]
	v_mfma_f32_16x16x32_bf16 v[2:5], v[176:179], v[220:223], v[2:5]
	v_mfma_f32_16x16x32_bf16 v[54:57], v[172:175], v[188:191], v[54:57]
	v_mfma_f32_16x16x32_bf16 v[50:53], v[180:183], v[188:191], v[50:53]
	v_mfma_f32_16x16x32_bf16 v[38:41], v[172:175], v[196:199], v[38:41]
	v_mfma_f32_16x16x32_bf16 v[34:37], v[180:183], v[196:199], v[34:37]
	v_mfma_f32_16x16x32_bf16 v[22:25], v[172:175], v[212:215], v[22:25]
	v_mfma_f32_16x16x32_bf16 v[18:21], v[180:183], v[212:215], v[18:21]
	v_mfma_f32_16x16x32_bf16 v[6:9], v[172:175], v[224:227], v[6:9]
	v_mfma_f32_16x16x32_bf16 v[2:5], v[180:183], v[224:227], v[2:5]
	s_barrier
	s_setprio 0
	s_add_i32 s44, s44, 2
	s_add_u32 s42, s42, 0x100000
	s_addc_u32 s43, s43, 0
	s_add_u32 s20, s20, 0x200000
	s_addc_u32 s21, s21, 0
	s_cmp_gt_u32 s44, 5
	s_cbranch_scc0 .LBB0_2185
	s_and_b64 vcc, exec, s[8:9]
	s_cbranch_vccz .LBB0_2188
	s_barrier

.LBB0_2480:
	ds_read_b128 v[18:21], v182
	ds_read_b128 v[22:25], v182 offset:1024
	ds_read_b128 v[26:29], v182 offset:2048
	ds_read_b128 v[30:33], v182 offset:3072
	ds_read_b128 v[2:5], v183
	ds_read_b128 v[6:9], v183 offset:1024
	ds_read_b128 v[10:13], v183 offset:2048
	ds_read_b128 v[14:17], v183 offset:3072
	s_add_u32 s26, s24, 0xfc000
	s_addc_u32 s27, s25, 0
	s_cmp_eq_u32 s48, 28
	s_cselect_b32 s30, s17, s26
	s_cselect_b32 s31, s5, s27
	s_cselect_b32 s28, s23, s46
	s_cselect_b32 s29, s15, s47
	s_add_u32 s26, s30, 0x100000
	s_addc_u32 s27, s31, 0
	s_add_i32 m0, s34, 0xc000
	ds_read_b128 v[186:189], v184
	ds_read_b128 v[190:193], v184 offset:1024
	ds_read_b128 v[220:223], v184 offset:2048
	ds_read_b128 v[224:227], v184 offset:3072
	ds_read_b128 v[228:231], v184 offset:4096
	ds_read_b128 v[232:235], v184 offset:5120
	ds_read_b128 v[236:239], v184 offset:6144
	ds_read_b128 v[240:243], v184 offset:7168
	global_load_lds_dwordx4 v172, s[24:25]
	s_add_i32 m0, s34, 0xe000
	s_nop 0
	global_load_lds_dwordx4 v174, s[24:25]
	s_waitcnt vmcnt(8)
	s_waitcnt lgkmcnt(0)
	s_setprio 1
	s_barrier
	v_mfma_f32_16x16x128_f8f6f4 v[158:161], v[18:25], v[186:193], v[158:161]
	v_mfma_f32_16x16x128_f8f6f4 v[154:157], v[26:33], v[186:193], v[154:157]
	v_mfma_f32_16x16x128_f8f6f4 v[142:145], v[18:25], v[220:227], v[142:145]
	v_mfma_f32_16x16x128_f8f6f4 v[138:141], v[26:33], v[220:227], v[138:141]
	v_mfma_f32_16x16x128_f8f6f4 v[126:129], v[18:25], v[228:235], v[126:129]
	v_mfma_f32_16x16x128_f8f6f4 v[122:125], v[26:33], v[228:235], v[122:125]
	v_mfma_f32_16x16x128_f8f6f4 v[110:113], v[18:25], v[236:243], v[110:113]
	v_mfma_f32_16x16x128_f8f6f4 v[106:109], v[26:33], v[236:243], v[106:109]
	s_setprio 0
	s_setprio 1
	v_mfma_f32_16x16x128_f8f6f4 v[150:153], v[2:9], v[186:193], v[150:153]
	v_mfma_f32_16x16x128_f8f6f4 v[146:149], v[10:17], v[186:193], v[146:149]
	v_mfma_f32_16x16x128_f8f6f4 v[134:137], v[2:9], v[220:227], v[134:137]
	v_mfma_f32_16x16x128_f8f6f4 v[130:133], v[10:17], v[220:227], v[130:133]
	v_mfma_f32_16x16x128_f8f6f4 v[118:121], v[2:9], v[228:235], v[118:121]
	v_mfma_f32_16x16x128_f8f6f4 v[114:117], v[10:17], v[228:235], v[114:117]
	v_mfma_f32_16x16x128_f8f6f4 v[102:105], v[2:9], v[236:243], v[102:105]
	v_mfma_f32_16x16x128_f8f6f4 v[98:101], v[10:17], v[236:243], v[98:101]
	s_barrier
	s_setprio 0
	s_add_i32 s49, s42, s0
	s_mov_b32 m0, s49
	ds_read_b128 v[186:189], v184 offset:16384
	ds_read_b128 v[190:193], v184 offset:17408
	ds_read_b128 v[220:223], v184 offset:18432
	ds_read_b128 v[224:227], v184 offset:19456
	ds_read_b128 v[228:231], v184 offset:20480
	ds_read_b128 v[232:235], v184 offset:21504
	ds_read_b128 v[236:239], v184 offset:22528
	ds_read_b128 v[240:243], v184 offset:23552
	global_load_lds_dwordx4 v166, s[28:29]
	s_add_i32 m0, s49, 0x2000
	s_add_u32 s50, s28, 0x4000
	s_addc_u32 s51, s29, 0
	s_add_i32 s49, s43, s0
	global_load_lds_dwordx4 v162, s[28:29]
	s_mov_b32 m0, s49
	s_nop 0
	global_load_lds_dwordx4 v166, s[50:51]
	s_add_i32 m0, s49, 0x2000
	s_nop 0
	global_load_lds_dwordx4 v162, s[50:51]
	s_mov_b32 m0, s34
	s_nop 0
	global_load_lds_dwordx4 v168, s[30:31]
	s_mov_b32 m0, s35
	s_nop 0
	global_load_lds_dwordx4 v164, s[30:31]
	s_waitcnt vmcnt(8)
	s_waitcnt lgkmcnt(0)
	s_setprio 1
	s_barrier
	v_mfma_f32_16x16x128_f8f6f4 v[94:97], v[18:25], v[186:193], v[94:97]
	v_mfma_f32_16x16x128_f8f6f4 v[90:93], v[26:33], v[186:193], v[90:93]
	v_mfma_f32_16x16x128_f8f6f4 v[78:81], v[18:25], v[220:227], v[78:81]
	v_mfma_f32_16x16x128_f8f6f4 v[74:77], v[26:33], v[220:227], v[74:77]
	v_mfma_f32_16x16x128_f8f6f4 v[62:65], v[18:25], v[228:235], v[62:65]
	v_mfma_f32_16x16x128_f8f6f4 v[58:61], v[26:33], v[228:235], v[58:61]
	v_mfma_f32_16x16x128_f8f6f4 v[46:49], v[18:25], v[236:243], v[46:49]
	v_mfma_f32_16x16x128_f8f6f4 v[42:45], v[26:33], v[236:243], v[42:45]
	s_setprio 0
	s_setprio 1
	v_mfma_f32_16x16x128_f8f6f4 v[86:89], v[2:9], v[186:193], v[86:89]
	v_mfma_f32_16x16x128_f8f6f4 v[82:85], v[10:17], v[186:193], v[82:85]
	v_mfma_f32_16x16x128_f8f6f4 v[70:73], v[2:9], v[220:227], v[70:73]
	v_mfma_f32_16x16x128_f8f6f4 v[66:69], v[10:17], v[220:227], v[66:69]
	v_mfma_f32_16x16x128_f8f6f4 v[54:57], v[2:9], v[228:235], v[54:57]
	v_mfma_f32_16x16x128_f8f6f4 v[50:53], v[10:17], v[228:235], v[50:53]
	v_mfma_f32_16x16x128_f8f6f4 v[38:41], v[2:9], v[236:243], v[38:41]
	v_mfma_f32_16x16x128_f8f6f4 v[34:37], v[10:17], v[236:243], v[34:37]
	s_barrier
	s_setprio 0
	s_add_i32 s49, 0, 0x18000
	s_add_i32 s50, 0, 0x1c000
	v_add_u32_e32 v14, s49, v181
	v_add_u32_e32 v30, s50, v181
	ds_read_b128 v[2:5], v14
	ds_read_b128 v[6:9], v14 offset:1024
	ds_read_b128 v[10:13], v14 offset:2048
	ds_read_b128 v[14:17], v14 offset:3072
	ds_read_b128 v[18:21], v30
	ds_read_b128 v[22:25], v30 offset:1024
	ds_read_b128 v[26:29], v30 offset:2048
	ds_read_b128 v[30:33], v30 offset:3072
	s_add_u32 s30, s30, 0x4000
	s_addc_u32 s31, s31, 0
	s_mov_b32 m0, s36
	ds_read_b128 v[186:189], v184 offset:32768
	ds_read_b128 v[190:193], v184 offset:33792
	ds_read_b128 v[220:223], v184 offset:34816
	ds_read_b128 v[224:227], v184 offset:35840
	ds_read_b128 v[228:231], v184 offset:36864
	ds_read_b128 v[232:235], v184 offset:37888
	ds_read_b128 v[236:239], v184 offset:38912
	ds_read_b128 v[240:243], v184 offset:39936
	global_load_lds_dwordx4 v168, s[30:31]
	s_mov_b32 m0, s37
	s_nop 0
	global_load_lds_dwordx4 v164, s[30:31]
	s_waitcnt vmcnt(8)
	s_waitcnt lgkmcnt(0)
	s_setprio 1
	s_barrier
	v_mfma_f32_16x16x128_f8f6f4 v[158:161], v[2:9], v[186:193], v[158:161]
	v_mfma_f32_16x16x128_f8f6f4 v[154:157], v[10:17], v[186:193], v[154:157]
	v_mfma_f32_16x16x128_f8f6f4 v[142:145], v[2:9], v[220:227], v[142:145]
	v_mfma_f32_16x16x128_f8f6f4 v[138:141], v[10:17], v[220:227], v[138:141]
	v_mfma_f32_16x16x128_f8f6f4 v[126:129], v[2:9], v[228:235], v[126:129]
	v_mfma_f32_16x16x128_f8f6f4 v[122:125], v[10:17], v[228:235], v[122:125]
	v_mfma_f32_16x16x128_f8f6f4 v[110:113], v[2:9], v[236:243], v[110:113]
	v_mfma_f32_16x16x128_f8f6f4 v[106:109], v[10:17], v[236:243], v[106:109]
	s_setprio 0
	s_setprio 1
	v_mfma_f32_16x16x128_f8f6f4 v[150:153], v[18:25], v[186:193], v[150:153]
	v_mfma_f32_16x16x128_f8f6f4 v[146:149], v[26:33], v[186:193], v[146:149]
	v_mfma_f32_16x16x128_f8f6f4 v[134:137], v[18:25], v[220:227], v[134:137]
	v_mfma_f32_16x16x128_f8f6f4 v[130:133], v[26:33], v[220:227], v[130:133]
	v_mfma_f32_16x16x128_f8f6f4 v[118:121], v[18:25], v[228:235], v[118:121]
	v_mfma_f32_16x16x128_f8f6f4 v[114:117], v[26:33], v[228:235], v[114:117]
	v_mfma_f32_16x16x128_f8f6f4 v[102:105], v[18:25], v[236:243], v[102:105]
	v_mfma_f32_16x16x128_f8f6f4 v[98:101], v[26:33], v[236:243], v[98:101]
	s_barrier
	s_setprio 0
	s_add_u32 s30, s28, 0x380000
	s_addc_u32 s31, s29, 0
	s_add_i32 s49, s49, s0
	s_mov_b32 m0, s49
	ds_read_b128 v[186:189], v184 offset:49152
	ds_read_b128 v[190:193], v184 offset:50176
	ds_read_b128 v[220:223], v184 offset:51200
	ds_read_b128 v[224:227], v184 offset:52224
	ds_read_b128 v[228:231], v184 offset:53248
	ds_read_b128 v[232:235], v184 offset:54272
	ds_read_b128 v[236:239], v184 offset:55296
	ds_read_b128 v[240:243], v184 offset:56320
	global_load_lds_dwordx4 v166, s[30:31]
	s_add_i32 m0, s49, 0x2000
	s_add_u32 s28, s28, 0x384000
	s_addc_u32 s29, s29, 0
	global_load_lds_dwordx4 v162, s[30:31]
	s_add_i32 s30, s50, s0
	s_mov_b32 m0, s30
	s_nop 0
	global_load_lds_dwordx4 v166, s[28:29]
	s_add_i32 m0, s30, 0x2000
	s_nop 0
	global_load_lds_dwordx4 v162, s[28:29]
	s_mov_b32 m0, s40
	s_nop 0
	global_load_lds_dwordx4 v168, s[26:27]
	s_mov_b32 m0, s41
	s_nop 0
	global_load_lds_dwordx4 v164, s[26:27]
	s_waitcnt vmcnt(8)
	s_waitcnt lgkmcnt(0)
	s_setprio 1
	s_barrier
	v_mfma_f32_16x16x128_f8f6f4 v[94:97], v[2:9], v[186:193], v[94:97]
	v_mfma_f32_16x16x128_f8f6f4 v[90:93], v[10:17], v[186:193], v[90:93]
	v_mfma_f32_16x16x128_f8f6f4 v[78:81], v[2:9], v[220:227], v[78:81]
	v_mfma_f32_16x16x128_f8f6f4 v[74:77], v[10:17], v[220:227], v[74:77]
	v_mfma_f32_16x16x128_f8f6f4 v[62:65], v[2:9], v[228:235], v[62:65]
	v_mfma_f32_16x16x128_f8f6f4 v[58:61], v[10:17], v[228:235], v[58:61]
	v_mfma_f32_16x16x128_f8f6f4 v[46:49], v[2:9], v[236:243], v[46:49]
	v_mfma_f32_16x16x128_f8f6f4 v[42:45], v[10:17], v[236:243], v[42:45]
	s_setprio 0
	s_setprio 1
	v_mfma_f32_16x16x128_f8f6f4 v[86:89], v[18:25], v[186:193], v[86:89]
	v_mfma_f32_16x16x128_f8f6f4 v[82:85], v[26:33], v[186:193], v[82:85]
	v_mfma_f32_16x16x128_f8f6f4 v[70:73], v[18:25], v[220:227], v[70:73]
	v_mfma_f32_16x16x128_f8f6f4 v[66:69], v[26:33], v[220:227], v[66:69]
	v_mfma_f32_16x16x128_f8f6f4 v[54:57], v[18:25], v[228:235], v[54:57]
	v_mfma_f32_16x16x128_f8f6f4 v[50:53], v[26:33], v[228:235], v[50:53]
	v_mfma_f32_16x16x128_f8f6f4 v[38:41], v[18:25], v[236:243], v[38:41]
	v_mfma_f32_16x16x128_f8f6f4 v[34:37], v[26:33], v[236:243], v[34:37]
	s_barrier
	s_setprio 0
	s_add_i32 s48, s48, 2
	s_add_u32 s46, s46, 0x700000
	s_addc_u32 s47, s47, 0
	s_add_u32 s24, s24, 0x200000
	s_addc_u32 s25, s25, 0
	s_cmp_gt_u32 s48, 29
	s_cbranch_scc0 .LBB0_2480
	s_and_b64 vcc, exec, s[8:9]
	s_cbranch_vccz .LBB0_2483
	s_barrier

.LBB0_2714:
	ds_read_b128 v[18:21], v180
	ds_read_b128 v[22:25], v180 offset:1024
	ds_read_b128 v[26:29], v180 offset:2048
	ds_read_b128 v[30:33], v180 offset:3072
	s_waitcnt lgkmcnt(0)
	ds_read_b128 v[2:5], v181
	ds_read_b128 v[6:9], v181 offset:1024
	ds_read_b128 v[10:13], v181 offset:2048
	ds_read_b128 v[14:17], v181 offset:3072
	s_add_u32 s24, s22, 0xfc000
	s_addc_u32 s25, s23, 0
	s_cmpk_eq_i32 s44, 0x6c
	s_cselect_b32 s28, s17, s24
	s_cselect_b32 s29, s5, s25
	s_cselect_b32 s26, s41, s42
	s_cselect_b32 s27, s15, s43
	s_add_u32 s24, s28, 0x100000
	s_addc_u32 s25, s29, 0
	s_add_i32 m0, s1, 0xc000
	ds_read_b128 v[184:187], v182
	ds_read_b128 v[188:191], v182 offset:1024
	ds_read_b128 v[192:195], v182 offset:2048
	ds_read_b128 v[196:199], v182 offset:3072
	ds_read_b128 v[220:223], v182 offset:4096
	ds_read_b128 v[224:227], v182 offset:5120
	ds_read_b128 v[228:231], v182 offset:6144
	ds_read_b128 v[232:235], v182 offset:7168
	global_load_lds_dwordx4 v170, s[22:23]
	s_add_i32 m0, s1, 0xe000
	s_nop 0
	global_load_lds_dwordx4 v172, s[22:23]
	s_waitcnt vmcnt(8)
	s_waitcnt lgkmcnt(0)
	s_setprio 1
	s_barrier
	v_mfma_f32_16x16x128_f8f6f4 v[158:161], v[18:25], v[184:191], v[158:161]
	v_mfma_f32_16x16x128_f8f6f4 v[154:157], v[26:33], v[184:191], v[154:157]
	v_mfma_f32_16x16x128_f8f6f4 v[142:145], v[18:25], v[192:199], v[142:145]
	v_mfma_f32_16x16x128_f8f6f4 v[138:141], v[26:33], v[192:199], v[138:141]
	v_mfma_f32_16x16x128_f8f6f4 v[126:129], v[18:25], v[220:227], v[126:129]
	v_mfma_f32_16x16x128_f8f6f4 v[122:125], v[26:33], v[220:227], v[122:125]
	v_mfma_f32_16x16x128_f8f6f4 v[110:113], v[18:25], v[228:235], v[110:113]
	v_mfma_f32_16x16x128_f8f6f4 v[106:109], v[26:33], v[228:235], v[106:109]
	s_setprio 0
	s_setprio 1
	v_mfma_f32_16x16x128_f8f6f4 v[150:153], v[2:9], v[184:191], v[150:153]
	v_mfma_f32_16x16x128_f8f6f4 v[146:149], v[10:17], v[184:191], v[146:149]
	v_mfma_f32_16x16x128_f8f6f4 v[134:137], v[2:9], v[192:199], v[134:137]
	v_mfma_f32_16x16x128_f8f6f4 v[130:133], v[10:17], v[192:199], v[130:133]
	v_mfma_f32_16x16x128_f8f6f4 v[118:121], v[2:9], v[220:227], v[118:121]
	v_mfma_f32_16x16x128_f8f6f4 v[114:117], v[10:17], v[220:227], v[114:117]
	v_mfma_f32_16x16x128_f8f6f4 v[102:105], v[2:9], v[228:235], v[102:105]
	v_mfma_f32_16x16x128_f8f6f4 v[98:101], v[10:17], v[228:235], v[98:101]
	s_barrier
	s_setprio 0
	s_add_i32 s45, s38, s0
	s_mov_b32 m0, s45
	ds_read_b128 v[184:187], v182 offset:16384
	ds_read_b128 v[188:191], v182 offset:17408
	ds_read_b128 v[192:195], v182 offset:18432
	ds_read_b128 v[196:199], v182 offset:19456
	ds_read_b128 v[220:223], v182 offset:20480
	ds_read_b128 v[224:227], v182 offset:21504
	ds_read_b128 v[228:231], v182 offset:22528
	ds_read_b128 v[232:235], v182 offset:23552
	global_load_lds_dwordx4 v164, s[26:27]
	s_add_i32 m0, s45, 0x2000
	s_add_u32 s46, s26, 0x4000
	s_addc_u32 s47, s27, 0
	s_add_i32 s45, s39, s0
	global_load_lds_dwordx4 v168, s[26:27]
	s_mov_b32 m0, s45
	s_nop 0
	global_load_lds_dwordx4 v164, s[46:47]
	s_add_i32 m0, s45, 0x2000
	s_nop 0
	global_load_lds_dwordx4 v168, s[46:47]
	s_mov_b32 m0, s1
	s_nop 0
	global_load_lds_dwordx4 v162, s[28:29]
	s_mov_b32 m0, s13
	s_nop 0
	global_load_lds_dwordx4 v166, s[28:29]
	s_waitcnt vmcnt(8)
	s_waitcnt lgkmcnt(0)
	s_setprio 1
	s_barrier
	v_mfma_f32_16x16x128_f8f6f4 v[94:97], v[18:25], v[184:191], v[94:97]
	v_mfma_f32_16x16x128_f8f6f4 v[90:93], v[26:33], v[184:191], v[90:93]
	v_mfma_f32_16x16x128_f8f6f4 v[78:81], v[18:25], v[192:199], v[78:81]
	v_mfma_f32_16x16x128_f8f6f4 v[74:77], v[26:33], v[192:199], v[74:77]
	v_mfma_f32_16x16x128_f8f6f4 v[62:65], v[18:25], v[220:227], v[62:65]
	v_mfma_f32_16x16x128_f8f6f4 v[58:61], v[26:33], v[220:227], v[58:61]
	v_mfma_f32_16x16x128_f8f6f4 v[46:49], v[18:25], v[228:235], v[46:49]
	v_mfma_f32_16x16x128_f8f6f4 v[42:45], v[26:33], v[228:235], v[42:45]
	s_setprio 0
	s_setprio 1
	v_mfma_f32_16x16x128_f8f6f4 v[86:89], v[2:9], v[184:191], v[86:89]
	v_mfma_f32_16x16x128_f8f6f4 v[82:85], v[10:17], v[184:191], v[82:85]
	v_mfma_f32_16x16x128_f8f6f4 v[70:73], v[2:9], v[192:199], v[70:73]
	v_mfma_f32_16x16x128_f8f6f4 v[66:69], v[10:17], v[192:199], v[66:69]
	v_mfma_f32_16x16x128_f8f6f4 v[54:57], v[2:9], v[220:227], v[54:57]
	v_mfma_f32_16x16x128_f8f6f4 v[50:53], v[10:17], v[220:227], v[50:53]
	v_mfma_f32_16x16x128_f8f6f4 v[38:41], v[2:9], v[228:235], v[38:41]
	v_mfma_f32_16x16x128_f8f6f4 v[34:37], v[10:17], v[228:235], v[34:37]
	s_barrier
	s_setprio 0
	s_add_i32 s45, 0, 0x18000
	s_add_i32 s46, 0, 0x1c000
	v_add_u32_e32 v14, s45, v179
	v_add_u32_e32 v30, s46, v179
	ds_read_b128 v[2:5], v14
	ds_read_b128 v[6:9], v14 offset:1024
	ds_read_b128 v[10:13], v14 offset:2048
	ds_read_b128 v[14:17], v14 offset:3072
	ds_read_b128 v[18:21], v30
	ds_read_b128 v[22:25], v30 offset:1024
	ds_read_b128 v[26:29], v30 offset:2048
	ds_read_b128 v[30:33], v30 offset:3072
	s_add_u32 s28, s28, 0x4000
	s_addc_u32 s29, s29, 0
	s_mov_b32 m0, s30
	ds_read_b128 v[184:187], v182 offset:32768
	ds_read_b128 v[188:191], v182 offset:33792
	ds_read_b128 v[192:195], v182 offset:34816
	ds_read_b128 v[196:199], v182 offset:35840
	ds_read_b128 v[220:223], v182 offset:36864
	ds_read_b128 v[224:227], v182 offset:37888
	ds_read_b128 v[228:231], v182 offset:38912
	ds_read_b128 v[232:235], v182 offset:39936
	global_load_lds_dwordx4 v162, s[28:29]
	s_mov_b32 m0, s31
	s_nop 0
	global_load_lds_dwordx4 v166, s[28:29]
	s_waitcnt vmcnt(8)
	s_waitcnt lgkmcnt(0)
	s_setprio 1
	s_barrier
	v_mfma_f32_16x16x128_f8f6f4 v[158:161], v[2:9], v[184:191], v[158:161]
	v_mfma_f32_16x16x128_f8f6f4 v[154:157], v[10:17], v[184:191], v[154:157]
	v_mfma_f32_16x16x128_f8f6f4 v[142:145], v[2:9], v[192:199], v[142:145]
	v_mfma_f32_16x16x128_f8f6f4 v[138:141], v[10:17], v[192:199], v[138:141]
	v_mfma_f32_16x16x128_f8f6f4 v[126:129], v[2:9], v[220:227], v[126:129]
	v_mfma_f32_16x16x128_f8f6f4 v[122:125], v[10:17], v[220:227], v[122:125]
	v_mfma_f32_16x16x128_f8f6f4 v[110:113], v[2:9], v[228:235], v[110:113]
	v_mfma_f32_16x16x128_f8f6f4 v[106:109], v[10:17], v[228:235], v[106:109]
	s_setprio 0
	s_setprio 1
	v_mfma_f32_16x16x128_f8f6f4 v[150:153], v[18:25], v[184:191], v[150:153]
	v_mfma_f32_16x16x128_f8f6f4 v[146:149], v[26:33], v[184:191], v[146:149]
	v_mfma_f32_16x16x128_f8f6f4 v[134:137], v[18:25], v[192:199], v[134:137]
	v_mfma_f32_16x16x128_f8f6f4 v[130:133], v[26:33], v[192:199], v[130:133]
	v_mfma_f32_16x16x128_f8f6f4 v[118:121], v[18:25], v[220:227], v[118:121]
	v_mfma_f32_16x16x128_f8f6f4 v[114:117], v[26:33], v[220:227], v[114:117]
	v_mfma_f32_16x16x128_f8f6f4 v[102:105], v[18:25], v[228:235], v[102:105]
	v_mfma_f32_16x16x128_f8f6f4 v[98:101], v[26:33], v[228:235], v[98:101]
	s_barrier
	s_setprio 0
	s_add_u32 s28, s26, 0x80000
	s_addc_u32 s29, s27, 0
	s_add_i32 s45, s45, s0
	s_mov_b32 m0, s45
	ds_read_b128 v[184:187], v182 offset:49152
	ds_read_b128 v[188:191], v182 offset:50176
	ds_read_b128 v[192:195], v182 offset:51200
	ds_read_b128 v[196:199], v182 offset:52224
	ds_read_b128 v[220:223], v182 offset:53248
	ds_read_b128 v[224:227], v182 offset:54272
	ds_read_b128 v[228:231], v182 offset:55296
	ds_read_b128 v[232:235], v182 offset:56320
	global_load_lds_dwordx4 v164, s[28:29]
	s_add_i32 m0, s45, 0x2000
	s_add_u32 s26, s26, 0x84000
	s_addc_u32 s27, s27, 0
	global_load_lds_dwordx4 v168, s[28:29]
	s_add_i32 s28, s46, s0
	s_mov_b32 m0, s28
	s_nop 0
	global_load_lds_dwordx4 v164, s[26:27]
	s_add_i32 m0, s28, 0x2000
	s_nop 0
	global_load_lds_dwordx4 v168, s[26:27]
	s_mov_b32 m0, s36
	s_nop 0
	global_load_lds_dwordx4 v162, s[24:25]
	s_mov_b32 m0, s37
	s_nop 0
	global_load_lds_dwordx4 v166, s[24:25]
	s_waitcnt vmcnt(8)
	s_waitcnt lgkmcnt(0)
	s_setprio 1
	s_barrier
	v_mfma_f32_16x16x128_f8f6f4 v[94:97], v[2:9], v[184:191], v[94:97]
	v_mfma_f32_16x16x128_f8f6f4 v[90:93], v[10:17], v[184:191], v[90:93]
	v_mfma_f32_16x16x128_f8f6f4 v[78:81], v[2:9], v[192:199], v[78:81]
	v_mfma_f32_16x16x128_f8f6f4 v[74:77], v[10:17], v[192:199], v[74:77]
	v_mfma_f32_16x16x128_f8f6f4 v[62:65], v[2:9], v[220:227], v[62:65]
	v_mfma_f32_16x16x128_f8f6f4 v[58:61], v[10:17], v[220:227], v[58:61]
	v_mfma_f32_16x16x128_f8f6f4 v[46:49], v[2:9], v[228:235], v[46:49]
	v_mfma_f32_16x16x128_f8f6f4 v[42:45], v[10:17], v[228:235], v[42:45]
	s_setprio 0
	s_setprio 1
	v_mfma_f32_16x16x128_f8f6f4 v[86:89], v[18:25], v[184:191], v[86:89]
	v_mfma_f32_16x16x128_f8f6f4 v[82:85], v[26:33], v[184:191], v[82:85]
	v_mfma_f32_16x16x128_f8f6f4 v[70:73], v[18:25], v[192:199], v[70:73]
	v_mfma_f32_16x16x128_f8f6f4 v[66:69], v[26:33], v[192:199], v[66:69]
	v_mfma_f32_16x16x128_f8f6f4 v[54:57], v[18:25], v[220:227], v[54:57]
	v_mfma_f32_16x16x128_f8f6f4 v[50:53], v[26:33], v[220:227], v[50:53]
	v_mfma_f32_16x16x128_f8f6f4 v[38:41], v[18:25], v[228:235], v[38:41]
	v_mfma_f32_16x16x128_f8f6f4 v[34:37], v[26:33], v[228:235], v[34:37]
	s_barrier
	s_setprio 0
	s_add_i32 s44, s44, 2
	s_add_u32 s42, s42, 0x100000
	s_addc_u32 s43, s43, 0
	s_add_u32 s22, s22, 0x200000
	s_addc_u32 s23, s23, 0
	s_cmpk_gt_u32 s44, 0x6d
	s_cbranch_scc0 .LBB0_2714
	s_and_b64 vcc, exec, s[10:11]
	s_cbranch_vccz .LBB0_2717
	s_barrier
